# v1 plus: first K-loop iteration peeled in all 11 GEMM loops (first-touch MFMAs take C=0) so the 128 accumulator-zeroing v_mov per tile are gone
# speedup vs baseline: 1.0116x; 1.0116x over previous
.LBB0_473:
	s_add_u32 s71, s26, 0x100
	s_addc_u32 s78, s27, 0
	s_mov_b32 s53, -2
	s_waitcnt lgkmcnt(0)
	s_add_u32 s0, s10, 0x100
	s_addc_u32 s1, s11, 0
	s_add_i32 s79, 0, 0x10000
	s_cmp_eq_u32 s53, 40
	s_cselect_b32 s29, s23, s1
	s_cselect_b32 s28, s22, s0
	s_cselect_b32 s27, s25, s78
	s_cselect_b32 s26, s24, s71
	s_add_i32 s85, 0, 0x14000
	v_add_u32_e32 v128, s79, v211
	v_add_u32_e32 v156, s85, v211
	ds_read_b128 v[112:115], v128
	ds_read_b128 v[116:119], v128 offset:1024
	ds_read_b128 v[124:127], v128 offset:2048
	ds_read_b128 v[128:131], v128 offset:3072
	ds_read_b128 v[144:147], v156
	ds_read_b128 v[148:151], v156 offset:1024
	ds_read_b128 v[152:155], v156 offset:2048
	ds_read_b128 v[156:159], v156 offset:3072
	v_lshl_add_u64 v[244:245], s[10:11], 0, v[190:191]
	s_add_i32 m0, s37, 0xc000
	ds_read_b128 v[160:163], v225
	ds_read_b128 v[164:167], v225 offset:1024
	ds_read_b128 v[168:171], v225 offset:2048
	ds_read_b128 v[172:175], v225 offset:3072
	ds_read_b128 v[192:195], v225 offset:4096
	ds_read_b128 v[196:199], v225 offset:5120
	ds_read_b128 v[236:239], v225 offset:6144
	ds_read_b128 v[240:243], v225 offset:7168
	global_load_lds_dwordx4 v[244:245], off
	v_lshl_add_u64 v[244:245], s[10:11], 0, v[188:189]
	s_add_i32 m0, s37, 0xe000
	s_nop 0
	global_load_lds_dwordx4 v[244:245], off
	s_waitcnt vmcnt(8)
	s_waitcnt lgkmcnt(0)
	s_barrier
	s_setprio 1
	s_waitcnt lgkmcnt(0)
	v_mfma_f32_16x16x32_f16 v[140:143], v[112:115], v[160:163], 0
	v_mfma_f32_16x16x32_f16 v[136:139], v[124:127], v[160:163], 0
	v_mfma_f32_16x16x32_f16 v[108:111], v[112:115], v[168:171], 0
	v_mfma_f32_16x16x32_f16 v[104:107], v[124:127], v[168:171], 0
	v_mfma_f32_16x16x32_f16 v[92:95], v[112:115], v[192:195], 0
	v_mfma_f32_16x16x32_f16 v[88:91], v[124:127], v[192:195], 0
	v_mfma_f32_16x16x32_f16 v[76:79], v[112:115], v[236:239], 0
	v_mfma_f32_16x16x32_f16 v[72:75], v[124:127], v[236:239], 0
	v_mfma_f32_16x16x32_f16 v[140:143], v[116:119], v[164:167], v[140:143]
	v_mfma_f32_16x16x32_f16 v[136:139], v[128:131], v[164:167], v[136:139]
	v_mfma_f32_16x16x32_f16 v[108:111], v[116:119], v[172:175], v[108:111]
	v_mfma_f32_16x16x32_f16 v[104:107], v[128:131], v[172:175], v[104:107]
	v_mfma_f32_16x16x32_f16 v[92:95], v[116:119], v[196:199], v[92:95]
	v_mfma_f32_16x16x32_f16 v[88:91], v[128:131], v[196:199], v[88:91]
	v_mfma_f32_16x16x32_f16 v[76:79], v[116:119], v[240:243], v[76:79]
	v_mfma_f32_16x16x32_f16 v[72:75], v[128:131], v[240:243], v[72:75]
	s_setprio 0
	s_setprio 1
	v_mfma_f32_16x16x32_f16 v[132:135], v[144:147], v[160:163], 0
	v_mfma_f32_16x16x32_f16 v[120:123], v[152:155], v[160:163], 0
	v_mfma_f32_16x16x32_f16 v[100:103], v[144:147], v[168:171], 0
	v_mfma_f32_16x16x32_f16 v[96:99], v[152:155], v[168:171], 0
	v_mfma_f32_16x16x32_f16 v[84:87], v[144:147], v[192:195], 0
	v_mfma_f32_16x16x32_f16 v[80:83], v[152:155], v[192:195], 0
	v_mfma_f32_16x16x32_f16 v[68:71], v[144:147], v[236:239], 0
	v_mfma_f32_16x16x32_f16 v[64:67], v[152:155], v[236:239], 0
	v_mfma_f32_16x16x32_f16 v[132:135], v[148:151], v[164:167], v[132:135]
	v_mfma_f32_16x16x32_f16 v[120:123], v[156:159], v[164:167], v[120:123]
	v_mfma_f32_16x16x32_f16 v[100:103], v[148:151], v[172:175], v[100:103]
	v_mfma_f32_16x16x32_f16 v[96:99], v[156:159], v[172:175], v[96:99]
	v_mfma_f32_16x16x32_f16 v[84:87], v[148:151], v[196:199], v[84:87]
	v_mfma_f32_16x16x32_f16 v[80:83], v[156:159], v[196:199], v[80:83]
	v_mfma_f32_16x16x32_f16 v[68:71], v[148:151], v[240:243], v[68:71]
	v_mfma_f32_16x16x32_f16 v[64:67], v[156:159], v[240:243], v[64:67]
	s_setprio 0
	s_barrier
	s_add_i32 s10, s79, s36
	v_lshl_add_u64 v[244:245], s[26:27], 0, v[176:177]
	s_mov_b32 m0, s10
	ds_read_b128 v[160:163], v225 offset:16384
	ds_read_b128 v[164:167], v225 offset:17408
	ds_read_b128 v[168:171], v225 offset:18432
	ds_read_b128 v[172:175], v225 offset:19456
	ds_read_b128 v[192:195], v225 offset:20480
	ds_read_b128 v[196:199], v225 offset:21504
	ds_read_b128 v[236:239], v225 offset:22528
	ds_read_b128 v[240:243], v225 offset:23552
	global_load_lds_dwordx4 v[244:245], off
	s_add_i32 m0, s10, 0x2000
	s_add_u32 s10, s26, 0xb0000
	v_lshl_add_u64 v[246:247], s[26:27], 0, v[182:183]
	s_addc_u32 s11, s27, 0
	s_add_i32 s79, s85, s36
	global_load_lds_dwordx4 v[246:247], off
	v_lshl_add_u64 v[248:249], s[10:11], 0, v[176:177]
	s_mov_b32 m0, s79
	v_lshl_add_u64 v[250:251], s[28:29], 0, v[184:185]
	global_load_lds_dwordx4 v[248:249], off
	v_lshl_add_u64 v[248:249], s[10:11], 0, v[182:183]
	s_add_i32 m0, s79, 0x2000
	s_nop 0
	global_load_lds_dwordx4 v[248:249], off
	v_lshl_add_u64 v[248:249], s[28:29], 0, v[186:187]
	s_mov_b32 m0, s37
	s_nop 0
	global_load_lds_dwordx4 v[248:249], off
	s_mov_b32 m0, s42
	s_nop 0
	global_load_lds_dwordx4 v[250:251], off
	s_waitcnt vmcnt(8)
	s_waitcnt lgkmcnt(0)
	s_barrier
	s_setprio 1
	s_waitcnt lgkmcnt(0)
	v_mfma_f32_16x16x32_f16 v[60:63], v[112:115], v[160:163], 0
	v_mfma_f32_16x16x32_f16 v[56:59], v[124:127], v[160:163], 0
	v_mfma_f32_16x16x32_f16 v[44:47], v[112:115], v[168:171], 0
	v_mfma_f32_16x16x32_f16 v[40:43], v[124:127], v[168:171], 0
	v_mfma_f32_16x16x32_f16 v[28:31], v[112:115], v[192:195], 0
	v_mfma_f32_16x16x32_f16 v[24:27], v[124:127], v[192:195], 0
	v_mfma_f32_16x16x32_f16 v[12:15], v[112:115], v[236:239], 0
	v_mfma_f32_16x16x32_f16 v[8:11], v[124:127], v[236:239], 0
	v_mfma_f32_16x16x32_f16 v[60:63], v[116:119], v[164:167], v[60:63]
	v_mfma_f32_16x16x32_f16 v[56:59], v[128:131], v[164:167], v[56:59]
	v_mfma_f32_16x16x32_f16 v[44:47], v[116:119], v[172:175], v[44:47]
	v_mfma_f32_16x16x32_f16 v[40:43], v[128:131], v[172:175], v[40:43]
	v_mfma_f32_16x16x32_f16 v[28:31], v[116:119], v[196:199], v[28:31]
	v_mfma_f32_16x16x32_f16 v[24:27], v[128:131], v[196:199], v[24:27]
	v_mfma_f32_16x16x32_f16 v[12:15], v[116:119], v[240:243], v[12:15]
	v_mfma_f32_16x16x32_f16 v[8:11], v[128:131], v[240:243], v[8:11]
	s_setprio 0
	s_setprio 1
	v_mfma_f32_16x16x32_f16 v[52:55], v[144:147], v[160:163], 0
	v_mfma_f32_16x16x32_f16 v[48:51], v[152:155], v[160:163], 0
	v_mfma_f32_16x16x32_f16 v[36:39], v[144:147], v[168:171], 0
	v_mfma_f32_16x16x32_f16 v[32:35], v[152:155], v[168:171], 0
	v_mfma_f32_16x16x32_f16 v[20:23], v[144:147], v[192:195], 0
	v_mfma_f32_16x16x32_f16 v[16:19], v[152:155], v[192:195], 0
	v_mfma_f32_16x16x32_f16 v[4:7], v[144:147], v[236:239], 0
	v_mfma_f32_16x16x32_f16 v[0:3], v[152:155], v[236:239], 0
	v_mfma_f32_16x16x32_f16 v[52:55], v[148:151], v[164:167], v[52:55]
	v_mfma_f32_16x16x32_f16 v[48:51], v[156:159], v[164:167], v[48:51]
	v_mfma_f32_16x16x32_f16 v[36:39], v[148:151], v[172:175], v[36:39]
	v_mfma_f32_16x16x32_f16 v[32:35], v[156:159], v[172:175], v[32:35]
	v_mfma_f32_16x16x32_f16 v[20:23], v[148:151], v[196:199], v[20:23]
	v_mfma_f32_16x16x32_f16 v[16:19], v[156:159], v[196:199], v[16:19]
	v_mfma_f32_16x16x32_f16 v[4:7], v[148:151], v[240:243], v[4:7]
	v_mfma_f32_16x16x32_f16 v[0:3], v[156:159], v[240:243], v[0:3]
	s_setprio 0
	s_barrier
	s_add_i32 s79, 0, 0x18000
	s_add_i32 s85, 0, 0x1c000
	v_add_u32_e32 v128, s79, v211
	v_add_u32_e32 v156, s85, v211
	ds_read_b128 v[112:115], v128
	ds_read_b128 v[116:119], v128 offset:1024
	ds_read_b128 v[124:127], v128 offset:2048
	ds_read_b128 v[128:131], v128 offset:3072
	ds_read_b128 v[144:147], v156
	ds_read_b128 v[148:151], v156 offset:1024
	ds_read_b128 v[152:155], v156 offset:2048
	ds_read_b128 v[156:159], v156 offset:3072
	s_add_u32 s10, s28, 0xb0000
	s_addc_u32 s11, s29, 0
	s_mov_b32 m0, s43
	v_lshl_add_u64 v[252:253], s[10:11], 0, v[186:187]
	ds_read_b128 v[160:163], v225 offset:32768
	ds_read_b128 v[164:167], v225 offset:33792
	ds_read_b128 v[168:171], v225 offset:34816
	ds_read_b128 v[172:175], v225 offset:35840
	ds_read_b128 v[192:195], v225 offset:36864
	ds_read_b128 v[196:199], v225 offset:37888
	ds_read_b128 v[236:239], v225 offset:38912
	ds_read_b128 v[240:243], v225 offset:39936
	global_load_lds_dwordx4 v[252:253], off
	v_lshl_add_u64 v[252:253], s[10:11], 0, v[184:185]
	s_mov_b32 m0, s50
	s_nop 0
	global_load_lds_dwordx4 v[252:253], off
	s_waitcnt vmcnt(8)
	s_waitcnt lgkmcnt(0)
	s_barrier
	s_setprio 1
	s_waitcnt lgkmcnt(0)
	v_mfma_f32_16x16x32_f16 v[140:143], v[112:115], v[160:163], v[140:143]
	v_mfma_f32_16x16x32_f16 v[136:139], v[124:127], v[160:163], v[136:139]
	v_mfma_f32_16x16x32_f16 v[108:111], v[112:115], v[168:171], v[108:111]
	v_mfma_f32_16x16x32_f16 v[104:107], v[124:127], v[168:171], v[104:107]
	v_mfma_f32_16x16x32_f16 v[92:95], v[112:115], v[192:195], v[92:95]
	v_mfma_f32_16x16x32_f16 v[88:91], v[124:127], v[192:195], v[88:91]
	v_mfma_f32_16x16x32_f16 v[76:79], v[112:115], v[236:239], v[76:79]
	v_mfma_f32_16x16x32_f16 v[72:75], v[124:127], v[236:239], v[72:75]
	v_mfma_f32_16x16x32_f16 v[140:143], v[116:119], v[164:167], v[140:143]
	v_mfma_f32_16x16x32_f16 v[136:139], v[128:131], v[164:167], v[136:139]
	v_mfma_f32_16x16x32_f16 v[108:111], v[116:119], v[172:175], v[108:111]
	v_mfma_f32_16x16x32_f16 v[104:107], v[128:131], v[172:175], v[104:107]
	v_mfma_f32_16x16x32_f16 v[92:95], v[116:119], v[196:199], v[92:95]
	v_mfma_f32_16x16x32_f16 v[88:91], v[128:131], v[196:199], v[88:91]
	v_mfma_f32_16x16x32_f16 v[76:79], v[116:119], v[240:243], v[76:79]
	v_mfma_f32_16x16x32_f16 v[72:75], v[128:131], v[240:243], v[72:75]
	s_setprio 0
	s_setprio 1
	v_mfma_f32_16x16x32_f16 v[132:135], v[144:147], v[160:163], v[132:135]
	v_mfma_f32_16x16x32_f16 v[120:123], v[152:155], v[160:163], v[120:123]
	v_mfma_f32_16x16x32_f16 v[100:103], v[144:147], v[168:171], v[100:103]
	v_mfma_f32_16x16x32_f16 v[96:99], v[152:155], v[168:171], v[96:99]
	v_mfma_f32_16x16x32_f16 v[84:87], v[144:147], v[192:195], v[84:87]
	v_mfma_f32_16x16x32_f16 v[80:83], v[152:155], v[192:195], v[80:83]
	v_mfma_f32_16x16x32_f16 v[68:71], v[144:147], v[236:239], v[68:71]
	v_mfma_f32_16x16x32_f16 v[64:67], v[152:155], v[236:239], v[64:67]
	v_mfma_f32_16x16x32_f16 v[132:135], v[148:151], v[164:167], v[132:135]
	v_mfma_f32_16x16x32_f16 v[120:123], v[156:159], v[164:167], v[120:123]
	v_mfma_f32_16x16x32_f16 v[100:103], v[148:151], v[172:175], v[100:103]
	v_mfma_f32_16x16x32_f16 v[96:99], v[156:159], v[172:175], v[96:99]
	v_mfma_f32_16x16x32_f16 v[84:87], v[148:151], v[196:199], v[84:87]
	v_mfma_f32_16x16x32_f16 v[80:83], v[156:159], v[196:199], v[80:83]
	v_mfma_f32_16x16x32_f16 v[68:71], v[148:151], v[240:243], v[68:71]
	v_mfma_f32_16x16x32_f16 v[64:67], v[156:159], v[240:243], v[64:67]
	s_setprio 0
	s_barrier
	s_add_i32 s10, s79, s36
	v_lshl_add_u64 v[244:245], v[244:245], 0, s[72:73]
	s_mov_b32 m0, s10
	ds_read_b128 v[160:163], v225 offset:49152
	ds_read_b128 v[164:167], v225 offset:50176
	ds_read_b128 v[168:171], v225 offset:51200
	ds_read_b128 v[172:175], v225 offset:52224
	ds_read_b128 v[192:195], v225 offset:53248
	ds_read_b128 v[196:199], v225 offset:54272
	ds_read_b128 v[236:239], v225 offset:55296
	ds_read_b128 v[240:243], v225 offset:56320
	global_load_lds_dwordx4 v[244:245], off
	s_add_i32 m0, s10, 0x2000
	s_add_u32 s10, s26, 0xb0080
	v_lshl_add_u64 v[244:245], v[246:247], 0, s[72:73]
	s_addc_u32 s11, s27, 0
	s_add_i32 s26, s85, s36
	global_load_lds_dwordx4 v[244:245], off
	v_lshl_add_u64 v[244:245], s[10:11], 0, v[176:177]
	s_mov_b32 m0, s26
	s_nop 0
	global_load_lds_dwordx4 v[244:245], off
	v_lshl_add_u64 v[244:245], s[10:11], 0, v[182:183]
	s_add_i32 m0, s26, 0x2000
	s_nop 0
	global_load_lds_dwordx4 v[244:245], off
	v_lshl_add_u64 v[244:245], v[248:249], 0, s[72:73]
	s_mov_b32 m0, s51
	s_nop 0
	global_load_lds_dwordx4 v[244:245], off
	v_lshl_add_u64 v[244:245], v[250:251], 0, s[72:73]
	s_mov_b32 m0, s54
	s_nop 0
	global_load_lds_dwordx4 v[244:245], off
	s_waitcnt vmcnt(8)
	s_waitcnt lgkmcnt(0)
	s_barrier
	s_setprio 1
	s_waitcnt lgkmcnt(0)
	v_mfma_f32_16x16x32_f16 v[60:63], v[112:115], v[160:163], v[60:63]
	v_mfma_f32_16x16x32_f16 v[56:59], v[124:127], v[160:163], v[56:59]
	v_mfma_f32_16x16x32_f16 v[44:47], v[112:115], v[168:171], v[44:47]
	v_mfma_f32_16x16x32_f16 v[40:43], v[124:127], v[168:171], v[40:43]
	v_mfma_f32_16x16x32_f16 v[28:31], v[112:115], v[192:195], v[28:31]
	v_mfma_f32_16x16x32_f16 v[24:27], v[124:127], v[192:195], v[24:27]
	v_mfma_f32_16x16x32_f16 v[12:15], v[112:115], v[236:239], v[12:15]
	v_mfma_f32_16x16x32_f16 v[8:11], v[124:127], v[236:239], v[8:11]
	v_mfma_f32_16x16x32_f16 v[60:63], v[116:119], v[164:167], v[60:63]
	v_mfma_f32_16x16x32_f16 v[56:59], v[128:131], v[164:167], v[56:59]
	v_mfma_f32_16x16x32_f16 v[44:47], v[116:119], v[172:175], v[44:47]
	v_mfma_f32_16x16x32_f16 v[40:43], v[128:131], v[172:175], v[40:43]
	v_mfma_f32_16x16x32_f16 v[28:31], v[116:119], v[196:199], v[28:31]
	v_mfma_f32_16x16x32_f16 v[24:27], v[128:131], v[196:199], v[24:27]
	v_mfma_f32_16x16x32_f16 v[12:15], v[116:119], v[240:243], v[12:15]
	v_mfma_f32_16x16x32_f16 v[8:11], v[128:131], v[240:243], v[8:11]
	s_setprio 0
	s_setprio 1
	v_mfma_f32_16x16x32_f16 v[52:55], v[144:147], v[160:163], v[52:55]
	v_mfma_f32_16x16x32_f16 v[48:51], v[152:155], v[160:163], v[48:51]
	v_mfma_f32_16x16x32_f16 v[36:39], v[144:147], v[168:171], v[36:39]
	v_mfma_f32_16x16x32_f16 v[32:35], v[152:155], v[168:171], v[32:35]
	v_mfma_f32_16x16x32_f16 v[20:23], v[144:147], v[192:195], v[20:23]
	v_mfma_f32_16x16x32_f16 v[16:19], v[152:155], v[192:195], v[16:19]
	v_mfma_f32_16x16x32_f16 v[4:7], v[144:147], v[236:239], v[4:7]
	v_mfma_f32_16x16x32_f16 v[0:3], v[152:155], v[236:239], v[0:3]
	v_mfma_f32_16x16x32_f16 v[52:55], v[148:151], v[164:167], v[52:55]
	v_mfma_f32_16x16x32_f16 v[48:51], v[156:159], v[164:167], v[48:51]
	v_mfma_f32_16x16x32_f16 v[36:39], v[148:151], v[172:175], v[36:39]
	v_mfma_f32_16x16x32_f16 v[32:35], v[156:159], v[172:175], v[32:35]
	v_mfma_f32_16x16x32_f16 v[20:23], v[148:151], v[196:199], v[20:23]
	v_mfma_f32_16x16x32_f16 v[16:19], v[156:159], v[196:199], v[16:19]
	v_mfma_f32_16x16x32_f16 v[4:7], v[148:151], v[240:243], v[4:7]
	v_mfma_f32_16x16x32_f16 v[0:3], v[156:159], v[240:243], v[0:3]
	s_setprio 0
	s_barrier
	s_add_i32 s53, s53, 2
	s_add_u32 s71, s71, 0x100
	s_addc_u32 s78, s78, 0
	s_cmp_gt_u32 s53, 41
	s_mov_b64 s[10:11], s[0:1]

.LBB0_569:
	s_ashr_i32 s11, s10, 31
	s_lshl_b64 s[14:15], s[10:11], 19
	s_add_u32 s14, s44, s14
	s_addc_u32 s15, s45, s15
	s_and_b64 s[16:17], s[4:5], exec
	s_cselect_b32 s11, s15, s21
	s_cselect_b32 s43, s14, s20
	s_ashr_i32 s9, s8, 31
	s_lshl_b64 s[16:17], s[8:9], 19
	s_add_u32 s16, s30, s16
	s_addc_u32 s17, s31, s17
	s_and_b64 s[22:23], s[4:5], exec
	s_cselect_b32 s9, s17, s19
	s_cselect_b32 s50, s16, s18
	s_add_u32 s51, s18, 0x100
	s_addc_u32 s54, s19, 0
	s_add_u32 s18, s20, 0x40080
	s_addc_u32 s19, s21, 0
	s_mov_b32 s55, -2
	s_add_u32 s20, s18, 0xfffc0080
	s_addc_u32 s21, s19, -1
	s_add_i32 s53, 0, 0x10000
	s_cmp_eq_u32 s55, 12
	s_cselect_b32 s23, s11, s21
	s_cselect_b32 s22, s43, s20
	v_add_u32_e32 v140, s53, v143
	s_cselect_b32 s21, s9, s54
	s_cselect_b32 s20, s50, s51
	s_add_i32 s70, 0, 0x14000
	ds_read_b128 v[148:151], v140
	ds_read_b128 v[152:155], v140 offset:1024
	ds_read_b128 v[156:159], v140 offset:2048
	ds_read_b128 v[160:163], v140 offset:3072
	v_add_u32_e32 v140, s70, v143
	ds_read_b128 v[164:167], v140
	ds_read_b128 v[168:171], v140 offset:1024
	ds_read_b128 v[172:175], v140 offset:2048
	ds_read_b128 v[182:185], v140 offset:3072
	v_lshl_add_u64 v[140:141], s[18:19], 0, v[138:139]
	s_add_i32 m0, s25, 0xc000
	ds_read_b128 v[186:189], v147
	ds_read_b128 v[190:193], v147 offset:1024
	ds_read_b128 v[194:197], v147 offset:2048
	ds_read_b128 v[210:213], v147 offset:3072
	ds_read_b128 v[214:217], v147 offset:4096
	ds_read_b128 v[218:221], v147 offset:5120
	ds_read_b128 v[222:225], v147 offset:6144
	ds_read_b128 v[226:229], v147 offset:7168
	global_load_lds_dwordx4 v[140:141], off
	v_lshl_add_u64 v[140:141], s[18:19], 0, v[136:137]
	s_add_i32 m0, s25, 0xe000
	s_nop 0
	global_load_lds_dwordx4 v[140:141], off
	s_waitcnt vmcnt(8)
	s_waitcnt lgkmcnt(0)
	s_barrier
	s_setprio 1
	s_waitcnt lgkmcnt(0)
	v_mfma_f32_16x16x32_f16 v[124:127], v[148:151], v[186:189], 0
	v_mfma_f32_16x16x32_f16 v[116:119], v[156:159], v[186:189], 0
	v_mfma_f32_16x16x32_f16 v[108:111], v[148:151], v[194:197], 0
	v_mfma_f32_16x16x32_f16 v[100:103], v[156:159], v[194:197], 0
	v_mfma_f32_16x16x32_f16 v[92:95], v[148:151], v[214:217], 0
	v_mfma_f32_16x16x32_f16 v[84:87], v[156:159], v[214:217], 0
	v_mfma_f32_16x16x32_f16 v[76:79], v[148:151], v[222:225], 0
	v_mfma_f32_16x16x32_f16 v[68:71], v[156:159], v[222:225], 0
	v_mfma_f32_16x16x32_f16 v[124:127], v[152:155], v[190:193], v[124:127]
	v_mfma_f32_16x16x32_f16 v[116:119], v[160:163], v[190:193], v[116:119]
	v_mfma_f32_16x16x32_f16 v[108:111], v[152:155], v[210:213], v[108:111]
	v_mfma_f32_16x16x32_f16 v[100:103], v[160:163], v[210:213], v[100:103]
	v_mfma_f32_16x16x32_f16 v[92:95], v[152:155], v[218:221], v[92:95]
	v_mfma_f32_16x16x32_f16 v[84:87], v[160:163], v[218:221], v[84:87]
	v_mfma_f32_16x16x32_f16 v[76:79], v[152:155], v[226:229], v[76:79]
	v_mfma_f32_16x16x32_f16 v[68:71], v[160:163], v[226:229], v[68:71]
	s_setprio 0
	s_setprio 1
	v_mfma_f32_16x16x32_f16 v[120:123], v[164:167], v[186:189], 0
	v_mfma_f32_16x16x32_f16 v[112:115], v[172:175], v[186:189], 0
	v_mfma_f32_16x16x32_f16 v[104:107], v[164:167], v[194:197], 0
	v_mfma_f32_16x16x32_f16 v[96:99], v[172:175], v[194:197], 0
	v_mfma_f32_16x16x32_f16 v[88:91], v[164:167], v[214:217], 0
	v_mfma_f32_16x16x32_f16 v[80:83], v[172:175], v[214:217], 0
	v_mfma_f32_16x16x32_f16 v[72:75], v[164:167], v[222:225], 0
	v_mfma_f32_16x16x32_f16 v[64:67], v[172:175], v[222:225], 0
	v_mfma_f32_16x16x32_f16 v[120:123], v[168:171], v[190:193], v[120:123]
	v_mfma_f32_16x16x32_f16 v[112:115], v[182:185], v[190:193], v[112:115]
	v_mfma_f32_16x16x32_f16 v[104:107], v[168:171], v[210:213], v[104:107]
	v_mfma_f32_16x16x32_f16 v[96:99], v[182:185], v[210:213], v[96:99]
	v_mfma_f32_16x16x32_f16 v[88:91], v[168:171], v[218:221], v[88:91]
	v_mfma_f32_16x16x32_f16 v[80:83], v[182:185], v[218:221], v[80:83]
	v_mfma_f32_16x16x32_f16 v[72:75], v[168:171], v[226:229], v[72:75]
	v_mfma_f32_16x16x32_f16 v[64:67], v[182:185], v[226:229], v[64:67]
	s_setprio 0
	s_barrier
	s_add_i32 s53, s53, s24
	v_lshl_add_u64 v[140:141], s[20:21], 0, v[132:133]
	s_mov_b32 m0, s53
	ds_read_b128 v[186:189], v147 offset:16384
	ds_read_b128 v[190:193], v147 offset:17408
	ds_read_b128 v[194:197], v147 offset:18432
	ds_read_b128 v[210:213], v147 offset:19456
	ds_read_b128 v[214:217], v147 offset:20480
	ds_read_b128 v[218:221], v147 offset:21504
	ds_read_b128 v[222:225], v147 offset:22528
	ds_read_b128 v[226:229], v147 offset:23552
	global_load_lds_dwordx4 v[140:141], off
	s_add_i32 m0, s53, 0x2000
	s_add_u32 s56, s20, 0x40000
	v_lshl_add_u64 v[198:199], s[20:21], 0, v[128:129]
	s_addc_u32 s57, s21, 0
	s_add_i32 s53, s70, s24
	global_load_lds_dwordx4 v[198:199], off
	v_lshl_add_u64 v[230:231], s[56:57], 0, v[132:133]
	s_mov_b32 m0, s53
	v_lshl_add_u64 v[232:233], s[22:23], 0, v[130:131]
	global_load_lds_dwordx4 v[230:231], off
	v_lshl_add_u64 v[230:231], s[56:57], 0, v[128:129]
	s_add_i32 m0, s53, 0x2000
	s_nop 0
	global_load_lds_dwordx4 v[230:231], off
	v_lshl_add_u64 v[230:231], s[22:23], 0, v[134:135]
	s_mov_b32 m0, s25
	s_nop 0
	global_load_lds_dwordx4 v[230:231], off
	s_mov_b32 m0, s26
	s_nop 0
	global_load_lds_dwordx4 v[232:233], off
	s_waitcnt vmcnt(8)
	s_waitcnt lgkmcnt(0)
	s_barrier
	s_setprio 1
	s_waitcnt lgkmcnt(0)
	v_mfma_f32_16x16x32_f16 v[60:63], v[148:151], v[186:189], 0
	v_mfma_f32_16x16x32_f16 v[52:55], v[156:159], v[186:189], 0
	v_mfma_f32_16x16x32_f16 v[44:47], v[148:151], v[194:197], 0
	v_mfma_f32_16x16x32_f16 v[36:39], v[156:159], v[194:197], 0
	v_mfma_f32_16x16x32_f16 v[28:31], v[148:151], v[214:217], 0
	v_mfma_f32_16x16x32_f16 v[20:23], v[156:159], v[214:217], 0
	v_mfma_f32_16x16x32_f16 v[12:15], v[148:151], v[222:225], 0
	v_mfma_f32_16x16x32_f16 v[4:7], v[156:159], v[222:225], 0
	v_mfma_f32_16x16x32_f16 v[60:63], v[152:155], v[190:193], v[60:63]
	v_mfma_f32_16x16x32_f16 v[52:55], v[160:163], v[190:193], v[52:55]
	v_mfma_f32_16x16x32_f16 v[44:47], v[152:155], v[210:213], v[44:47]
	v_mfma_f32_16x16x32_f16 v[36:39], v[160:163], v[210:213], v[36:39]
	v_mfma_f32_16x16x32_f16 v[28:31], v[152:155], v[218:221], v[28:31]
	v_mfma_f32_16x16x32_f16 v[20:23], v[160:163], v[218:221], v[20:23]
	v_mfma_f32_16x16x32_f16 v[12:15], v[152:155], v[226:229], v[12:15]
	v_mfma_f32_16x16x32_f16 v[4:7], v[160:163], v[226:229], v[4:7]
	s_setprio 0
	s_setprio 1
	v_mfma_f32_16x16x32_f16 v[56:59], v[164:167], v[186:189], 0
	v_mfma_f32_16x16x32_f16 v[48:51], v[172:175], v[186:189], 0
	v_mfma_f32_16x16x32_f16 v[40:43], v[164:167], v[194:197], 0
	v_mfma_f32_16x16x32_f16 v[32:35], v[172:175], v[194:197], 0
	v_mfma_f32_16x16x32_f16 v[24:27], v[164:167], v[214:217], 0
	v_mfma_f32_16x16x32_f16 v[16:19], v[172:175], v[214:217], 0
	v_mfma_f32_16x16x32_f16 v[8:11], v[164:167], v[222:225], 0
	v_mfma_f32_16x16x32_f16 v[0:3], v[172:175], v[222:225], 0
	v_mfma_f32_16x16x32_f16 v[56:59], v[168:171], v[190:193], v[56:59]
	v_mfma_f32_16x16x32_f16 v[48:51], v[182:185], v[190:193], v[48:51]
	v_mfma_f32_16x16x32_f16 v[40:43], v[168:171], v[210:213], v[40:43]
	v_mfma_f32_16x16x32_f16 v[32:35], v[182:185], v[210:213], v[32:35]
	v_mfma_f32_16x16x32_f16 v[24:27], v[168:171], v[218:221], v[24:27]
	v_mfma_f32_16x16x32_f16 v[16:19], v[182:185], v[218:221], v[16:19]
	v_mfma_f32_16x16x32_f16 v[8:11], v[168:171], v[226:229], v[8:11]
	v_mfma_f32_16x16x32_f16 v[0:3], v[182:185], v[226:229], v[0:3]
	s_setprio 0
	s_barrier
	s_add_i32 s53, 0, 0x18000
	s_add_i32 s56, 0, 0x1c000
	v_add_u32_e32 v160, s53, v143
	v_add_u32_e32 v182, s56, v143
	ds_read_b128 v[148:151], v160
	ds_read_b128 v[152:155], v160 offset:1024
	ds_read_b128 v[156:159], v160 offset:2048
	ds_read_b128 v[160:163], v160 offset:3072
	ds_read_b128 v[164:167], v182
	ds_read_b128 v[168:171], v182 offset:1024
	ds_read_b128 v[172:175], v182 offset:2048
	ds_read_b128 v[182:185], v182 offset:3072
	s_add_u32 s22, s22, 0x40000
	s_addc_u32 s23, s23, 0
	s_mov_b32 m0, s27
	v_lshl_add_u64 v[234:235], s[22:23], 0, v[134:135]
	ds_read_b128 v[186:189], v147 offset:32768
	ds_read_b128 v[190:193], v147 offset:33792
	ds_read_b128 v[194:197], v147 offset:34816
	ds_read_b128 v[210:213], v147 offset:35840
	ds_read_b128 v[214:217], v147 offset:36864
	ds_read_b128 v[218:221], v147 offset:37888
	ds_read_b128 v[222:225], v147 offset:38912
	ds_read_b128 v[226:229], v147 offset:39936
	global_load_lds_dwordx4 v[234:235], off
	v_lshl_add_u64 v[234:235], s[22:23], 0, v[130:131]
	s_mov_b32 m0, s28
	s_nop 0
	global_load_lds_dwordx4 v[234:235], off
	s_waitcnt vmcnt(8)
	s_waitcnt lgkmcnt(0)
	s_barrier
	s_setprio 1
	s_waitcnt lgkmcnt(0)
	v_mfma_f32_16x16x32_f16 v[124:127], v[148:151], v[186:189], v[124:127]
	v_mfma_f32_16x16x32_f16 v[116:119], v[156:159], v[186:189], v[116:119]
	v_mfma_f32_16x16x32_f16 v[108:111], v[148:151], v[194:197], v[108:111]
	v_mfma_f32_16x16x32_f16 v[100:103], v[156:159], v[194:197], v[100:103]
	v_mfma_f32_16x16x32_f16 v[92:95], v[148:151], v[214:217], v[92:95]
	v_mfma_f32_16x16x32_f16 v[84:87], v[156:159], v[214:217], v[84:87]
	v_mfma_f32_16x16x32_f16 v[76:79], v[148:151], v[222:225], v[76:79]
	v_mfma_f32_16x16x32_f16 v[68:71], v[156:159], v[222:225], v[68:71]
	v_mfma_f32_16x16x32_f16 v[124:127], v[152:155], v[190:193], v[124:127]
	v_mfma_f32_16x16x32_f16 v[116:119], v[160:163], v[190:193], v[116:119]
	v_mfma_f32_16x16x32_f16 v[108:111], v[152:155], v[210:213], v[108:111]
	v_mfma_f32_16x16x32_f16 v[100:103], v[160:163], v[210:213], v[100:103]
	v_mfma_f32_16x16x32_f16 v[92:95], v[152:155], v[218:221], v[92:95]
	v_mfma_f32_16x16x32_f16 v[84:87], v[160:163], v[218:221], v[84:87]
	v_mfma_f32_16x16x32_f16 v[76:79], v[152:155], v[226:229], v[76:79]
	v_mfma_f32_16x16x32_f16 v[68:71], v[160:163], v[226:229], v[68:71]
	s_setprio 0
	s_setprio 1
	v_mfma_f32_16x16x32_f16 v[120:123], v[164:167], v[186:189], v[120:123]
	v_mfma_f32_16x16x32_f16 v[112:115], v[172:175], v[186:189], v[112:115]
	v_mfma_f32_16x16x32_f16 v[104:107], v[164:167], v[194:197], v[104:107]
	v_mfma_f32_16x16x32_f16 v[96:99], v[172:175], v[194:197], v[96:99]
	v_mfma_f32_16x16x32_f16 v[88:91], v[164:167], v[214:217], v[88:91]
	v_mfma_f32_16x16x32_f16 v[80:83], v[172:175], v[214:217], v[80:83]
	v_mfma_f32_16x16x32_f16 v[72:75], v[164:167], v[222:225], v[72:75]
	v_mfma_f32_16x16x32_f16 v[64:67], v[172:175], v[222:225], v[64:67]
	v_mfma_f32_16x16x32_f16 v[120:123], v[168:171], v[190:193], v[120:123]
	v_mfma_f32_16x16x32_f16 v[112:115], v[182:185], v[190:193], v[112:115]
	v_mfma_f32_16x16x32_f16 v[104:107], v[168:171], v[210:213], v[104:107]
	v_mfma_f32_16x16x32_f16 v[96:99], v[182:185], v[210:213], v[96:99]
	v_mfma_f32_16x16x32_f16 v[88:91], v[168:171], v[218:221], v[88:91]
	v_mfma_f32_16x16x32_f16 v[80:83], v[182:185], v[218:221], v[80:83]
	v_mfma_f32_16x16x32_f16 v[72:75], v[168:171], v[226:229], v[72:75]
	v_mfma_f32_16x16x32_f16 v[64:67], v[182:185], v[226:229], v[64:67]
	s_setprio 0
	s_barrier
	s_add_i32 s22, s53, s24
	v_lshl_add_u64 v[140:141], v[140:141], 0, s[72:73]
	s_mov_b32 m0, s22
	ds_read_b128 v[186:189], v147 offset:49152
	ds_read_b128 v[190:193], v147 offset:50176
	ds_read_b128 v[194:197], v147 offset:51200
	ds_read_b128 v[210:213], v147 offset:52224
	ds_read_b128 v[214:217], v147 offset:53248
	ds_read_b128 v[218:221], v147 offset:54272
	ds_read_b128 v[222:225], v147 offset:55296
	ds_read_b128 v[226:229], v147 offset:56320
	global_load_lds_dwordx4 v[140:141], off
	s_add_i32 m0, s22, 0x2000
	s_add_u32 s20, s20, 0x40080
	v_lshl_add_u64 v[140:141], v[198:199], 0, s[72:73]
	s_addc_u32 s21, s21, 0
	s_add_i32 s22, s56, s24
	global_load_lds_dwordx4 v[140:141], off
	v_lshl_add_u64 v[140:141], s[20:21], 0, v[132:133]
	s_mov_b32 m0, s22
	s_nop 0
	global_load_lds_dwordx4 v[140:141], off
	v_lshl_add_u64 v[140:141], s[20:21], 0, v[128:129]
	s_add_i32 m0, s22, 0x2000
	s_nop 0
	global_load_lds_dwordx4 v[140:141], off
	v_lshl_add_u64 v[140:141], v[230:231], 0, s[72:73]
	s_mov_b32 m0, s29
	s_nop 0
	global_load_lds_dwordx4 v[140:141], off
	v_lshl_add_u64 v[140:141], v[232:233], 0, s[72:73]
	s_mov_b32 m0, s34
	s_nop 0
	global_load_lds_dwordx4 v[140:141], off
	s_waitcnt vmcnt(8)
	s_waitcnt lgkmcnt(0)
	s_barrier
	s_setprio 1
	s_waitcnt lgkmcnt(0)
	v_mfma_f32_16x16x32_f16 v[60:63], v[148:151], v[186:189], v[60:63]
	v_mfma_f32_16x16x32_f16 v[52:55], v[156:159], v[186:189], v[52:55]
	v_mfma_f32_16x16x32_f16 v[44:47], v[148:151], v[194:197], v[44:47]
	v_mfma_f32_16x16x32_f16 v[36:39], v[156:159], v[194:197], v[36:39]
	v_mfma_f32_16x16x32_f16 v[28:31], v[148:151], v[214:217], v[28:31]
	v_mfma_f32_16x16x32_f16 v[20:23], v[156:159], v[214:217], v[20:23]
	v_mfma_f32_16x16x32_f16 v[12:15], v[148:151], v[222:225], v[12:15]
	v_mfma_f32_16x16x32_f16 v[4:7], v[156:159], v[222:225], v[4:7]
	v_mfma_f32_16x16x32_f16 v[60:63], v[152:155], v[190:193], v[60:63]
	v_mfma_f32_16x16x32_f16 v[52:55], v[160:163], v[190:193], v[52:55]
	v_mfma_f32_16x16x32_f16 v[44:47], v[152:155], v[210:213], v[44:47]
	v_mfma_f32_16x16x32_f16 v[36:39], v[160:163], v[210:213], v[36:39]
	v_mfma_f32_16x16x32_f16 v[28:31], v[152:155], v[218:221], v[28:31]
	v_mfma_f32_16x16x32_f16 v[20:23], v[160:163], v[218:221], v[20:23]
	v_mfma_f32_16x16x32_f16 v[12:15], v[152:155], v[226:229], v[12:15]
	v_mfma_f32_16x16x32_f16 v[4:7], v[160:163], v[226:229], v[4:7]
	s_setprio 0
	s_setprio 1
	v_mfma_f32_16x16x32_f16 v[56:59], v[164:167], v[186:189], v[56:59]
	v_mfma_f32_16x16x32_f16 v[48:51], v[172:175], v[186:189], v[48:51]
	v_mfma_f32_16x16x32_f16 v[40:43], v[164:167], v[194:197], v[40:43]
	v_mfma_f32_16x16x32_f16 v[32:35], v[172:175], v[194:197], v[32:35]
	v_mfma_f32_16x16x32_f16 v[24:27], v[164:167], v[214:217], v[24:27]
	v_mfma_f32_16x16x32_f16 v[16:19], v[172:175], v[214:217], v[16:19]
	v_mfma_f32_16x16x32_f16 v[8:11], v[164:167], v[222:225], v[8:11]
	v_mfma_f32_16x16x32_f16 v[0:3], v[172:175], v[222:225], v[0:3]
	v_mfma_f32_16x16x32_f16 v[56:59], v[168:171], v[190:193], v[56:59]
	v_mfma_f32_16x16x32_f16 v[48:51], v[182:185], v[190:193], v[48:51]
	v_mfma_f32_16x16x32_f16 v[40:43], v[168:171], v[210:213], v[40:43]
	v_mfma_f32_16x16x32_f16 v[32:35], v[182:185], v[210:213], v[32:35]
	v_mfma_f32_16x16x32_f16 v[24:27], v[168:171], v[218:221], v[24:27]
	v_mfma_f32_16x16x32_f16 v[16:19], v[182:185], v[218:221], v[16:19]
	v_mfma_f32_16x16x32_f16 v[8:11], v[168:171], v[226:229], v[8:11]
	v_mfma_f32_16x16x32_f16 v[0:3], v[182:185], v[226:229], v[0:3]
	s_setprio 0
	s_barrier
	s_add_i32 s55, s55, 2
	s_add_u32 s51, s51, 0x100
	s_addc_u32 s54, s54, 0
	s_add_u32 s18, s18, 0x100
	s_addc_u32 s19, s19, 0
	s_cmp_gt_u32 s55, 13

.LBB0_598:
	s_ashr_i32 s23, s22, 31
	s_lshl_b64 s[24:25], s[22:23], 19
	s_add_u32 s24, s78, s24
	s_addc_u32 s25, s79, s25
	s_and_b64 s[26:27], s[8:9], exec
	s_cselect_b32 s23, s25, s11
	s_cselect_b32 s85, s24, s10
	s_ashr_i32 s21, s20, 31
	s_lshl_b64 s[26:27], s[20:21], 19
	s_add_u32 s26, s30, s26
	s_addc_u32 s27, s31, s27
	s_and_b64 s[28:29], s[8:9], exec
	s_cselect_b32 s21, s27, s1
	s_cselect_b32 s96, s26, s0
	s_add_u32 s86, s0, 0x100
	s_addc_u32 s87, s1, 0
	s_add_u32 s0, s10, 0x40080
	s_addc_u32 s1, s11, 0
	s_mov_b32 s53, -2
	s_waitcnt lgkmcnt(0)
	s_add_u32 s10, s0, 0xfffc0080
	s_addc_u32 s11, s1, -1
	s_add_i32 s92, 0, 0x10000
	s_cmp_eq_u32 s53, 12
	s_cselect_b32 s29, s23, s11
	s_cselect_b32 s28, s85, s10
	s_cselect_b32 s11, s21, s87
	s_cselect_b32 s10, s96, s86
	s_add_i32 vcc_lo, 0, 0x14000
	v_add_u32_e32 v128, s92, v211
	v_add_u32_e32 v156, vcc_lo, v211
	ds_read_b128 v[112:115], v128
	ds_read_b128 v[116:119], v128 offset:1024
	ds_read_b128 v[124:127], v128 offset:2048
	ds_read_b128 v[128:131], v128 offset:3072
	ds_read_b128 v[144:147], v156
	ds_read_b128 v[148:151], v156 offset:1024
	ds_read_b128 v[152:155], v156 offset:2048
	ds_read_b128 v[156:159], v156 offset:3072
	v_lshl_add_u64 v[244:245], s[0:1], 0, v[190:191]
	s_add_i32 m0, s35, 0xc000
	ds_read_b128 v[160:163], v225
	ds_read_b128 v[164:167], v225 offset:1024
	ds_read_b128 v[168:171], v225 offset:2048
	ds_read_b128 v[172:175], v225 offset:3072
	ds_read_b128 v[192:195], v225 offset:4096
	ds_read_b128 v[196:199], v225 offset:5120
	ds_read_b128 v[236:239], v225 offset:6144
	ds_read_b128 v[240:243], v225 offset:7168
	global_load_lds_dwordx4 v[244:245], off
	v_lshl_add_u64 v[244:245], s[0:1], 0, v[188:189]
	s_add_i32 m0, s35, 0xe000
	s_nop 0
	global_load_lds_dwordx4 v[244:245], off
	s_waitcnt vmcnt(8)
	s_waitcnt lgkmcnt(0)
	s_barrier
	s_setprio 1
	s_waitcnt lgkmcnt(0)
	v_mfma_f32_16x16x32_f16 v[140:143], v[112:115], v[160:163], 0
	v_mfma_f32_16x16x32_f16 v[136:139], v[124:127], v[160:163], 0
	v_mfma_f32_16x16x32_f16 v[108:111], v[112:115], v[168:171], 0
	v_mfma_f32_16x16x32_f16 v[104:107], v[124:127], v[168:171], 0
	v_mfma_f32_16x16x32_f16 v[92:95], v[112:115], v[192:195], 0
	v_mfma_f32_16x16x32_f16 v[88:91], v[124:127], v[192:195], 0
	v_mfma_f32_16x16x32_f16 v[76:79], v[112:115], v[236:239], 0
	v_mfma_f32_16x16x32_f16 v[72:75], v[124:127], v[236:239], 0
	v_mfma_f32_16x16x32_f16 v[140:143], v[116:119], v[164:167], v[140:143]
	v_mfma_f32_16x16x32_f16 v[136:139], v[128:131], v[164:167], v[136:139]
	v_mfma_f32_16x16x32_f16 v[108:111], v[116:119], v[172:175], v[108:111]
	v_mfma_f32_16x16x32_f16 v[104:107], v[128:131], v[172:175], v[104:107]
	v_mfma_f32_16x16x32_f16 v[92:95], v[116:119], v[196:199], v[92:95]
	v_mfma_f32_16x16x32_f16 v[88:91], v[128:131], v[196:199], v[88:91]
	v_mfma_f32_16x16x32_f16 v[76:79], v[116:119], v[240:243], v[76:79]
	v_mfma_f32_16x16x32_f16 v[72:75], v[128:131], v[240:243], v[72:75]
	s_setprio 0
	s_setprio 1
	v_mfma_f32_16x16x32_f16 v[132:135], v[144:147], v[160:163], 0
	v_mfma_f32_16x16x32_f16 v[120:123], v[152:155], v[160:163], 0
	v_mfma_f32_16x16x32_f16 v[100:103], v[144:147], v[168:171], 0
	v_mfma_f32_16x16x32_f16 v[96:99], v[152:155], v[168:171], 0
	v_mfma_f32_16x16x32_f16 v[84:87], v[144:147], v[192:195], 0
	v_mfma_f32_16x16x32_f16 v[80:83], v[152:155], v[192:195], 0
	v_mfma_f32_16x16x32_f16 v[68:71], v[144:147], v[236:239], 0
	v_mfma_f32_16x16x32_f16 v[64:67], v[152:155], v[236:239], 0
	v_mfma_f32_16x16x32_f16 v[132:135], v[148:151], v[164:167], v[132:135]
	v_mfma_f32_16x16x32_f16 v[120:123], v[156:159], v[164:167], v[120:123]
	v_mfma_f32_16x16x32_f16 v[100:103], v[148:151], v[172:175], v[100:103]
	v_mfma_f32_16x16x32_f16 v[96:99], v[156:159], v[172:175], v[96:99]
	v_mfma_f32_16x16x32_f16 v[84:87], v[148:151], v[196:199], v[84:87]
	v_mfma_f32_16x16x32_f16 v[80:83], v[156:159], v[196:199], v[80:83]
	v_mfma_f32_16x16x32_f16 v[68:71], v[148:151], v[240:243], v[68:71]
	v_mfma_f32_16x16x32_f16 v[64:67], v[156:159], v[240:243], v[64:67]
	s_setprio 0
	s_barrier
	s_add_i32 s92, s92, s34
	v_lshl_add_u64 v[244:245], s[10:11], 0, v[176:177]
	s_mov_b32 m0, s92
	ds_read_b128 v[160:163], v225 offset:16384
	ds_read_b128 v[164:167], v225 offset:17408
	ds_read_b128 v[168:171], v225 offset:18432
	ds_read_b128 v[172:175], v225 offset:19456
	ds_read_b128 v[192:195], v225 offset:20480
	ds_read_b128 v[196:199], v225 offset:21504
	ds_read_b128 v[236:239], v225 offset:22528
	ds_read_b128 v[240:243], v225 offset:23552
	global_load_lds_dwordx4 v[244:245], off
	s_add_i32 m0, s92, 0x2000
	s_add_u32 s92, s10, 0x40000
	v_lshl_add_u64 v[246:247], s[10:11], 0, v[182:183]
	s_addc_u32 s93, s11, 0
	s_add_i32 vcc_lo, vcc_lo, s34
	global_load_lds_dwordx4 v[246:247], off
	v_lshl_add_u64 v[248:249], s[92:93], 0, v[176:177]
	s_mov_b32 m0, vcc_lo
	v_lshl_add_u64 v[250:251], s[28:29], 0, v[184:185]
	global_load_lds_dwordx4 v[248:249], off
	v_lshl_add_u64 v[248:249], s[92:93], 0, v[182:183]
	s_add_i32 m0, vcc_lo, 0x2000
	s_nop 0
	global_load_lds_dwordx4 v[248:249], off
	v_lshl_add_u64 v[248:249], s[28:29], 0, v[186:187]
	s_mov_b32 m0, s35
	s_nop 0
	global_load_lds_dwordx4 v[248:249], off
	s_mov_b32 m0, s36
	s_nop 0
	global_load_lds_dwordx4 v[250:251], off
	s_waitcnt vmcnt(8)
	s_waitcnt lgkmcnt(0)
	s_barrier
	s_setprio 1
	s_waitcnt lgkmcnt(0)
	v_mfma_f32_16x16x32_f16 v[60:63], v[112:115], v[160:163], 0
	v_mfma_f32_16x16x32_f16 v[56:59], v[124:127], v[160:163], 0
	v_mfma_f32_16x16x32_f16 v[44:47], v[112:115], v[168:171], 0
	v_mfma_f32_16x16x32_f16 v[40:43], v[124:127], v[168:171], 0
	v_mfma_f32_16x16x32_f16 v[28:31], v[112:115], v[192:195], 0
	v_mfma_f32_16x16x32_f16 v[24:27], v[124:127], v[192:195], 0
	v_mfma_f32_16x16x32_f16 v[12:15], v[112:115], v[236:239], 0
	v_mfma_f32_16x16x32_f16 v[8:11], v[124:127], v[236:239], 0
	v_mfma_f32_16x16x32_f16 v[60:63], v[116:119], v[164:167], v[60:63]
	v_mfma_f32_16x16x32_f16 v[56:59], v[128:131], v[164:167], v[56:59]
	v_mfma_f32_16x16x32_f16 v[44:47], v[116:119], v[172:175], v[44:47]
	v_mfma_f32_16x16x32_f16 v[40:43], v[128:131], v[172:175], v[40:43]
	v_mfma_f32_16x16x32_f16 v[28:31], v[116:119], v[196:199], v[28:31]
	v_mfma_f32_16x16x32_f16 v[24:27], v[128:131], v[196:199], v[24:27]
	v_mfma_f32_16x16x32_f16 v[12:15], v[116:119], v[240:243], v[12:15]
	v_mfma_f32_16x16x32_f16 v[8:11], v[128:131], v[240:243], v[8:11]
	s_setprio 0
	s_setprio 1
	v_mfma_f32_16x16x32_f16 v[52:55], v[144:147], v[160:163], 0
	v_mfma_f32_16x16x32_f16 v[48:51], v[152:155], v[160:163], 0
	v_mfma_f32_16x16x32_f16 v[36:39], v[144:147], v[168:171], 0
	v_mfma_f32_16x16x32_f16 v[32:35], v[152:155], v[168:171], 0
	v_mfma_f32_16x16x32_f16 v[20:23], v[144:147], v[192:195], 0
	v_mfma_f32_16x16x32_f16 v[16:19], v[152:155], v[192:195], 0
	v_mfma_f32_16x16x32_f16 v[4:7], v[144:147], v[236:239], 0
	v_mfma_f32_16x16x32_f16 v[0:3], v[152:155], v[236:239], 0
	v_mfma_f32_16x16x32_f16 v[52:55], v[148:151], v[164:167], v[52:55]
	v_mfma_f32_16x16x32_f16 v[48:51], v[156:159], v[164:167], v[48:51]
	v_mfma_f32_16x16x32_f16 v[36:39], v[148:151], v[172:175], v[36:39]
	v_mfma_f32_16x16x32_f16 v[32:35], v[156:159], v[172:175], v[32:35]
	v_mfma_f32_16x16x32_f16 v[20:23], v[148:151], v[196:199], v[20:23]
	v_mfma_f32_16x16x32_f16 v[16:19], v[156:159], v[196:199], v[16:19]
	v_mfma_f32_16x16x32_f16 v[4:7], v[148:151], v[240:243], v[4:7]
	v_mfma_f32_16x16x32_f16 v[0:3], v[156:159], v[240:243], v[0:3]
	s_setprio 0
	s_barrier
	s_add_i32 s92, 0, 0x18000
	s_add_i32 s93, 0, 0x1c000
	v_add_u32_e32 v128, s92, v211
	v_add_u32_e32 v156, s93, v211
	ds_read_b128 v[112:115], v128
	ds_read_b128 v[116:119], v128 offset:1024
	ds_read_b128 v[124:127], v128 offset:2048
	ds_read_b128 v[128:131], v128 offset:3072
	ds_read_b128 v[144:147], v156
	ds_read_b128 v[148:151], v156 offset:1024
	ds_read_b128 v[152:155], v156 offset:2048
	ds_read_b128 v[156:159], v156 offset:3072
	s_add_u32 s28, s28, 0x40000
	s_addc_u32 s29, s29, 0
	s_mov_b32 m0, s37
	v_lshl_add_u64 v[252:253], s[28:29], 0, v[186:187]
	ds_read_b128 v[160:163], v225 offset:32768
	ds_read_b128 v[164:167], v225 offset:33792
	ds_read_b128 v[168:171], v225 offset:34816
	ds_read_b128 v[172:175], v225 offset:35840
	ds_read_b128 v[192:195], v225 offset:36864
	ds_read_b128 v[196:199], v225 offset:37888
	ds_read_b128 v[236:239], v225 offset:38912
	ds_read_b128 v[240:243], v225 offset:39936
	global_load_lds_dwordx4 v[252:253], off
	v_lshl_add_u64 v[252:253], s[28:29], 0, v[184:185]
	s_mov_b32 m0, s54
	s_nop 0
	global_load_lds_dwordx4 v[252:253], off
	s_waitcnt vmcnt(8)
	s_waitcnt lgkmcnt(0)
	s_barrier
	s_setprio 1
	s_waitcnt lgkmcnt(0)
	v_mfma_f32_16x16x32_f16 v[140:143], v[112:115], v[160:163], v[140:143]
	v_mfma_f32_16x16x32_f16 v[136:139], v[124:127], v[160:163], v[136:139]
	v_mfma_f32_16x16x32_f16 v[108:111], v[112:115], v[168:171], v[108:111]
	v_mfma_f32_16x16x32_f16 v[104:107], v[124:127], v[168:171], v[104:107]
	v_mfma_f32_16x16x32_f16 v[92:95], v[112:115], v[192:195], v[92:95]
	v_mfma_f32_16x16x32_f16 v[88:91], v[124:127], v[192:195], v[88:91]
	v_mfma_f32_16x16x32_f16 v[76:79], v[112:115], v[236:239], v[76:79]
	v_mfma_f32_16x16x32_f16 v[72:75], v[124:127], v[236:239], v[72:75]
	v_mfma_f32_16x16x32_f16 v[140:143], v[116:119], v[164:167], v[140:143]
	v_mfma_f32_16x16x32_f16 v[136:139], v[128:131], v[164:167], v[136:139]
	v_mfma_f32_16x16x32_f16 v[108:111], v[116:119], v[172:175], v[108:111]
	v_mfma_f32_16x16x32_f16 v[104:107], v[128:131], v[172:175], v[104:107]
	v_mfma_f32_16x16x32_f16 v[92:95], v[116:119], v[196:199], v[92:95]
	v_mfma_f32_16x16x32_f16 v[88:91], v[128:131], v[196:199], v[88:91]
	v_mfma_f32_16x16x32_f16 v[76:79], v[116:119], v[240:243], v[76:79]
	v_mfma_f32_16x16x32_f16 v[72:75], v[128:131], v[240:243], v[72:75]
	s_setprio 0
	s_setprio 1
	v_mfma_f32_16x16x32_f16 v[132:135], v[144:147], v[160:163], v[132:135]
	v_mfma_f32_16x16x32_f16 v[120:123], v[152:155], v[160:163], v[120:123]
	v_mfma_f32_16x16x32_f16 v[100:103], v[144:147], v[168:171], v[100:103]
	v_mfma_f32_16x16x32_f16 v[96:99], v[152:155], v[168:171], v[96:99]
	v_mfma_f32_16x16x32_f16 v[84:87], v[144:147], v[192:195], v[84:87]
	v_mfma_f32_16x16x32_f16 v[80:83], v[152:155], v[192:195], v[80:83]
	v_mfma_f32_16x16x32_f16 v[68:71], v[144:147], v[236:239], v[68:71]
	v_mfma_f32_16x16x32_f16 v[64:67], v[152:155], v[236:239], v[64:67]
	v_mfma_f32_16x16x32_f16 v[132:135], v[148:151], v[164:167], v[132:135]
	v_mfma_f32_16x16x32_f16 v[120:123], v[156:159], v[164:167], v[120:123]
	v_mfma_f32_16x16x32_f16 v[100:103], v[148:151], v[172:175], v[100:103]
	v_mfma_f32_16x16x32_f16 v[96:99], v[156:159], v[172:175], v[96:99]
	v_mfma_f32_16x16x32_f16 v[84:87], v[148:151], v[196:199], v[84:87]
	v_mfma_f32_16x16x32_f16 v[80:83], v[156:159], v[196:199], v[80:83]
	v_mfma_f32_16x16x32_f16 v[68:71], v[148:151], v[240:243], v[68:71]
	v_mfma_f32_16x16x32_f16 v[64:67], v[156:159], v[240:243], v[64:67]
	s_setprio 0
	s_barrier
	s_add_i32 s28, s92, s34
	v_lshl_add_u64 v[244:245], v[244:245], 0, s[72:73]
	s_mov_b32 m0, s28
	ds_read_b128 v[160:163], v225 offset:49152
	ds_read_b128 v[164:167], v225 offset:50176
	ds_read_b128 v[168:171], v225 offset:51200
	ds_read_b128 v[172:175], v225 offset:52224
	ds_read_b128 v[192:195], v225 offset:53248
	ds_read_b128 v[196:199], v225 offset:54272
	ds_read_b128 v[236:239], v225 offset:55296
	ds_read_b128 v[240:243], v225 offset:56320
	global_load_lds_dwordx4 v[244:245], off
	s_add_i32 m0, s28, 0x2000
	s_add_u32 s10, s10, 0x40080
	v_lshl_add_u64 v[244:245], v[246:247], 0, s[72:73]
	s_addc_u32 s11, s11, 0
	s_add_i32 s28, s93, s34
	global_load_lds_dwordx4 v[244:245], off
	v_lshl_add_u64 v[244:245], s[10:11], 0, v[176:177]
	s_mov_b32 m0, s28
	s_nop 0
	global_load_lds_dwordx4 v[244:245], off
	v_lshl_add_u64 v[244:245], s[10:11], 0, v[182:183]
	s_add_i32 m0, s28, 0x2000
	s_nop 0
	global_load_lds_dwordx4 v[244:245], off
	v_lshl_add_u64 v[244:245], v[248:249], 0, s[72:73]
	s_mov_b32 m0, s55
	s_nop 0
	global_load_lds_dwordx4 v[244:245], off
	v_lshl_add_u64 v[244:245], v[250:251], 0, s[72:73]
	s_mov_b32 m0, s56
	s_nop 0
	global_load_lds_dwordx4 v[244:245], off
	s_waitcnt vmcnt(8)
	s_waitcnt lgkmcnt(0)
	s_barrier
	s_setprio 1
	s_waitcnt lgkmcnt(0)
	v_mfma_f32_16x16x32_f16 v[60:63], v[112:115], v[160:163], v[60:63]
	v_mfma_f32_16x16x32_f16 v[56:59], v[124:127], v[160:163], v[56:59]
	v_mfma_f32_16x16x32_f16 v[44:47], v[112:115], v[168:171], v[44:47]
	v_mfma_f32_16x16x32_f16 v[40:43], v[124:127], v[168:171], v[40:43]
	v_mfma_f32_16x16x32_f16 v[28:31], v[112:115], v[192:195], v[28:31]
	v_mfma_f32_16x16x32_f16 v[24:27], v[124:127], v[192:195], v[24:27]
	v_mfma_f32_16x16x32_f16 v[12:15], v[112:115], v[236:239], v[12:15]
	v_mfma_f32_16x16x32_f16 v[8:11], v[124:127], v[236:239], v[8:11]
	v_mfma_f32_16x16x32_f16 v[60:63], v[116:119], v[164:167], v[60:63]
	v_mfma_f32_16x16x32_f16 v[56:59], v[128:131], v[164:167], v[56:59]
	v_mfma_f32_16x16x32_f16 v[44:47], v[116:119], v[172:175], v[44:47]
	v_mfma_f32_16x16x32_f16 v[40:43], v[128:131], v[172:175], v[40:43]
	v_mfma_f32_16x16x32_f16 v[28:31], v[116:119], v[196:199], v[28:31]
	v_mfma_f32_16x16x32_f16 v[24:27], v[128:131], v[196:199], v[24:27]
	v_mfma_f32_16x16x32_f16 v[12:15], v[116:119], v[240:243], v[12:15]
	v_mfma_f32_16x16x32_f16 v[8:11], v[128:131], v[240:243], v[8:11]
	s_setprio 0
	s_setprio 1
	v_mfma_f32_16x16x32_f16 v[52:55], v[144:147], v[160:163], v[52:55]
	v_mfma_f32_16x16x32_f16 v[48:51], v[152:155], v[160:163], v[48:51]
	v_mfma_f32_16x16x32_f16 v[36:39], v[144:147], v[168:171], v[36:39]
	v_mfma_f32_16x16x32_f16 v[32:35], v[152:155], v[168:171], v[32:35]
	v_mfma_f32_16x16x32_f16 v[20:23], v[144:147], v[192:195], v[20:23]
	v_mfma_f32_16x16x32_f16 v[16:19], v[152:155], v[192:195], v[16:19]
	v_mfma_f32_16x16x32_f16 v[4:7], v[144:147], v[236:239], v[4:7]
	v_mfma_f32_16x16x32_f16 v[0:3], v[152:155], v[236:239], v[0:3]
	v_mfma_f32_16x16x32_f16 v[52:55], v[148:151], v[164:167], v[52:55]
	v_mfma_f32_16x16x32_f16 v[48:51], v[156:159], v[164:167], v[48:51]
	v_mfma_f32_16x16x32_f16 v[36:39], v[148:151], v[172:175], v[36:39]
	v_mfma_f32_16x16x32_f16 v[32:35], v[156:159], v[172:175], v[32:35]
	v_mfma_f32_16x16x32_f16 v[20:23], v[148:151], v[196:199], v[20:23]
	v_mfma_f32_16x16x32_f16 v[16:19], v[156:159], v[196:199], v[16:19]
	v_mfma_f32_16x16x32_f16 v[4:7], v[148:151], v[240:243], v[4:7]
	v_mfma_f32_16x16x32_f16 v[0:3], v[156:159], v[240:243], v[0:3]
	s_setprio 0
	s_barrier
	s_add_i32 s53, s53, 2
	s_add_u32 s86, s86, 0x100
	s_addc_u32 s87, s87, 0
	s_add_u32 s0, s0, 0x100
	s_addc_u32 s1, s1, 0
	s_cmp_gt_u32 s53, 13

.LBB0_710:
	s_ashr_i32 s11, s10, 31
	s_lshl_b64 s[12:13], s[10:11], 19
	s_add_u32 s12, s44, s12
	s_addc_u32 s13, s45, s13
	s_and_b64 s[14:15], s[4:5], exec
	s_cselect_b32 s11, s13, s19
	s_cselect_b32 s37, s12, s18
	s_ashr_i32 s9, s8, 31
	s_lshl_b64 s[14:15], s[8:9], 19
	s_add_u32 s14, s22, s14
	s_addc_u32 s15, s23, s15
	s_and_b64 s[20:21], s[4:5], exec
	s_cselect_b32 s9, s15, s17
	s_cselect_b32 s54, s14, s16
	s_add_u32 s55, s16, 0x100
	s_addc_u32 s56, s17, 0
	s_add_u32 s16, s18, 0x40080
	s_addc_u32 s17, s19, 0
	s_mov_b32 s53, -2
	s_add_u32 s18, s16, 0xfffc0080
	s_addc_u32 s19, s17, -1
	s_add_i32 s57, 0, 0x10000
	s_cmp_eq_u32 s53, 12
	s_cselect_b32 s21, s11, s19
	s_cselect_b32 s20, s37, s18
	v_add_u32_e32 v140, s57, v143
	s_cselect_b32 s19, s9, s56
	s_cselect_b32 s18, s54, s55
	s_add_i32 s85, 0, 0x14000
	ds_read_b128 v[148:151], v140
	ds_read_b128 v[152:155], v140 offset:1024
	ds_read_b128 v[156:159], v140 offset:2048
	ds_read_b128 v[160:163], v140 offset:3072
	v_add_u32_e32 v140, s85, v143
	ds_read_b128 v[164:167], v140
	ds_read_b128 v[168:171], v140 offset:1024
	ds_read_b128 v[172:175], v140 offset:2048
	ds_read_b128 v[182:185], v140 offset:3072
	v_lshl_add_u64 v[140:141], s[16:17], 0, v[138:139]
	s_add_i32 m0, s25, 0xc000
	ds_read_b128 v[186:189], v147
	ds_read_b128 v[190:193], v147 offset:1024
	ds_read_b128 v[194:197], v147 offset:2048
	ds_read_b128 v[210:213], v147 offset:3072
	ds_read_b128 v[214:217], v147 offset:4096
	ds_read_b128 v[218:221], v147 offset:5120
	ds_read_b128 v[222:225], v147 offset:6144
	ds_read_b128 v[226:229], v147 offset:7168
	global_load_lds_dwordx4 v[140:141], off
	v_lshl_add_u64 v[140:141], s[16:17], 0, v[136:137]
	s_add_i32 m0, s25, 0xe000
	s_nop 0
	global_load_lds_dwordx4 v[140:141], off
	s_waitcnt vmcnt(8)
	s_waitcnt lgkmcnt(0)
	s_barrier
	s_setprio 1
	s_waitcnt lgkmcnt(0)
	v_mfma_f32_16x16x32_f16 v[124:127], v[148:151], v[186:189], 0
	v_mfma_f32_16x16x32_f16 v[120:123], v[156:159], v[186:189], 0
	v_mfma_f32_16x16x32_f16 v[112:115], v[148:151], v[194:197], 0
	v_mfma_f32_16x16x32_f16 v[104:107], v[156:159], v[194:197], 0
	v_mfma_f32_16x16x32_f16 v[96:99], v[148:151], v[214:217], 0
	v_mfma_f32_16x16x32_f16 v[88:91], v[156:159], v[214:217], 0
	v_mfma_f32_16x16x32_f16 v[80:83], v[148:151], v[222:225], 0
	v_mfma_f32_16x16x32_f16 v[72:75], v[156:159], v[222:225], 0
	v_mfma_f32_16x16x32_f16 v[124:127], v[152:155], v[190:193], v[124:127]
	v_mfma_f32_16x16x32_f16 v[120:123], v[160:163], v[190:193], v[120:123]
	v_mfma_f32_16x16x32_f16 v[112:115], v[152:155], v[210:213], v[112:115]
	v_mfma_f32_16x16x32_f16 v[104:107], v[160:163], v[210:213], v[104:107]
	v_mfma_f32_16x16x32_f16 v[96:99], v[152:155], v[218:221], v[96:99]
	v_mfma_f32_16x16x32_f16 v[88:91], v[160:163], v[218:221], v[88:91]
	v_mfma_f32_16x16x32_f16 v[80:83], v[152:155], v[226:229], v[80:83]
	v_mfma_f32_16x16x32_f16 v[72:75], v[160:163], v[226:229], v[72:75]
	s_setprio 0
	s_setprio 1
	v_mfma_f32_16x16x32_f16 v[116:119], v[164:167], v[186:189], 0
	v_mfma_f32_16x16x32_f16 v[108:111], v[172:175], v[186:189], 0
	v_mfma_f32_16x16x32_f16 v[100:103], v[164:167], v[194:197], 0
	v_mfma_f32_16x16x32_f16 v[92:95], v[172:175], v[194:197], 0
	v_mfma_f32_16x16x32_f16 v[84:87], v[164:167], v[214:217], 0
	v_mfma_f32_16x16x32_f16 v[76:79], v[172:175], v[214:217], 0
	v_mfma_f32_16x16x32_f16 v[68:71], v[164:167], v[222:225], 0
	v_mfma_f32_16x16x32_f16 v[64:67], v[172:175], v[222:225], 0
	v_mfma_f32_16x16x32_f16 v[116:119], v[168:171], v[190:193], v[116:119]
	v_mfma_f32_16x16x32_f16 v[108:111], v[182:185], v[190:193], v[108:111]
	v_mfma_f32_16x16x32_f16 v[100:103], v[168:171], v[210:213], v[100:103]
	v_mfma_f32_16x16x32_f16 v[92:95], v[182:185], v[210:213], v[92:95]
	v_mfma_f32_16x16x32_f16 v[84:87], v[168:171], v[218:221], v[84:87]
	v_mfma_f32_16x16x32_f16 v[76:79], v[182:185], v[218:221], v[76:79]
	v_mfma_f32_16x16x32_f16 v[68:71], v[168:171], v[226:229], v[68:71]
	v_mfma_f32_16x16x32_f16 v[64:67], v[182:185], v[226:229], v[64:67]
	s_setprio 0
	s_barrier
	s_add_i32 s57, s57, s24
	v_lshl_add_u64 v[140:141], s[18:19], 0, v[132:133]
	s_mov_b32 m0, s57
	ds_read_b128 v[186:189], v147 offset:16384
	ds_read_b128 v[190:193], v147 offset:17408
	ds_read_b128 v[194:197], v147 offset:18432
	ds_read_b128 v[210:213], v147 offset:19456
	ds_read_b128 v[214:217], v147 offset:20480
	ds_read_b128 v[218:221], v147 offset:21504
	ds_read_b128 v[222:225], v147 offset:22528
	ds_read_b128 v[226:229], v147 offset:23552
	global_load_lds_dwordx4 v[140:141], off
	s_add_i32 m0, s57, 0x2000
	s_add_u32 s70, s18, 0x40000
	v_lshl_add_u64 v[198:199], s[18:19], 0, v[128:129]
	s_addc_u32 s71, s19, 0
	s_add_i32 s57, s85, s24
	global_load_lds_dwordx4 v[198:199], off
	v_lshl_add_u64 v[230:231], s[70:71], 0, v[132:133]
	s_mov_b32 m0, s57
	v_lshl_add_u64 v[232:233], s[20:21], 0, v[130:131]
	global_load_lds_dwordx4 v[230:231], off
	v_lshl_add_u64 v[230:231], s[70:71], 0, v[128:129]
	s_add_i32 m0, s57, 0x2000
	s_nop 0
	global_load_lds_dwordx4 v[230:231], off
	v_lshl_add_u64 v[230:231], s[20:21], 0, v[134:135]
	s_mov_b32 m0, s25
	s_nop 0
	global_load_lds_dwordx4 v[230:231], off
	s_mov_b32 m0, s26
	s_nop 0
	global_load_lds_dwordx4 v[232:233], off
	s_waitcnt vmcnt(8)
	s_waitcnt lgkmcnt(0)
	s_barrier
	s_setprio 1
	s_waitcnt lgkmcnt(0)
	v_mfma_f32_16x16x32_f16 v[60:63], v[148:151], v[186:189], 0
	v_mfma_f32_16x16x32_f16 v[56:59], v[156:159], v[186:189], 0
	v_mfma_f32_16x16x32_f16 v[52:55], v[148:151], v[194:197], 0
	v_mfma_f32_16x16x32_f16 v[44:47], v[156:159], v[194:197], 0
	v_mfma_f32_16x16x32_f16 v[36:39], v[148:151], v[214:217], 0
	v_mfma_f32_16x16x32_f16 v[28:31], v[156:159], v[214:217], 0
	v_mfma_f32_16x16x32_f16 v[20:23], v[148:151], v[222:225], 0
	v_mfma_f32_16x16x32_f16 v[12:15], v[156:159], v[222:225], 0
	v_mfma_f32_16x16x32_f16 v[60:63], v[152:155], v[190:193], v[60:63]
	v_mfma_f32_16x16x32_f16 v[56:59], v[160:163], v[190:193], v[56:59]
	v_mfma_f32_16x16x32_f16 v[52:55], v[152:155], v[210:213], v[52:55]
	v_mfma_f32_16x16x32_f16 v[44:47], v[160:163], v[210:213], v[44:47]
	v_mfma_f32_16x16x32_f16 v[36:39], v[152:155], v[218:221], v[36:39]
	v_mfma_f32_16x16x32_f16 v[28:31], v[160:163], v[218:221], v[28:31]
	v_mfma_f32_16x16x32_f16 v[20:23], v[152:155], v[226:229], v[20:23]
	v_mfma_f32_16x16x32_f16 v[12:15], v[160:163], v[226:229], v[12:15]
	s_setprio 0
	s_setprio 1
	v_mfma_f32_16x16x32_f16 v[48:51], v[164:167], v[186:189], 0
	v_mfma_f32_16x16x32_f16 v[40:43], v[172:175], v[186:189], 0
	v_mfma_f32_16x16x32_f16 v[32:35], v[164:167], v[194:197], 0
	v_mfma_f32_16x16x32_f16 v[24:27], v[172:175], v[194:197], 0
	v_mfma_f32_16x16x32_f16 v[16:19], v[164:167], v[214:217], 0
	v_mfma_f32_16x16x32_f16 v[8:11], v[172:175], v[214:217], 0
	v_mfma_f32_16x16x32_f16 v[4:7], v[164:167], v[222:225], 0
	v_mfma_f32_16x16x32_f16 v[0:3], v[172:175], v[222:225], 0
	v_mfma_f32_16x16x32_f16 v[48:51], v[168:171], v[190:193], v[48:51]
	v_mfma_f32_16x16x32_f16 v[40:43], v[182:185], v[190:193], v[40:43]
	v_mfma_f32_16x16x32_f16 v[32:35], v[168:171], v[210:213], v[32:35]
	v_mfma_f32_16x16x32_f16 v[24:27], v[182:185], v[210:213], v[24:27]
	v_mfma_f32_16x16x32_f16 v[16:19], v[168:171], v[218:221], v[16:19]
	v_mfma_f32_16x16x32_f16 v[8:11], v[182:185], v[218:221], v[8:11]
	v_mfma_f32_16x16x32_f16 v[4:7], v[168:171], v[226:229], v[4:7]
	v_mfma_f32_16x16x32_f16 v[0:3], v[182:185], v[226:229], v[0:3]
	s_setprio 0
	s_barrier
	s_add_i32 s57, 0, 0x18000
	s_add_i32 s70, 0, 0x1c000
	v_add_u32_e32 v160, s57, v143
	v_add_u32_e32 v182, s70, v143
	ds_read_b128 v[148:151], v160
	ds_read_b128 v[152:155], v160 offset:1024
	ds_read_b128 v[156:159], v160 offset:2048
	ds_read_b128 v[160:163], v160 offset:3072
	ds_read_b128 v[164:167], v182
	ds_read_b128 v[168:171], v182 offset:1024
	ds_read_b128 v[172:175], v182 offset:2048
	ds_read_b128 v[182:185], v182 offset:3072
	s_add_u32 s20, s20, 0x40000
	s_addc_u32 s21, s21, 0
	s_mov_b32 m0, s27
	v_lshl_add_u64 v[234:235], s[20:21], 0, v[134:135]
	ds_read_b128 v[186:189], v147 offset:32768
	ds_read_b128 v[190:193], v147 offset:33792
	ds_read_b128 v[194:197], v147 offset:34816
	ds_read_b128 v[210:213], v147 offset:35840
	ds_read_b128 v[214:217], v147 offset:36864
	ds_read_b128 v[218:221], v147 offset:37888
	ds_read_b128 v[222:225], v147 offset:38912
	ds_read_b128 v[226:229], v147 offset:39936
	global_load_lds_dwordx4 v[234:235], off
	v_lshl_add_u64 v[234:235], s[20:21], 0, v[130:131]
	s_mov_b32 m0, s28
	s_nop 0
	global_load_lds_dwordx4 v[234:235], off
	s_waitcnt vmcnt(8)
	s_waitcnt lgkmcnt(0)
	s_barrier
	s_setprio 1
	s_waitcnt lgkmcnt(0)
	v_mfma_f32_16x16x32_f16 v[124:127], v[148:151], v[186:189], v[124:127]
	v_mfma_f32_16x16x32_f16 v[120:123], v[156:159], v[186:189], v[120:123]
	v_mfma_f32_16x16x32_f16 v[112:115], v[148:151], v[194:197], v[112:115]
	v_mfma_f32_16x16x32_f16 v[104:107], v[156:159], v[194:197], v[104:107]
	v_mfma_f32_16x16x32_f16 v[96:99], v[148:151], v[214:217], v[96:99]
	v_mfma_f32_16x16x32_f16 v[88:91], v[156:159], v[214:217], v[88:91]
	v_mfma_f32_16x16x32_f16 v[80:83], v[148:151], v[222:225], v[80:83]
	v_mfma_f32_16x16x32_f16 v[72:75], v[156:159], v[222:225], v[72:75]
	v_mfma_f32_16x16x32_f16 v[124:127], v[152:155], v[190:193], v[124:127]
	v_mfma_f32_16x16x32_f16 v[120:123], v[160:163], v[190:193], v[120:123]
	v_mfma_f32_16x16x32_f16 v[112:115], v[152:155], v[210:213], v[112:115]
	v_mfma_f32_16x16x32_f16 v[104:107], v[160:163], v[210:213], v[104:107]
	v_mfma_f32_16x16x32_f16 v[96:99], v[152:155], v[218:221], v[96:99]
	v_mfma_f32_16x16x32_f16 v[88:91], v[160:163], v[218:221], v[88:91]
	v_mfma_f32_16x16x32_f16 v[80:83], v[152:155], v[226:229], v[80:83]
	v_mfma_f32_16x16x32_f16 v[72:75], v[160:163], v[226:229], v[72:75]
	s_setprio 0
	s_setprio 1
	v_mfma_f32_16x16x32_f16 v[116:119], v[164:167], v[186:189], v[116:119]
	v_mfma_f32_16x16x32_f16 v[108:111], v[172:175], v[186:189], v[108:111]
	v_mfma_f32_16x16x32_f16 v[100:103], v[164:167], v[194:197], v[100:103]
	v_mfma_f32_16x16x32_f16 v[92:95], v[172:175], v[194:197], v[92:95]
	v_mfma_f32_16x16x32_f16 v[84:87], v[164:167], v[214:217], v[84:87]
	v_mfma_f32_16x16x32_f16 v[76:79], v[172:175], v[214:217], v[76:79]
	v_mfma_f32_16x16x32_f16 v[68:71], v[164:167], v[222:225], v[68:71]
	v_mfma_f32_16x16x32_f16 v[64:67], v[172:175], v[222:225], v[64:67]
	v_mfma_f32_16x16x32_f16 v[116:119], v[168:171], v[190:193], v[116:119]
	v_mfma_f32_16x16x32_f16 v[108:111], v[182:185], v[190:193], v[108:111]
	v_mfma_f32_16x16x32_f16 v[100:103], v[168:171], v[210:213], v[100:103]
	v_mfma_f32_16x16x32_f16 v[92:95], v[182:185], v[210:213], v[92:95]
	v_mfma_f32_16x16x32_f16 v[84:87], v[168:171], v[218:221], v[84:87]
	v_mfma_f32_16x16x32_f16 v[76:79], v[182:185], v[218:221], v[76:79]
	v_mfma_f32_16x16x32_f16 v[68:71], v[168:171], v[226:229], v[68:71]
	v_mfma_f32_16x16x32_f16 v[64:67], v[182:185], v[226:229], v[64:67]
	s_setprio 0
	s_barrier
	s_add_i32 s20, s57, s24
	v_lshl_add_u64 v[140:141], v[140:141], 0, s[72:73]
	s_mov_b32 m0, s20
	ds_read_b128 v[186:189], v147 offset:49152
	ds_read_b128 v[190:193], v147 offset:50176
	ds_read_b128 v[194:197], v147 offset:51200
	ds_read_b128 v[210:213], v147 offset:52224
	ds_read_b128 v[214:217], v147 offset:53248
	ds_read_b128 v[218:221], v147 offset:54272
	ds_read_b128 v[222:225], v147 offset:55296
	ds_read_b128 v[226:229], v147 offset:56320
	global_load_lds_dwordx4 v[140:141], off
	s_add_i32 m0, s20, 0x2000
	s_add_u32 s18, s18, 0x40080
	v_lshl_add_u64 v[140:141], v[198:199], 0, s[72:73]
	s_addc_u32 s19, s19, 0
	s_add_i32 s20, s70, s24
	global_load_lds_dwordx4 v[140:141], off
	v_lshl_add_u64 v[140:141], s[18:19], 0, v[132:133]
	s_mov_b32 m0, s20
	s_nop 0
	global_load_lds_dwordx4 v[140:141], off
	v_lshl_add_u64 v[140:141], s[18:19], 0, v[128:129]
	s_add_i32 m0, s20, 0x2000
	s_nop 0
	global_load_lds_dwordx4 v[140:141], off
	v_lshl_add_u64 v[140:141], v[230:231], 0, s[72:73]
	s_mov_b32 m0, s29
	s_nop 0
	global_load_lds_dwordx4 v[140:141], off
	v_lshl_add_u64 v[140:141], v[232:233], 0, s[72:73]
	s_mov_b32 m0, s30
	s_nop 0
	global_load_lds_dwordx4 v[140:141], off
	s_waitcnt vmcnt(8)
	s_waitcnt lgkmcnt(0)
	s_barrier
	s_setprio 1
	s_waitcnt lgkmcnt(0)
	v_mfma_f32_16x16x32_f16 v[60:63], v[148:151], v[186:189], v[60:63]
	v_mfma_f32_16x16x32_f16 v[56:59], v[156:159], v[186:189], v[56:59]
	v_mfma_f32_16x16x32_f16 v[52:55], v[148:151], v[194:197], v[52:55]
	v_mfma_f32_16x16x32_f16 v[44:47], v[156:159], v[194:197], v[44:47]
	v_mfma_f32_16x16x32_f16 v[36:39], v[148:151], v[214:217], v[36:39]
	v_mfma_f32_16x16x32_f16 v[28:31], v[156:159], v[214:217], v[28:31]
	v_mfma_f32_16x16x32_f16 v[20:23], v[148:151], v[222:225], v[20:23]
	v_mfma_f32_16x16x32_f16 v[12:15], v[156:159], v[222:225], v[12:15]
	v_mfma_f32_16x16x32_f16 v[60:63], v[152:155], v[190:193], v[60:63]
	v_mfma_f32_16x16x32_f16 v[56:59], v[160:163], v[190:193], v[56:59]
	v_mfma_f32_16x16x32_f16 v[52:55], v[152:155], v[210:213], v[52:55]
	v_mfma_f32_16x16x32_f16 v[44:47], v[160:163], v[210:213], v[44:47]
	v_mfma_f32_16x16x32_f16 v[36:39], v[152:155], v[218:221], v[36:39]
	v_mfma_f32_16x16x32_f16 v[28:31], v[160:163], v[218:221], v[28:31]
	v_mfma_f32_16x16x32_f16 v[20:23], v[152:155], v[226:229], v[20:23]
	v_mfma_f32_16x16x32_f16 v[12:15], v[160:163], v[226:229], v[12:15]
	s_setprio 0
	s_setprio 1
	v_mfma_f32_16x16x32_f16 v[48:51], v[164:167], v[186:189], v[48:51]
	v_mfma_f32_16x16x32_f16 v[40:43], v[172:175], v[186:189], v[40:43]
	v_mfma_f32_16x16x32_f16 v[32:35], v[164:167], v[194:197], v[32:35]
	v_mfma_f32_16x16x32_f16 v[24:27], v[172:175], v[194:197], v[24:27]
	v_mfma_f32_16x16x32_f16 v[16:19], v[164:167], v[214:217], v[16:19]
	v_mfma_f32_16x16x32_f16 v[8:11], v[172:175], v[214:217], v[8:11]
	v_mfma_f32_16x16x32_f16 v[4:7], v[164:167], v[222:225], v[4:7]
	v_mfma_f32_16x16x32_f16 v[0:3], v[172:175], v[222:225], v[0:3]
	v_mfma_f32_16x16x32_f16 v[48:51], v[168:171], v[190:193], v[48:51]
	v_mfma_f32_16x16x32_f16 v[40:43], v[182:185], v[190:193], v[40:43]
	v_mfma_f32_16x16x32_f16 v[32:35], v[168:171], v[210:213], v[32:35]
	v_mfma_f32_16x16x32_f16 v[24:27], v[182:185], v[210:213], v[24:27]
	v_mfma_f32_16x16x32_f16 v[16:19], v[168:171], v[218:221], v[16:19]
	v_mfma_f32_16x16x32_f16 v[8:11], v[182:185], v[218:221], v[8:11]
	v_mfma_f32_16x16x32_f16 v[4:7], v[168:171], v[226:229], v[4:7]
	v_mfma_f32_16x16x32_f16 v[0:3], v[182:185], v[226:229], v[0:3]
	s_setprio 0
	s_barrier
	s_add_i32 s53, s53, 2
	s_add_u32 s55, s55, 0x100
	s_addc_u32 s56, s56, 0
	s_add_u32 s16, s16, 0x100
	s_addc_u32 s17, s17, 0
	s_cmp_gt_u32 s53, 13

.LBB0_756:
	s_ashr_i32 s11, s10, 31
	s_lshl_b64 s[12:13], s[10:11], 19
	s_add_u32 s12, s20, s12
	s_addc_u32 s13, s21, s13
	s_and_b64 s[14:15], s[2:3], exec
	s_cselect_b32 s11, s13, s17
	s_cselect_b32 s34, s12, s16
	s_ashr_i32 s9, s8, 31
	s_lshl_b64 s[14:15], s[8:9], 19
	s_add_u32 s14, s44, s14
	s_addc_u32 s15, s45, s15
	s_and_b64 s[18:19], s[2:3], exec
	s_cselect_b32 s9, s15, s1
	s_cselect_b32 s35, s14, s0
	s_add_u32 s36, s0, 0x100
	s_addc_u32 s37, s1, 0
	s_add_u32 s0, s16, 0x40080
	s_addc_u32 s1, s17, 0
	s_mov_b32 s53, -2
	s_add_u32 s16, s0, 0xfffc0080
	s_addc_u32 s17, s1, -1
	s_add_i32 s54, 0, 0x10000
	s_cmp_eq_u32 s53, 12
	s_cselect_b32 s19, s11, s17
	s_cselect_b32 s18, s34, s16
	s_cselect_b32 s17, s9, s37
	s_cselect_b32 s16, s35, s36
	s_add_i32 s56, 0, 0x14000
	v_add_u32_e32 v150, s54, v167
	v_add_u32_e32 v170, s56, v167
	ds_read_b128 v[128:131], v150
	ds_read_b128 v[132:135], v150 offset:1024
	ds_read_b128 v[136:139], v150 offset:2048
	ds_read_b128 v[150:153], v150 offset:3072
	ds_read_b128 v[154:157], v170
	ds_read_b128 v[158:161], v170 offset:1024
	ds_read_b128 v[162:165], v170 offset:2048
	ds_read_b128 v[170:173], v170 offset:3072
	v_lshl_add_u64 v[174:175], s[0:1], 0, v[148:149]
	s_add_i32 m0, s23, 0xc000
	ds_read_b128 v[182:185], v169
	ds_read_b128 v[186:189], v169 offset:1024
	ds_read_b128 v[190:193], v169 offset:2048
	ds_read_b128 v[194:197], v169 offset:3072
	ds_read_b128 v[210:213], v169 offset:4096
	ds_read_b128 v[214:217], v169 offset:5120
	ds_read_b128 v[218:221], v169 offset:6144
	ds_read_b128 v[222:225], v169 offset:7168
	global_load_lds_dwordx4 v[174:175], off
	v_lshl_add_u64 v[174:175], s[0:1], 0, v[146:147]
	s_add_i32 m0, s23, 0xe000
	s_nop 0
	global_load_lds_dwordx4 v[174:175], off
	s_waitcnt vmcnt(8)
	s_waitcnt lgkmcnt(0)
	s_barrier
	s_setprio 1
	s_waitcnt lgkmcnt(0)
	v_mfma_f32_16x16x32_f16 v[124:127], v[128:131], v[182:185], 0
	v_mfma_f32_16x16x32_f16 v[120:123], v[136:139], v[182:185], 0
	v_mfma_f32_16x16x32_f16 v[112:115], v[128:131], v[190:193], 0
	v_mfma_f32_16x16x32_f16 v[104:107], v[136:139], v[190:193], 0
	v_mfma_f32_16x16x32_f16 v[96:99], v[128:131], v[210:213], 0
	v_mfma_f32_16x16x32_f16 v[88:91], v[136:139], v[210:213], 0
	v_mfma_f32_16x16x32_f16 v[80:83], v[128:131], v[218:221], 0
	v_mfma_f32_16x16x32_f16 v[72:75], v[136:139], v[218:221], 0
	v_mfma_f32_16x16x32_f16 v[124:127], v[132:135], v[186:189], v[124:127]
	v_mfma_f32_16x16x32_f16 v[120:123], v[150:153], v[186:189], v[120:123]
	v_mfma_f32_16x16x32_f16 v[112:115], v[132:135], v[194:197], v[112:115]
	v_mfma_f32_16x16x32_f16 v[104:107], v[150:153], v[194:197], v[104:107]
	v_mfma_f32_16x16x32_f16 v[96:99], v[132:135], v[214:217], v[96:99]
	v_mfma_f32_16x16x32_f16 v[88:91], v[150:153], v[214:217], v[88:91]
	v_mfma_f32_16x16x32_f16 v[80:83], v[132:135], v[222:225], v[80:83]
	v_mfma_f32_16x16x32_f16 v[72:75], v[150:153], v[222:225], v[72:75]
	s_setprio 0
	s_setprio 1
	v_mfma_f32_16x16x32_f16 v[116:119], v[154:157], v[182:185], 0
	v_mfma_f32_16x16x32_f16 v[108:111], v[162:165], v[182:185], 0
	v_mfma_f32_16x16x32_f16 v[100:103], v[154:157], v[190:193], 0
	v_mfma_f32_16x16x32_f16 v[92:95], v[162:165], v[190:193], 0
	v_mfma_f32_16x16x32_f16 v[84:87], v[154:157], v[210:213], 0
	v_mfma_f32_16x16x32_f16 v[76:79], v[162:165], v[210:213], 0
	v_mfma_f32_16x16x32_f16 v[68:71], v[154:157], v[218:221], 0
	v_mfma_f32_16x16x32_f16 v[64:67], v[162:165], v[218:221], 0
	v_mfma_f32_16x16x32_f16 v[116:119], v[158:161], v[186:189], v[116:119]
	v_mfma_f32_16x16x32_f16 v[108:111], v[170:173], v[186:189], v[108:111]
	v_mfma_f32_16x16x32_f16 v[100:103], v[158:161], v[194:197], v[100:103]
	v_mfma_f32_16x16x32_f16 v[92:95], v[170:173], v[194:197], v[92:95]
	v_mfma_f32_16x16x32_f16 v[84:87], v[158:161], v[214:217], v[84:87]
	v_mfma_f32_16x16x32_f16 v[76:79], v[170:173], v[214:217], v[76:79]
	v_mfma_f32_16x16x32_f16 v[68:71], v[158:161], v[222:225], v[68:71]
	v_mfma_f32_16x16x32_f16 v[64:67], v[170:173], v[222:225], v[64:67]
	s_setprio 0
	s_barrier
	s_add_i32 s54, s54, s22
	v_lshl_add_u64 v[174:175], s[16:17], 0, v[176:177]
	s_mov_b32 m0, s54
	ds_read_b128 v[182:185], v169 offset:16384
	ds_read_b128 v[186:189], v169 offset:17408
	ds_read_b128 v[190:193], v169 offset:18432
	ds_read_b128 v[194:197], v169 offset:19456
	ds_read_b128 v[210:213], v169 offset:20480
	ds_read_b128 v[214:217], v169 offset:21504
	ds_read_b128 v[218:221], v169 offset:22528
	ds_read_b128 v[222:225], v169 offset:23552
	global_load_lds_dwordx4 v[174:175], off
	s_add_i32 m0, s54, 0x2000
	s_add_u32 s54, s16, 0x40000
	v_lshl_add_u64 v[198:199], s[16:17], 0, v[140:141]
	s_addc_u32 s55, s17, 0
	s_add_i32 s56, s56, s22
	global_load_lds_dwordx4 v[198:199], off
	v_lshl_add_u64 v[226:227], s[54:55], 0, v[176:177]
	s_mov_b32 m0, s56
	v_lshl_add_u64 v[228:229], s[18:19], 0, v[142:143]
	global_load_lds_dwordx4 v[226:227], off
	v_lshl_add_u64 v[226:227], s[54:55], 0, v[140:141]
	s_add_i32 m0, s56, 0x2000
	s_nop 0
	global_load_lds_dwordx4 v[226:227], off
	v_lshl_add_u64 v[226:227], s[18:19], 0, v[144:145]
	s_mov_b32 m0, s23
	s_nop 0
	global_load_lds_dwordx4 v[226:227], off
	s_mov_b32 m0, s24
	s_nop 0
	global_load_lds_dwordx4 v[228:229], off
	s_waitcnt vmcnt(8)
	s_waitcnt lgkmcnt(0)
	s_barrier
	s_setprio 1
	s_waitcnt lgkmcnt(0)
	v_mfma_f32_16x16x32_f16 v[60:63], v[128:131], v[182:185], 0
	v_mfma_f32_16x16x32_f16 v[56:59], v[136:139], v[182:185], 0
	v_mfma_f32_16x16x32_f16 v[52:55], v[128:131], v[190:193], 0
	v_mfma_f32_16x16x32_f16 v[44:47], v[136:139], v[190:193], 0
	v_mfma_f32_16x16x32_f16 v[36:39], v[128:131], v[210:213], 0
	v_mfma_f32_16x16x32_f16 v[28:31], v[136:139], v[210:213], 0
	v_mfma_f32_16x16x32_f16 v[20:23], v[128:131], v[218:221], 0
	v_mfma_f32_16x16x32_f16 v[12:15], v[136:139], v[218:221], 0
	v_mfma_f32_16x16x32_f16 v[60:63], v[132:135], v[186:189], v[60:63]
	v_mfma_f32_16x16x32_f16 v[56:59], v[150:153], v[186:189], v[56:59]
	v_mfma_f32_16x16x32_f16 v[52:55], v[132:135], v[194:197], v[52:55]
	v_mfma_f32_16x16x32_f16 v[44:47], v[150:153], v[194:197], v[44:47]
	v_mfma_f32_16x16x32_f16 v[36:39], v[132:135], v[214:217], v[36:39]
	v_mfma_f32_16x16x32_f16 v[28:31], v[150:153], v[214:217], v[28:31]
	v_mfma_f32_16x16x32_f16 v[20:23], v[132:135], v[222:225], v[20:23]
	v_mfma_f32_16x16x32_f16 v[12:15], v[150:153], v[222:225], v[12:15]
	s_setprio 0
	s_setprio 1
	v_mfma_f32_16x16x32_f16 v[48:51], v[154:157], v[182:185], 0
	v_mfma_f32_16x16x32_f16 v[40:43], v[162:165], v[182:185], 0
	v_mfma_f32_16x16x32_f16 v[32:35], v[154:157], v[190:193], 0
	v_mfma_f32_16x16x32_f16 v[24:27], v[162:165], v[190:193], 0
	v_mfma_f32_16x16x32_f16 v[16:19], v[154:157], v[210:213], 0
	v_mfma_f32_16x16x32_f16 v[8:11], v[162:165], v[210:213], 0
	v_mfma_f32_16x16x32_f16 v[4:7], v[154:157], v[218:221], 0
	v_mfma_f32_16x16x32_f16 v[0:3], v[162:165], v[218:221], 0
	v_mfma_f32_16x16x32_f16 v[48:51], v[158:161], v[186:189], v[48:51]
	v_mfma_f32_16x16x32_f16 v[40:43], v[170:173], v[186:189], v[40:43]
	v_mfma_f32_16x16x32_f16 v[32:35], v[158:161], v[194:197], v[32:35]
	v_mfma_f32_16x16x32_f16 v[24:27], v[170:173], v[194:197], v[24:27]
	v_mfma_f32_16x16x32_f16 v[16:19], v[158:161], v[214:217], v[16:19]
	v_mfma_f32_16x16x32_f16 v[8:11], v[170:173], v[214:217], v[8:11]
	v_mfma_f32_16x16x32_f16 v[4:7], v[158:161], v[222:225], v[4:7]
	v_mfma_f32_16x16x32_f16 v[0:3], v[170:173], v[222:225], v[0:3]
	s_setprio 0
	s_barrier
	s_add_i32 s54, 0, 0x18000
	s_add_i32 s55, 0, 0x1c000
	v_add_u32_e32 v150, s54, v167
	v_add_u32_e32 v170, s55, v167
	ds_read_b128 v[128:131], v150
	ds_read_b128 v[132:135], v150 offset:1024
	ds_read_b128 v[136:139], v150 offset:2048
	ds_read_b128 v[150:153], v150 offset:3072
	ds_read_b128 v[154:157], v170
	ds_read_b128 v[158:161], v170 offset:1024
	ds_read_b128 v[162:165], v170 offset:2048
	ds_read_b128 v[170:173], v170 offset:3072
	s_add_u32 s18, s18, 0x40000
	s_addc_u32 s19, s19, 0
	s_mov_b32 m0, s25
	v_lshl_add_u64 v[230:231], s[18:19], 0, v[144:145]
	ds_read_b128 v[182:185], v169 offset:32768
	ds_read_b128 v[186:189], v169 offset:33792
	ds_read_b128 v[190:193], v169 offset:34816
	ds_read_b128 v[194:197], v169 offset:35840
	ds_read_b128 v[210:213], v169 offset:36864
	ds_read_b128 v[214:217], v169 offset:37888
	ds_read_b128 v[218:221], v169 offset:38912
	ds_read_b128 v[222:225], v169 offset:39936
	global_load_lds_dwordx4 v[230:231], off
	v_lshl_add_u64 v[230:231], s[18:19], 0, v[142:143]
	s_mov_b32 m0, s26
	s_nop 0
	global_load_lds_dwordx4 v[230:231], off
	s_waitcnt vmcnt(8)
	s_waitcnt lgkmcnt(0)
	s_barrier
	s_setprio 1
	s_waitcnt lgkmcnt(0)
	v_mfma_f32_16x16x32_f16 v[124:127], v[128:131], v[182:185], v[124:127]
	v_mfma_f32_16x16x32_f16 v[120:123], v[136:139], v[182:185], v[120:123]
	v_mfma_f32_16x16x32_f16 v[112:115], v[128:131], v[190:193], v[112:115]
	v_mfma_f32_16x16x32_f16 v[104:107], v[136:139], v[190:193], v[104:107]
	v_mfma_f32_16x16x32_f16 v[96:99], v[128:131], v[210:213], v[96:99]
	v_mfma_f32_16x16x32_f16 v[88:91], v[136:139], v[210:213], v[88:91]
	v_mfma_f32_16x16x32_f16 v[80:83], v[128:131], v[218:221], v[80:83]
	v_mfma_f32_16x16x32_f16 v[72:75], v[136:139], v[218:221], v[72:75]
	v_mfma_f32_16x16x32_f16 v[124:127], v[132:135], v[186:189], v[124:127]
	v_mfma_f32_16x16x32_f16 v[120:123], v[150:153], v[186:189], v[120:123]
	v_mfma_f32_16x16x32_f16 v[112:115], v[132:135], v[194:197], v[112:115]
	v_mfma_f32_16x16x32_f16 v[104:107], v[150:153], v[194:197], v[104:107]
	v_mfma_f32_16x16x32_f16 v[96:99], v[132:135], v[214:217], v[96:99]
	v_mfma_f32_16x16x32_f16 v[88:91], v[150:153], v[214:217], v[88:91]
	v_mfma_f32_16x16x32_f16 v[80:83], v[132:135], v[222:225], v[80:83]
	v_mfma_f32_16x16x32_f16 v[72:75], v[150:153], v[222:225], v[72:75]
	s_setprio 0
	s_setprio 1
	v_mfma_f32_16x16x32_f16 v[116:119], v[154:157], v[182:185], v[116:119]
	v_mfma_f32_16x16x32_f16 v[108:111], v[162:165], v[182:185], v[108:111]
	v_mfma_f32_16x16x32_f16 v[100:103], v[154:157], v[190:193], v[100:103]
	v_mfma_f32_16x16x32_f16 v[92:95], v[162:165], v[190:193], v[92:95]
	v_mfma_f32_16x16x32_f16 v[84:87], v[154:157], v[210:213], v[84:87]
	v_mfma_f32_16x16x32_f16 v[76:79], v[162:165], v[210:213], v[76:79]
	v_mfma_f32_16x16x32_f16 v[68:71], v[154:157], v[218:221], v[68:71]
	v_mfma_f32_16x16x32_f16 v[64:67], v[162:165], v[218:221], v[64:67]
	v_mfma_f32_16x16x32_f16 v[116:119], v[158:161], v[186:189], v[116:119]
	v_mfma_f32_16x16x32_f16 v[108:111], v[170:173], v[186:189], v[108:111]
	v_mfma_f32_16x16x32_f16 v[100:103], v[158:161], v[194:197], v[100:103]
	v_mfma_f32_16x16x32_f16 v[92:95], v[170:173], v[194:197], v[92:95]
	v_mfma_f32_16x16x32_f16 v[84:87], v[158:161], v[214:217], v[84:87]
	v_mfma_f32_16x16x32_f16 v[76:79], v[170:173], v[214:217], v[76:79]
	v_mfma_f32_16x16x32_f16 v[68:71], v[158:161], v[222:225], v[68:71]
	v_mfma_f32_16x16x32_f16 v[64:67], v[170:173], v[222:225], v[64:67]
	s_setprio 0
	s_barrier
	s_add_i32 s18, s54, s22
	v_lshl_add_u64 v[174:175], v[174:175], 0, s[72:73]
	s_mov_b32 m0, s18
	ds_read_b128 v[182:185], v169 offset:49152
	ds_read_b128 v[186:189], v169 offset:50176
	ds_read_b128 v[190:193], v169 offset:51200
	ds_read_b128 v[194:197], v169 offset:52224
	ds_read_b128 v[210:213], v169 offset:53248
	ds_read_b128 v[214:217], v169 offset:54272
	ds_read_b128 v[218:221], v169 offset:55296
	ds_read_b128 v[222:225], v169 offset:56320
	global_load_lds_dwordx4 v[174:175], off
	s_add_i32 m0, s18, 0x2000
	s_add_u32 s16, s16, 0x40080
	v_lshl_add_u64 v[174:175], v[198:199], 0, s[72:73]
	s_addc_u32 s17, s17, 0
	s_add_i32 s18, s55, s22
	global_load_lds_dwordx4 v[174:175], off
	v_lshl_add_u64 v[174:175], s[16:17], 0, v[176:177]
	s_mov_b32 m0, s18
	s_nop 0
	global_load_lds_dwordx4 v[174:175], off
	v_lshl_add_u64 v[174:175], s[16:17], 0, v[140:141]
	s_add_i32 m0, s18, 0x2000
	s_nop 0
	global_load_lds_dwordx4 v[174:175], off
	v_lshl_add_u64 v[174:175], v[226:227], 0, s[72:73]
	s_mov_b32 m0, s27
	s_nop 0
	global_load_lds_dwordx4 v[174:175], off
	v_lshl_add_u64 v[174:175], v[228:229], 0, s[72:73]
	s_mov_b32 m0, s28
	s_nop 0
	global_load_lds_dwordx4 v[174:175], off
	s_waitcnt vmcnt(8)
	s_waitcnt lgkmcnt(0)
	s_barrier
	s_setprio 1
	s_waitcnt lgkmcnt(0)
	v_mfma_f32_16x16x32_f16 v[60:63], v[128:131], v[182:185], v[60:63]
	v_mfma_f32_16x16x32_f16 v[56:59], v[136:139], v[182:185], v[56:59]
	v_mfma_f32_16x16x32_f16 v[52:55], v[128:131], v[190:193], v[52:55]
	v_mfma_f32_16x16x32_f16 v[44:47], v[136:139], v[190:193], v[44:47]
	v_mfma_f32_16x16x32_f16 v[36:39], v[128:131], v[210:213], v[36:39]
	v_mfma_f32_16x16x32_f16 v[28:31], v[136:139], v[210:213], v[28:31]
	v_mfma_f32_16x16x32_f16 v[20:23], v[128:131], v[218:221], v[20:23]
	v_mfma_f32_16x16x32_f16 v[12:15], v[136:139], v[218:221], v[12:15]
	v_mfma_f32_16x16x32_f16 v[60:63], v[132:135], v[186:189], v[60:63]
	v_mfma_f32_16x16x32_f16 v[56:59], v[150:153], v[186:189], v[56:59]
	v_mfma_f32_16x16x32_f16 v[52:55], v[132:135], v[194:197], v[52:55]
	v_mfma_f32_16x16x32_f16 v[44:47], v[150:153], v[194:197], v[44:47]
	v_mfma_f32_16x16x32_f16 v[36:39], v[132:135], v[214:217], v[36:39]
	v_mfma_f32_16x16x32_f16 v[28:31], v[150:153], v[214:217], v[28:31]
	v_mfma_f32_16x16x32_f16 v[20:23], v[132:135], v[222:225], v[20:23]
	v_mfma_f32_16x16x32_f16 v[12:15], v[150:153], v[222:225], v[12:15]
	s_setprio 0
	s_setprio 1
	v_mfma_f32_16x16x32_f16 v[48:51], v[154:157], v[182:185], v[48:51]
	v_mfma_f32_16x16x32_f16 v[40:43], v[162:165], v[182:185], v[40:43]
	v_mfma_f32_16x16x32_f16 v[32:35], v[154:157], v[190:193], v[32:35]
	v_mfma_f32_16x16x32_f16 v[24:27], v[162:165], v[190:193], v[24:27]
	v_mfma_f32_16x16x32_f16 v[16:19], v[154:157], v[210:213], v[16:19]
	v_mfma_f32_16x16x32_f16 v[8:11], v[162:165], v[210:213], v[8:11]
	v_mfma_f32_16x16x32_f16 v[4:7], v[154:157], v[218:221], v[4:7]
	v_mfma_f32_16x16x32_f16 v[0:3], v[162:165], v[218:221], v[0:3]
	v_mfma_f32_16x16x32_f16 v[48:51], v[158:161], v[186:189], v[48:51]
	v_mfma_f32_16x16x32_f16 v[40:43], v[170:173], v[186:189], v[40:43]
	v_mfma_f32_16x16x32_f16 v[32:35], v[158:161], v[194:197], v[32:35]
	v_mfma_f32_16x16x32_f16 v[24:27], v[170:173], v[194:197], v[24:27]
	v_mfma_f32_16x16x32_f16 v[16:19], v[158:161], v[214:217], v[16:19]
	v_mfma_f32_16x16x32_f16 v[8:11], v[170:173], v[214:217], v[8:11]
	v_mfma_f32_16x16x32_f16 v[4:7], v[158:161], v[222:225], v[4:7]
	v_mfma_f32_16x16x32_f16 v[0:3], v[170:173], v[222:225], v[0:3]
	s_setprio 0
	s_barrier
	s_add_i32 s53, s53, 2
	s_add_u32 s36, s36, 0x100
	s_addc_u32 s37, s37, 0
	s_add_u32 s0, s0, 0x100
	s_addc_u32 s1, s1, 0
	s_cmp_gt_u32 s53, 13

.LBB0_781:
	s_ashr_i32 s25, s24, 31
	s_lshl_b64 s[26:27], s[24:25], 19
	s_add_u32 s26, s78, s26
	s_addc_u32 s27, s79, s27
	s_and_b64 s[28:29], s[8:9], exec
	s_cselect_b32 s25, s27, s11
	s_cselect_b32 vcc_lo, s26, s10
	s_ashr_i32 s23, s22, 31
	s_lshl_b64 s[28:29], s[22:23], 19
	s_add_u32 s28, s36, s28
	s_addc_u32 s29, s37, s29
	s_and_b64 s[30:31], s[8:9], exec
	s_cselect_b32 s23, s29, s1
	s_cselect_b32 vcc_hi, s28, s0
	s_add_u32 s86, s0, 0x100
	s_addc_u32 s87, s1, 0
	s_add_u32 s0, s10, 0x40080
	s_addc_u32 s1, s11, 0
	s_mov_b32 s53, -2
	s_waitcnt lgkmcnt(0)
	s_add_u32 s10, s0, 0xfffc0080
	s_addc_u32 s11, s1, -1
	s_add_i32 s14, 0, 0x10000
	s_cmp_eq_u32 s53, 12
	s_cselect_b32 s31, s25, s11
	s_cselect_b32 s30, vcc_lo, s10
	s_cselect_b32 s11, s23, s87
	s_cselect_b32 s10, vcc_hi, s86
	s_add_i32 s92, 0, 0x14000
	v_add_u32_e32 v132, s14, v211
	v_add_u32_e32 v156, s92, v211
	ds_read_b128 v[112:115], v132
	ds_read_b128 v[120:123], v132 offset:1024
	ds_read_b128 v[124:127], v132 offset:2048
	ds_read_b128 v[132:135], v132 offset:3072
	ds_read_b128 v[144:147], v156
	ds_read_b128 v[148:151], v156 offset:1024
	ds_read_b128 v[152:155], v156 offset:2048
	ds_read_b128 v[156:159], v156 offset:3072
	v_lshl_add_u64 v[244:245], s[0:1], 0, v[190:191]
	s_add_i32 m0, s43, 0xc000
	ds_read_b128 v[160:163], v227
	ds_read_b128 v[164:167], v227 offset:1024
	ds_read_b128 v[168:171], v227 offset:2048
	ds_read_b128 v[172:175], v227 offset:3072
	ds_read_b128 v[192:195], v227 offset:4096
	ds_read_b128 v[196:199], v227 offset:5120
	ds_read_b128 v[236:239], v227 offset:6144
	ds_read_b128 v[240:243], v227 offset:7168
	global_load_lds_dwordx4 v[244:245], off
	v_lshl_add_u64 v[244:245], s[0:1], 0, v[188:189]
	s_add_i32 m0, s43, 0xe000
	s_nop 0
	global_load_lds_dwordx4 v[244:245], off
	s_waitcnt vmcnt(8)
	s_waitcnt lgkmcnt(0)
	s_barrier
	s_setprio 1
	s_waitcnt lgkmcnt(0)
	v_mfma_f32_16x16x32_f16 v[140:143], v[112:115], v[160:163], 0
	v_mfma_f32_16x16x32_f16 v[136:139], v[124:127], v[160:163], 0
	v_mfma_f32_16x16x32_f16 v[108:111], v[112:115], v[168:171], 0
	v_mfma_f32_16x16x32_f16 v[104:107], v[124:127], v[168:171], 0
	v_mfma_f32_16x16x32_f16 v[92:95], v[112:115], v[192:195], 0
	v_mfma_f32_16x16x32_f16 v[88:91], v[124:127], v[192:195], 0
	v_mfma_f32_16x16x32_f16 v[76:79], v[112:115], v[236:239], 0
	v_mfma_f32_16x16x32_f16 v[72:75], v[124:127], v[236:239], 0
	v_mfma_f32_16x16x32_f16 v[140:143], v[120:123], v[164:167], v[140:143]
	v_mfma_f32_16x16x32_f16 v[136:139], v[132:135], v[164:167], v[136:139]
	v_mfma_f32_16x16x32_f16 v[108:111], v[120:123], v[172:175], v[108:111]
	v_mfma_f32_16x16x32_f16 v[104:107], v[132:135], v[172:175], v[104:107]
	v_mfma_f32_16x16x32_f16 v[92:95], v[120:123], v[196:199], v[92:95]
	v_mfma_f32_16x16x32_f16 v[88:91], v[132:135], v[196:199], v[88:91]
	v_mfma_f32_16x16x32_f16 v[76:79], v[120:123], v[240:243], v[76:79]
	v_mfma_f32_16x16x32_f16 v[72:75], v[132:135], v[240:243], v[72:75]
	s_setprio 0
	s_setprio 1
	v_mfma_f32_16x16x32_f16 v[128:131], v[144:147], v[160:163], 0
	v_mfma_f32_16x16x32_f16 v[116:119], v[152:155], v[160:163], 0
	v_mfma_f32_16x16x32_f16 v[100:103], v[144:147], v[168:171], 0
	v_mfma_f32_16x16x32_f16 v[96:99], v[152:155], v[168:171], 0
	v_mfma_f32_16x16x32_f16 v[84:87], v[144:147], v[192:195], 0
	v_mfma_f32_16x16x32_f16 v[80:83], v[152:155], v[192:195], 0
	v_mfma_f32_16x16x32_f16 v[68:71], v[144:147], v[236:239], 0
	v_mfma_f32_16x16x32_f16 v[64:67], v[152:155], v[236:239], 0
	v_mfma_f32_16x16x32_f16 v[128:131], v[148:151], v[164:167], v[128:131]
	v_mfma_f32_16x16x32_f16 v[116:119], v[156:159], v[164:167], v[116:119]
	v_mfma_f32_16x16x32_f16 v[100:103], v[148:151], v[172:175], v[100:103]
	v_mfma_f32_16x16x32_f16 v[96:99], v[156:159], v[172:175], v[96:99]
	v_mfma_f32_16x16x32_f16 v[84:87], v[148:151], v[196:199], v[84:87]
	v_mfma_f32_16x16x32_f16 v[80:83], v[156:159], v[196:199], v[80:83]
	v_mfma_f32_16x16x32_f16 v[68:71], v[148:151], v[240:243], v[68:71]
	v_mfma_f32_16x16x32_f16 v[64:67], v[156:159], v[240:243], v[64:67]
	s_setprio 0
	s_barrier
	s_add_i32 s14, s14, s42
	v_lshl_add_u64 v[244:245], s[10:11], 0, v[176:177]
	s_mov_b32 m0, s14
	ds_read_b128 v[160:163], v227 offset:16384
	ds_read_b128 v[164:167], v227 offset:17408
	ds_read_b128 v[168:171], v227 offset:18432
	ds_read_b128 v[172:175], v227 offset:19456
	ds_read_b128 v[192:195], v227 offset:20480
	ds_read_b128 v[196:199], v227 offset:21504
	ds_read_b128 v[236:239], v227 offset:22528
	ds_read_b128 v[240:243], v227 offset:23552
	global_load_lds_dwordx4 v[244:245], off
	s_add_i32 m0, s14, 0x2000
	s_add_u32 s14, s10, 0x40000
	v_lshl_add_u64 v[246:247], s[10:11], 0, v[182:183]
	s_addc_u32 s15, s11, 0
	s_add_i32 s92, s92, s42
	global_load_lds_dwordx4 v[246:247], off
	v_lshl_add_u64 v[248:249], s[14:15], 0, v[176:177]
	s_mov_b32 m0, s92
	v_lshl_add_u64 v[250:251], s[30:31], 0, v[184:185]
	global_load_lds_dwordx4 v[248:249], off
	v_lshl_add_u64 v[248:249], s[14:15], 0, v[182:183]
	s_add_i32 m0, s92, 0x2000
	s_nop 0
	global_load_lds_dwordx4 v[248:249], off
	v_lshl_add_u64 v[248:249], s[30:31], 0, v[186:187]
	s_mov_b32 m0, s43
	s_nop 0
	global_load_lds_dwordx4 v[248:249], off
	s_mov_b32 m0, s54
	s_nop 0
	global_load_lds_dwordx4 v[250:251], off
	s_waitcnt vmcnt(8)
	s_waitcnt lgkmcnt(0)
	s_barrier
	s_setprio 1
	s_waitcnt lgkmcnt(0)
	v_mfma_f32_16x16x32_f16 v[60:63], v[112:115], v[160:163], 0
	v_mfma_f32_16x16x32_f16 v[56:59], v[124:127], v[160:163], 0
	v_mfma_f32_16x16x32_f16 v[44:47], v[112:115], v[168:171], 0
	v_mfma_f32_16x16x32_f16 v[40:43], v[124:127], v[168:171], 0
	v_mfma_f32_16x16x32_f16 v[28:31], v[112:115], v[192:195], 0
	v_mfma_f32_16x16x32_f16 v[24:27], v[124:127], v[192:195], 0
	v_mfma_f32_16x16x32_f16 v[12:15], v[112:115], v[236:239], 0
	v_mfma_f32_16x16x32_f16 v[8:11], v[124:127], v[236:239], 0
	v_mfma_f32_16x16x32_f16 v[60:63], v[120:123], v[164:167], v[60:63]
	v_mfma_f32_16x16x32_f16 v[56:59], v[132:135], v[164:167], v[56:59]
	v_mfma_f32_16x16x32_f16 v[44:47], v[120:123], v[172:175], v[44:47]
	v_mfma_f32_16x16x32_f16 v[40:43], v[132:135], v[172:175], v[40:43]
	v_mfma_f32_16x16x32_f16 v[28:31], v[120:123], v[196:199], v[28:31]
	v_mfma_f32_16x16x32_f16 v[24:27], v[132:135], v[196:199], v[24:27]
	v_mfma_f32_16x16x32_f16 v[12:15], v[120:123], v[240:243], v[12:15]
	v_mfma_f32_16x16x32_f16 v[8:11], v[132:135], v[240:243], v[8:11]
	s_setprio 0
	s_setprio 1
	v_mfma_f32_16x16x32_f16 v[52:55], v[144:147], v[160:163], 0
	v_mfma_f32_16x16x32_f16 v[48:51], v[152:155], v[160:163], 0
	v_mfma_f32_16x16x32_f16 v[36:39], v[144:147], v[168:171], 0
	v_mfma_f32_16x16x32_f16 v[32:35], v[152:155], v[168:171], 0
	v_mfma_f32_16x16x32_f16 v[20:23], v[144:147], v[192:195], 0
	v_mfma_f32_16x16x32_f16 v[16:19], v[152:155], v[192:195], 0
	v_mfma_f32_16x16x32_f16 v[4:7], v[144:147], v[236:239], 0
	v_mfma_f32_16x16x32_f16 v[0:3], v[152:155], v[236:239], 0
	v_mfma_f32_16x16x32_f16 v[52:55], v[148:151], v[164:167], v[52:55]
	v_mfma_f32_16x16x32_f16 v[48:51], v[156:159], v[164:167], v[48:51]
	v_mfma_f32_16x16x32_f16 v[36:39], v[148:151], v[172:175], v[36:39]
	v_mfma_f32_16x16x32_f16 v[32:35], v[156:159], v[172:175], v[32:35]
	v_mfma_f32_16x16x32_f16 v[20:23], v[148:151], v[196:199], v[20:23]
	v_mfma_f32_16x16x32_f16 v[16:19], v[156:159], v[196:199], v[16:19]
	v_mfma_f32_16x16x32_f16 v[4:7], v[148:151], v[240:243], v[4:7]
	v_mfma_f32_16x16x32_f16 v[0:3], v[156:159], v[240:243], v[0:3]
	s_setprio 0
	s_barrier
	s_add_i32 s92, 0, 0x18000
	s_add_i32 s93, 0, 0x1c000
	v_add_u32_e32 v132, s92, v211
	v_add_u32_e32 v156, s93, v211
	ds_read_b128 v[112:115], v132
	ds_read_b128 v[120:123], v132 offset:1024
	ds_read_b128 v[124:127], v132 offset:2048
	ds_read_b128 v[132:135], v132 offset:3072
	ds_read_b128 v[144:147], v156
	ds_read_b128 v[148:151], v156 offset:1024
	ds_read_b128 v[152:155], v156 offset:2048
	ds_read_b128 v[156:159], v156 offset:3072
	s_add_u32 s14, s30, 0x40000
	s_addc_u32 s15, s31, 0
	s_mov_b32 m0, s55
	v_lshl_add_u64 v[252:253], s[14:15], 0, v[186:187]
	ds_read_b128 v[160:163], v227 offset:32768
	ds_read_b128 v[164:167], v227 offset:33792
	ds_read_b128 v[168:171], v227 offset:34816
	ds_read_b128 v[172:175], v227 offset:35840
	ds_read_b128 v[192:195], v227 offset:36864
	ds_read_b128 v[196:199], v227 offset:37888
	ds_read_b128 v[236:239], v227 offset:38912
	ds_read_b128 v[240:243], v227 offset:39936
	global_load_lds_dwordx4 v[252:253], off
	v_lshl_add_u64 v[252:253], s[14:15], 0, v[184:185]
	s_mov_b32 m0, s56
	s_nop 0
	global_load_lds_dwordx4 v[252:253], off
	s_waitcnt vmcnt(8)
	s_waitcnt lgkmcnt(0)
	s_barrier
	s_setprio 1
	s_waitcnt lgkmcnt(0)
	v_mfma_f32_16x16x32_f16 v[140:143], v[112:115], v[160:163], v[140:143]
	v_mfma_f32_16x16x32_f16 v[136:139], v[124:127], v[160:163], v[136:139]
	v_mfma_f32_16x16x32_f16 v[108:111], v[112:115], v[168:171], v[108:111]
	v_mfma_f32_16x16x32_f16 v[104:107], v[124:127], v[168:171], v[104:107]
	v_mfma_f32_16x16x32_f16 v[92:95], v[112:115], v[192:195], v[92:95]
	v_mfma_f32_16x16x32_f16 v[88:91], v[124:127], v[192:195], v[88:91]
	v_mfma_f32_16x16x32_f16 v[76:79], v[112:115], v[236:239], v[76:79]
	v_mfma_f32_16x16x32_f16 v[72:75], v[124:127], v[236:239], v[72:75]
	v_mfma_f32_16x16x32_f16 v[140:143], v[120:123], v[164:167], v[140:143]
	v_mfma_f32_16x16x32_f16 v[136:139], v[132:135], v[164:167], v[136:139]
	v_mfma_f32_16x16x32_f16 v[108:111], v[120:123], v[172:175], v[108:111]
	v_mfma_f32_16x16x32_f16 v[104:107], v[132:135], v[172:175], v[104:107]
	v_mfma_f32_16x16x32_f16 v[92:95], v[120:123], v[196:199], v[92:95]
	v_mfma_f32_16x16x32_f16 v[88:91], v[132:135], v[196:199], v[88:91]
	v_mfma_f32_16x16x32_f16 v[76:79], v[120:123], v[240:243], v[76:79]
	v_mfma_f32_16x16x32_f16 v[72:75], v[132:135], v[240:243], v[72:75]
	s_setprio 0
	s_setprio 1
	v_mfma_f32_16x16x32_f16 v[128:131], v[144:147], v[160:163], v[128:131]
	v_mfma_f32_16x16x32_f16 v[116:119], v[152:155], v[160:163], v[116:119]
	v_mfma_f32_16x16x32_f16 v[100:103], v[144:147], v[168:171], v[100:103]
	v_mfma_f32_16x16x32_f16 v[96:99], v[152:155], v[168:171], v[96:99]
	v_mfma_f32_16x16x32_f16 v[84:87], v[144:147], v[192:195], v[84:87]
	v_mfma_f32_16x16x32_f16 v[80:83], v[152:155], v[192:195], v[80:83]
	v_mfma_f32_16x16x32_f16 v[68:71], v[144:147], v[236:239], v[68:71]
	v_mfma_f32_16x16x32_f16 v[64:67], v[152:155], v[236:239], v[64:67]
	v_mfma_f32_16x16x32_f16 v[128:131], v[148:151], v[164:167], v[128:131]
	v_mfma_f32_16x16x32_f16 v[116:119], v[156:159], v[164:167], v[116:119]
	v_mfma_f32_16x16x32_f16 v[100:103], v[148:151], v[172:175], v[100:103]
	v_mfma_f32_16x16x32_f16 v[96:99], v[156:159], v[172:175], v[96:99]
	v_mfma_f32_16x16x32_f16 v[84:87], v[148:151], v[196:199], v[84:87]
	v_mfma_f32_16x16x32_f16 v[80:83], v[156:159], v[196:199], v[80:83]
	v_mfma_f32_16x16x32_f16 v[68:71], v[148:151], v[240:243], v[68:71]
	v_mfma_f32_16x16x32_f16 v[64:67], v[156:159], v[240:243], v[64:67]
	s_setprio 0
	s_barrier
	s_add_i32 s14, s92, s42
	v_lshl_add_u64 v[244:245], v[244:245], 0, s[72:73]
	s_mov_b32 m0, s14
	ds_read_b128 v[160:163], v227 offset:49152
	ds_read_b128 v[164:167], v227 offset:50176
	ds_read_b128 v[168:171], v227 offset:51200
	ds_read_b128 v[172:175], v227 offset:52224
	ds_read_b128 v[192:195], v227 offset:53248
	ds_read_b128 v[196:199], v227 offset:54272
	ds_read_b128 v[236:239], v227 offset:55296
	ds_read_b128 v[240:243], v227 offset:56320
	global_load_lds_dwordx4 v[244:245], off
	s_add_i32 m0, s14, 0x2000
	s_add_u32 s10, s10, 0x40080
	v_lshl_add_u64 v[244:245], v[246:247], 0, s[72:73]
	s_addc_u32 s11, s11, 0
	s_add_i32 s14, s93, s42
	global_load_lds_dwordx4 v[244:245], off
	v_lshl_add_u64 v[244:245], s[10:11], 0, v[176:177]
	s_mov_b32 m0, s14
	s_nop 0
	global_load_lds_dwordx4 v[244:245], off
	v_lshl_add_u64 v[244:245], s[10:11], 0, v[182:183]
	s_add_i32 m0, s14, 0x2000
	s_nop 0
	global_load_lds_dwordx4 v[244:245], off
	v_lshl_add_u64 v[244:245], v[248:249], 0, s[72:73]
	s_mov_b32 m0, s57
	s_nop 0
	global_load_lds_dwordx4 v[244:245], off
	v_lshl_add_u64 v[244:245], v[250:251], 0, s[72:73]
	s_mov_b32 m0, s70
	s_nop 0
	global_load_lds_dwordx4 v[244:245], off
	s_waitcnt vmcnt(8)
	s_waitcnt lgkmcnt(0)
	s_barrier
	s_setprio 1
	s_waitcnt lgkmcnt(0)
	v_mfma_f32_16x16x32_f16 v[60:63], v[112:115], v[160:163], v[60:63]
	v_mfma_f32_16x16x32_f16 v[56:59], v[124:127], v[160:163], v[56:59]
	v_mfma_f32_16x16x32_f16 v[44:47], v[112:115], v[168:171], v[44:47]
	v_mfma_f32_16x16x32_f16 v[40:43], v[124:127], v[168:171], v[40:43]
	v_mfma_f32_16x16x32_f16 v[28:31], v[112:115], v[192:195], v[28:31]
	v_mfma_f32_16x16x32_f16 v[24:27], v[124:127], v[192:195], v[24:27]
	v_mfma_f32_16x16x32_f16 v[12:15], v[112:115], v[236:239], v[12:15]
	v_mfma_f32_16x16x32_f16 v[8:11], v[124:127], v[236:239], v[8:11]
	v_mfma_f32_16x16x32_f16 v[60:63], v[120:123], v[164:167], v[60:63]
	v_mfma_f32_16x16x32_f16 v[56:59], v[132:135], v[164:167], v[56:59]
	v_mfma_f32_16x16x32_f16 v[44:47], v[120:123], v[172:175], v[44:47]
	v_mfma_f32_16x16x32_f16 v[40:43], v[132:135], v[172:175], v[40:43]
	v_mfma_f32_16x16x32_f16 v[28:31], v[120:123], v[196:199], v[28:31]
	v_mfma_f32_16x16x32_f16 v[24:27], v[132:135], v[196:199], v[24:27]
	v_mfma_f32_16x16x32_f16 v[12:15], v[120:123], v[240:243], v[12:15]
	v_mfma_f32_16x16x32_f16 v[8:11], v[132:135], v[240:243], v[8:11]
	s_setprio 0
	s_setprio 1
	v_mfma_f32_16x16x32_f16 v[52:55], v[144:147], v[160:163], v[52:55]
	v_mfma_f32_16x16x32_f16 v[48:51], v[152:155], v[160:163], v[48:51]
	v_mfma_f32_16x16x32_f16 v[36:39], v[144:147], v[168:171], v[36:39]
	v_mfma_f32_16x16x32_f16 v[32:35], v[152:155], v[168:171], v[32:35]
	v_mfma_f32_16x16x32_f16 v[20:23], v[144:147], v[192:195], v[20:23]
	v_mfma_f32_16x16x32_f16 v[16:19], v[152:155], v[192:195], v[16:19]
	v_mfma_f32_16x16x32_f16 v[4:7], v[144:147], v[236:239], v[4:7]
	v_mfma_f32_16x16x32_f16 v[0:3], v[152:155], v[236:239], v[0:3]
	v_mfma_f32_16x16x32_f16 v[52:55], v[148:151], v[164:167], v[52:55]
	v_mfma_f32_16x16x32_f16 v[48:51], v[156:159], v[164:167], v[48:51]
	v_mfma_f32_16x16x32_f16 v[36:39], v[148:151], v[172:175], v[36:39]
	v_mfma_f32_16x16x32_f16 v[32:35], v[156:159], v[172:175], v[32:35]
	v_mfma_f32_16x16x32_f16 v[20:23], v[148:151], v[196:199], v[20:23]
	v_mfma_f32_16x16x32_f16 v[16:19], v[156:159], v[196:199], v[16:19]
	v_mfma_f32_16x16x32_f16 v[4:7], v[148:151], v[240:243], v[4:7]
	v_mfma_f32_16x16x32_f16 v[0:3], v[156:159], v[240:243], v[0:3]
	s_setprio 0
	s_barrier
	s_add_i32 s53, s53, 2
	s_add_u32 s86, s86, 0x100
	s_addc_u32 s87, s87, 0
	s_add_u32 s0, s0, 0x100
	s_addc_u32 s1, s1, 0
	s_cmp_gt_u32 s53, 13

.LBB0_881:
	s_ashr_i32 s9, s8, 31
	s_lshl_b64 s[10:11], s[8:9], 19
	s_add_u32 s10, s48, s10
	s_addc_u32 s11, s49, s11
	s_and_b64 s[14:15], s[2:3], exec
	s_cselect_b32 s9, s11, s19
	s_cselect_b32 s38, s10, s18
	s_ashr_i32 s7, s6, 31
	s_lshl_b64 s[14:15], s[6:7], 19
	s_add_u32 s14, s22, s14
	s_addc_u32 s15, s23, s15
	s_and_b64 s[20:21], s[2:3], exec
	s_cselect_b32 s7, s15, s17
	s_cselect_b32 s39, s14, s16
	s_add_u32 s42, s16, 0x100
	s_addc_u32 s43, s17, 0
	s_add_u32 s16, s18, 0x40080
	s_addc_u32 s17, s19, 0
	s_mov_b32 s54, -2
	s_add_u32 s18, s16, 0xfffc0080
	s_addc_u32 s19, s17, -1
	s_add_i32 s53, 0, 0x10000
	s_cmp_eq_u32 s54, 12
	s_cselect_b32 s21, s9, s19
	s_cselect_b32 s20, s38, s18
	s_cselect_b32 s19, s7, s43
	s_cselect_b32 s18, s39, s42
	s_add_i32 s55, 0, 0x14000
	v_add_u32_e32 v128, s53, v191
	v_add_u32_e32 v156, s55, v191
	ds_read_b128 v[96:99], v128
	ds_read_b128 v[108:111], v128 offset:1024
	ds_read_b128 v[120:123], v128 offset:2048
	ds_read_b128 v[128:131], v128 offset:3072
	ds_read_b128 v[132:135], v156
	ds_read_b128 v[140:143], v156 offset:1024
	ds_read_b128 v[152:155], v156 offset:2048
	ds_read_b128 v[156:159], v156 offset:3072
	v_lshl_add_u64 v[174:175], s[16:17], 0, v[172:173]
	s_add_i32 m0, s25, 0xc000
	ds_read_b128 v[182:185], v192
	ds_read_b128 v[186:189], v192 offset:1024
	ds_read_b128 v[194:197], v192 offset:2048
	ds_read_b128 v[210:213], v192 offset:3072
	ds_read_b128 v[214:217], v192 offset:4096
	ds_read_b128 v[218:221], v192 offset:5120
	ds_read_b128 v[222:225], v192 offset:6144
	ds_read_b128 v[226:229], v192 offset:7168
	global_load_lds_dwordx4 v[174:175], off
	v_lshl_add_u64 v[174:175], s[16:17], 0, v[170:171]
	s_add_i32 m0, s25, 0xe000
	s_nop 0
	global_load_lds_dwordx4 v[174:175], off
	s_waitcnt vmcnt(8)
	s_waitcnt lgkmcnt(0)
	s_barrier
	s_setprio 1
	s_waitcnt lgkmcnt(0)
	v_mfma_f32_16x16x32_f16 v[148:151], v[96:99], v[182:185], 0
	v_mfma_f32_16x16x32_f16 v[144:147], v[120:123], v[182:185], 0
	v_mfma_f32_16x16x32_f16 v[116:119], v[96:99], v[194:197], 0
	v_mfma_f32_16x16x32_f16 v[112:115], v[120:123], v[194:197], 0
	v_mfma_f32_16x16x32_f16 v[92:95], v[96:99], v[214:217], 0
	v_mfma_f32_16x16x32_f16 v[88:91], v[120:123], v[214:217], 0
	v_mfma_f32_16x16x32_f16 v[76:79], v[96:99], v[222:225], 0
	v_mfma_f32_16x16x32_f16 v[72:75], v[120:123], v[222:225], 0
	v_mfma_f32_16x16x32_f16 v[148:151], v[108:111], v[186:189], v[148:151]
	v_mfma_f32_16x16x32_f16 v[144:147], v[128:131], v[186:189], v[144:147]
	v_mfma_f32_16x16x32_f16 v[116:119], v[108:111], v[210:213], v[116:119]
	v_mfma_f32_16x16x32_f16 v[112:115], v[128:131], v[210:213], v[112:115]
	v_mfma_f32_16x16x32_f16 v[92:95], v[108:111], v[218:221], v[92:95]
	v_mfma_f32_16x16x32_f16 v[88:91], v[128:131], v[218:221], v[88:91]
	v_mfma_f32_16x16x32_f16 v[76:79], v[108:111], v[226:229], v[76:79]
	v_mfma_f32_16x16x32_f16 v[72:75], v[128:131], v[226:229], v[72:75]
	s_setprio 0
	s_setprio 1
	v_mfma_f32_16x16x32_f16 v[136:139], v[132:135], v[182:185], 0
	v_mfma_f32_16x16x32_f16 v[124:127], v[152:155], v[182:185], 0
	v_mfma_f32_16x16x32_f16 v[104:107], v[132:135], v[194:197], 0
	v_mfma_f32_16x16x32_f16 v[100:103], v[152:155], v[194:197], 0
	v_mfma_f32_16x16x32_f16 v[84:87], v[132:135], v[214:217], 0
	v_mfma_f32_16x16x32_f16 v[80:83], v[152:155], v[214:217], 0
	v_mfma_f32_16x16x32_f16 v[68:71], v[132:135], v[222:225], 0
	v_mfma_f32_16x16x32_f16 v[64:67], v[152:155], v[222:225], 0
	v_mfma_f32_16x16x32_f16 v[136:139], v[140:143], v[186:189], v[136:139]
	v_mfma_f32_16x16x32_f16 v[124:127], v[156:159], v[186:189], v[124:127]
	v_mfma_f32_16x16x32_f16 v[104:107], v[140:143], v[210:213], v[104:107]
	v_mfma_f32_16x16x32_f16 v[100:103], v[156:159], v[210:213], v[100:103]
	v_mfma_f32_16x16x32_f16 v[84:87], v[140:143], v[218:221], v[84:87]
	v_mfma_f32_16x16x32_f16 v[80:83], v[156:159], v[218:221], v[80:83]
	v_mfma_f32_16x16x32_f16 v[68:71], v[140:143], v[226:229], v[68:71]
	v_mfma_f32_16x16x32_f16 v[64:67], v[156:159], v[226:229], v[64:67]
	s_setprio 0
	s_barrier
	s_add_i32 s53, s53, s24
	v_lshl_add_u64 v[174:175], s[18:19], 0, v[164:165]
	s_mov_b32 m0, s53
	ds_read_b128 v[182:185], v192 offset:16384
	ds_read_b128 v[186:189], v192 offset:17408
	ds_read_b128 v[194:197], v192 offset:18432
	ds_read_b128 v[210:213], v192 offset:19456
	ds_read_b128 v[214:217], v192 offset:20480
	ds_read_b128 v[218:221], v192 offset:21504
	ds_read_b128 v[222:225], v192 offset:22528
	ds_read_b128 v[226:229], v192 offset:23552
	global_load_lds_dwordx4 v[174:175], off
	s_add_i32 m0, s53, 0x2000
	s_add_u32 s56, s18, 0x40000
	v_lshl_add_u64 v[198:199], s[18:19], 0, v[160:161]
	s_addc_u32 s57, s19, 0
	s_add_i32 s53, s55, s24
	global_load_lds_dwordx4 v[198:199], off
	v_lshl_add_u64 v[230:231], s[56:57], 0, v[164:165]
	s_mov_b32 m0, s53
	v_lshl_add_u64 v[232:233], s[20:21], 0, v[162:163]
	global_load_lds_dwordx4 v[230:231], off
	v_lshl_add_u64 v[230:231], s[56:57], 0, v[160:161]
	s_add_i32 m0, s53, 0x2000
	s_nop 0
	global_load_lds_dwordx4 v[230:231], off
	v_lshl_add_u64 v[230:231], s[20:21], 0, v[166:167]
	s_mov_b32 m0, s25
	s_nop 0
	global_load_lds_dwordx4 v[230:231], off
	s_mov_b32 m0, s26
	s_nop 0
	global_load_lds_dwordx4 v[232:233], off
	s_waitcnt vmcnt(8)
	s_waitcnt lgkmcnt(0)
	s_barrier
	s_setprio 1
	s_waitcnt lgkmcnt(0)
	v_mfma_f32_16x16x32_f16 v[60:63], v[96:99], v[182:185], 0
	v_mfma_f32_16x16x32_f16 v[56:59], v[120:123], v[182:185], 0
	v_mfma_f32_16x16x32_f16 v[44:47], v[96:99], v[194:197], 0
	v_mfma_f32_16x16x32_f16 v[40:43], v[120:123], v[194:197], 0
	v_mfma_f32_16x16x32_f16 v[28:31], v[96:99], v[214:217], 0
	v_mfma_f32_16x16x32_f16 v[24:27], v[120:123], v[214:217], 0
	v_mfma_f32_16x16x32_f16 v[12:15], v[96:99], v[222:225], 0
	v_mfma_f32_16x16x32_f16 v[8:11], v[120:123], v[222:225], 0
	v_mfma_f32_16x16x32_f16 v[60:63], v[108:111], v[186:189], v[60:63]
	v_mfma_f32_16x16x32_f16 v[56:59], v[128:131], v[186:189], v[56:59]
	v_mfma_f32_16x16x32_f16 v[44:47], v[108:111], v[210:213], v[44:47]
	v_mfma_f32_16x16x32_f16 v[40:43], v[128:131], v[210:213], v[40:43]
	v_mfma_f32_16x16x32_f16 v[28:31], v[108:111], v[218:221], v[28:31]
	v_mfma_f32_16x16x32_f16 v[24:27], v[128:131], v[218:221], v[24:27]
	v_mfma_f32_16x16x32_f16 v[12:15], v[108:111], v[226:229], v[12:15]
	v_mfma_f32_16x16x32_f16 v[8:11], v[128:131], v[226:229], v[8:11]
	s_setprio 0
	s_setprio 1
	v_mfma_f32_16x16x32_f16 v[52:55], v[132:135], v[182:185], 0
	v_mfma_f32_16x16x32_f16 v[48:51], v[152:155], v[182:185], 0
	v_mfma_f32_16x16x32_f16 v[36:39], v[132:135], v[194:197], 0
	v_mfma_f32_16x16x32_f16 v[32:35], v[152:155], v[194:197], 0
	v_mfma_f32_16x16x32_f16 v[20:23], v[132:135], v[214:217], 0
	v_mfma_f32_16x16x32_f16 v[16:19], v[152:155], v[214:217], 0
	v_mfma_f32_16x16x32_f16 v[4:7], v[132:135], v[222:225], 0
	v_mfma_f32_16x16x32_f16 v[0:3], v[152:155], v[222:225], 0
	v_mfma_f32_16x16x32_f16 v[52:55], v[140:143], v[186:189], v[52:55]
	v_mfma_f32_16x16x32_f16 v[48:51], v[156:159], v[186:189], v[48:51]
	v_mfma_f32_16x16x32_f16 v[36:39], v[140:143], v[210:213], v[36:39]
	v_mfma_f32_16x16x32_f16 v[32:35], v[156:159], v[210:213], v[32:35]
	v_mfma_f32_16x16x32_f16 v[20:23], v[140:143], v[218:221], v[20:23]
	v_mfma_f32_16x16x32_f16 v[16:19], v[156:159], v[218:221], v[16:19]
	v_mfma_f32_16x16x32_f16 v[4:7], v[140:143], v[226:229], v[4:7]
	v_mfma_f32_16x16x32_f16 v[0:3], v[156:159], v[226:229], v[0:3]
	s_setprio 0
	s_barrier
	s_add_i32 s53, 0, 0x18000
	s_add_i32 s55, 0, 0x1c000
	v_add_u32_e32 v128, s53, v191
	v_add_u32_e32 v156, s55, v191
	ds_read_b128 v[96:99], v128
	ds_read_b128 v[108:111], v128 offset:1024
	ds_read_b128 v[120:123], v128 offset:2048
	ds_read_b128 v[128:131], v128 offset:3072
	ds_read_b128 v[132:135], v156
	ds_read_b128 v[140:143], v156 offset:1024
	ds_read_b128 v[152:155], v156 offset:2048
	ds_read_b128 v[156:159], v156 offset:3072
	s_add_u32 s20, s20, 0x40000
	s_addc_u32 s21, s21, 0
	s_mov_b32 m0, s27
	v_lshl_add_u64 v[234:235], s[20:21], 0, v[166:167]
	ds_read_b128 v[182:185], v192 offset:32768
	ds_read_b128 v[186:189], v192 offset:33792
	ds_read_b128 v[194:197], v192 offset:34816
	ds_read_b128 v[210:213], v192 offset:35840
	ds_read_b128 v[214:217], v192 offset:36864
	ds_read_b128 v[218:221], v192 offset:37888
	ds_read_b128 v[222:225], v192 offset:38912
	ds_read_b128 v[226:229], v192 offset:39936
	global_load_lds_dwordx4 v[234:235], off
	v_lshl_add_u64 v[234:235], s[20:21], 0, v[162:163]
	s_mov_b32 m0, s28
	s_nop 0
	global_load_lds_dwordx4 v[234:235], off
	s_waitcnt vmcnt(8)
	s_waitcnt lgkmcnt(0)
	s_barrier
	s_setprio 1
	s_waitcnt lgkmcnt(0)
	v_mfma_f32_16x16x32_f16 v[148:151], v[96:99], v[182:185], v[148:151]
	v_mfma_f32_16x16x32_f16 v[144:147], v[120:123], v[182:185], v[144:147]
	v_mfma_f32_16x16x32_f16 v[116:119], v[96:99], v[194:197], v[116:119]
	v_mfma_f32_16x16x32_f16 v[112:115], v[120:123], v[194:197], v[112:115]
	v_mfma_f32_16x16x32_f16 v[92:95], v[96:99], v[214:217], v[92:95]
	v_mfma_f32_16x16x32_f16 v[88:91], v[120:123], v[214:217], v[88:91]
	v_mfma_f32_16x16x32_f16 v[76:79], v[96:99], v[222:225], v[76:79]
	v_mfma_f32_16x16x32_f16 v[72:75], v[120:123], v[222:225], v[72:75]
	v_mfma_f32_16x16x32_f16 v[148:151], v[108:111], v[186:189], v[148:151]
	v_mfma_f32_16x16x32_f16 v[144:147], v[128:131], v[186:189], v[144:147]
	v_mfma_f32_16x16x32_f16 v[116:119], v[108:111], v[210:213], v[116:119]
	v_mfma_f32_16x16x32_f16 v[112:115], v[128:131], v[210:213], v[112:115]
	v_mfma_f32_16x16x32_f16 v[92:95], v[108:111], v[218:221], v[92:95]
	v_mfma_f32_16x16x32_f16 v[88:91], v[128:131], v[218:221], v[88:91]
	v_mfma_f32_16x16x32_f16 v[76:79], v[108:111], v[226:229], v[76:79]
	v_mfma_f32_16x16x32_f16 v[72:75], v[128:131], v[226:229], v[72:75]
	s_setprio 0
	s_setprio 1
	v_mfma_f32_16x16x32_f16 v[136:139], v[132:135], v[182:185], v[136:139]
	v_mfma_f32_16x16x32_f16 v[124:127], v[152:155], v[182:185], v[124:127]
	v_mfma_f32_16x16x32_f16 v[104:107], v[132:135], v[194:197], v[104:107]
	v_mfma_f32_16x16x32_f16 v[100:103], v[152:155], v[194:197], v[100:103]
	v_mfma_f32_16x16x32_f16 v[84:87], v[132:135], v[214:217], v[84:87]
	v_mfma_f32_16x16x32_f16 v[80:83], v[152:155], v[214:217], v[80:83]
	v_mfma_f32_16x16x32_f16 v[68:71], v[132:135], v[222:225], v[68:71]
	v_mfma_f32_16x16x32_f16 v[64:67], v[152:155], v[222:225], v[64:67]
	v_mfma_f32_16x16x32_f16 v[136:139], v[140:143], v[186:189], v[136:139]
	v_mfma_f32_16x16x32_f16 v[124:127], v[156:159], v[186:189], v[124:127]
	v_mfma_f32_16x16x32_f16 v[104:107], v[140:143], v[210:213], v[104:107]
	v_mfma_f32_16x16x32_f16 v[100:103], v[156:159], v[210:213], v[100:103]
	v_mfma_f32_16x16x32_f16 v[84:87], v[140:143], v[218:221], v[84:87]
	v_mfma_f32_16x16x32_f16 v[80:83], v[156:159], v[218:221], v[80:83]
	v_mfma_f32_16x16x32_f16 v[68:71], v[140:143], v[226:229], v[68:71]
	v_mfma_f32_16x16x32_f16 v[64:67], v[156:159], v[226:229], v[64:67]
	s_setprio 0
	s_barrier
	s_add_i32 s20, s53, s24
	v_lshl_add_u64 v[174:175], v[174:175], 0, s[72:73]
	s_mov_b32 m0, s20
	ds_read_b128 v[182:185], v192 offset:49152
	ds_read_b128 v[186:189], v192 offset:50176
	ds_read_b128 v[194:197], v192 offset:51200
	ds_read_b128 v[210:213], v192 offset:52224
	ds_read_b128 v[214:217], v192 offset:53248
	ds_read_b128 v[218:221], v192 offset:54272
	ds_read_b128 v[222:225], v192 offset:55296
	ds_read_b128 v[226:229], v192 offset:56320
	global_load_lds_dwordx4 v[174:175], off
	s_add_i32 m0, s20, 0x2000
	s_add_u32 s18, s18, 0x40080
	v_lshl_add_u64 v[174:175], v[198:199], 0, s[72:73]
	s_addc_u32 s19, s19, 0
	s_add_i32 s20, s55, s24
	global_load_lds_dwordx4 v[174:175], off
	v_lshl_add_u64 v[174:175], s[18:19], 0, v[164:165]
	s_mov_b32 m0, s20
	s_nop 0
	global_load_lds_dwordx4 v[174:175], off
	v_lshl_add_u64 v[174:175], s[18:19], 0, v[160:161]
	s_add_i32 m0, s20, 0x2000
	s_nop 0
	global_load_lds_dwordx4 v[174:175], off
	v_lshl_add_u64 v[174:175], v[230:231], 0, s[72:73]
	s_mov_b32 m0, s29
	s_nop 0
	global_load_lds_dwordx4 v[174:175], off
	v_lshl_add_u64 v[174:175], v[232:233], 0, s[72:73]
	s_mov_b32 m0, s30
	s_nop 0
	global_load_lds_dwordx4 v[174:175], off
	s_waitcnt vmcnt(8)
	s_waitcnt lgkmcnt(0)
	s_barrier
	s_setprio 1
	s_waitcnt lgkmcnt(0)
	v_mfma_f32_16x16x32_f16 v[60:63], v[96:99], v[182:185], v[60:63]
	v_mfma_f32_16x16x32_f16 v[56:59], v[120:123], v[182:185], v[56:59]
	v_mfma_f32_16x16x32_f16 v[44:47], v[96:99], v[194:197], v[44:47]
	v_mfma_f32_16x16x32_f16 v[40:43], v[120:123], v[194:197], v[40:43]
	v_mfma_f32_16x16x32_f16 v[28:31], v[96:99], v[214:217], v[28:31]
	v_mfma_f32_16x16x32_f16 v[24:27], v[120:123], v[214:217], v[24:27]
	v_mfma_f32_16x16x32_f16 v[12:15], v[96:99], v[222:225], v[12:15]
	v_mfma_f32_16x16x32_f16 v[8:11], v[120:123], v[222:225], v[8:11]
	v_mfma_f32_16x16x32_f16 v[60:63], v[108:111], v[186:189], v[60:63]
	v_mfma_f32_16x16x32_f16 v[56:59], v[128:131], v[186:189], v[56:59]
	v_mfma_f32_16x16x32_f16 v[44:47], v[108:111], v[210:213], v[44:47]
	v_mfma_f32_16x16x32_f16 v[40:43], v[128:131], v[210:213], v[40:43]
	v_mfma_f32_16x16x32_f16 v[28:31], v[108:111], v[218:221], v[28:31]
	v_mfma_f32_16x16x32_f16 v[24:27], v[128:131], v[218:221], v[24:27]
	v_mfma_f32_16x16x32_f16 v[12:15], v[108:111], v[226:229], v[12:15]
	v_mfma_f32_16x16x32_f16 v[8:11], v[128:131], v[226:229], v[8:11]
	s_setprio 0
	s_setprio 1
	v_mfma_f32_16x16x32_f16 v[52:55], v[132:135], v[182:185], v[52:55]
	v_mfma_f32_16x16x32_f16 v[48:51], v[152:155], v[182:185], v[48:51]
	v_mfma_f32_16x16x32_f16 v[36:39], v[132:135], v[194:197], v[36:39]
	v_mfma_f32_16x16x32_f16 v[32:35], v[152:155], v[194:197], v[32:35]
	v_mfma_f32_16x16x32_f16 v[20:23], v[132:135], v[214:217], v[20:23]
	v_mfma_f32_16x16x32_f16 v[16:19], v[152:155], v[214:217], v[16:19]
	v_mfma_f32_16x16x32_f16 v[4:7], v[132:135], v[222:225], v[4:7]
	v_mfma_f32_16x16x32_f16 v[0:3], v[152:155], v[222:225], v[0:3]
	v_mfma_f32_16x16x32_f16 v[52:55], v[140:143], v[186:189], v[52:55]
	v_mfma_f32_16x16x32_f16 v[48:51], v[156:159], v[186:189], v[48:51]
	v_mfma_f32_16x16x32_f16 v[36:39], v[140:143], v[210:213], v[36:39]
	v_mfma_f32_16x16x32_f16 v[32:35], v[156:159], v[210:213], v[32:35]
	v_mfma_f32_16x16x32_f16 v[20:23], v[140:143], v[218:221], v[20:23]
	v_mfma_f32_16x16x32_f16 v[16:19], v[156:159], v[218:221], v[16:19]
	v_mfma_f32_16x16x32_f16 v[4:7], v[140:143], v[226:229], v[4:7]
	v_mfma_f32_16x16x32_f16 v[0:3], v[156:159], v[226:229], v[0:3]
	s_setprio 0
	s_barrier
	s_add_i32 s54, s54, 2
	s_add_u32 s42, s42, 0x100
	s_addc_u32 s43, s43, 0
	s_add_u32 s16, s16, 0x100
	s_addc_u32 s17, s17, 0
	s_cmp_gt_u32 s54, 13

.LBB0_903:
	v_mov_b32_e32 v135, 0
	s_cmp_lt_i32 s31, -1
	v_mov_b32_e32 v134, v135
	v_mov_b32_e32 v133, v135
	v_mov_b32_e32 v132, v135
	v_mov_b32_e32 v131, v135
	v_mov_b32_e32 v130, v135
	v_mov_b32_e32 v129, v135
	v_mov_b32_e32 v128, v135
	v_mov_b32_e32 v119, v135
	v_mov_b32_e32 v118, v135
	v_mov_b32_e32 v117, v135
	v_mov_b32_e32 v116, v135
	v_mov_b32_e32 v115, v135
	v_mov_b32_e32 v114, v135
	v_mov_b32_e32 v113, v135
	v_mov_b32_e32 v112, v135
	v_mov_b32_e32 v103, v135
	v_mov_b32_e32 v102, v135
	v_mov_b32_e32 v101, v135
	v_mov_b32_e32 v100, v135
	v_mov_b32_e32 v99, v135
	v_mov_b32_e32 v98, v135
	v_mov_b32_e32 v97, v135
	v_mov_b32_e32 v96, v135
	v_mov_b32_e32 v87, v135
	v_mov_b32_e32 v86, v135
	v_mov_b32_e32 v85, v135
	v_mov_b32_e32 v84, v135
	v_mov_b32_e32 v83, v135
	v_mov_b32_e32 v82, v135
	v_mov_b32_e32 v81, v135
	v_mov_b32_e32 v80, v135
	v_mov_b32_e32 v127, v135
	v_mov_b32_e32 v126, v135
	v_mov_b32_e32 v125, v135
	v_mov_b32_e32 v124, v135
	v_mov_b32_e32 v123, v135
	v_mov_b32_e32 v122, v135
	v_mov_b32_e32 v121, v135
	v_mov_b32_e32 v120, v135
	v_mov_b32_e32 v111, v135
	v_mov_b32_e32 v110, v135
	v_mov_b32_e32 v109, v135
	v_mov_b32_e32 v108, v135
	v_mov_b32_e32 v107, v135
	v_mov_b32_e32 v106, v135
	v_mov_b32_e32 v105, v135
	v_mov_b32_e32 v104, v135
	v_mov_b32_e32 v95, v135
	v_mov_b32_e32 v94, v135
	v_mov_b32_e32 v93, v135
	v_mov_b32_e32 v92, v135
	v_mov_b32_e32 v91, v135
	v_mov_b32_e32 v90, v135
	v_mov_b32_e32 v89, v135
	v_mov_b32_e32 v88, v135
	v_mov_b32_e32 v79, v135
	v_mov_b32_e32 v78, v135
	v_mov_b32_e32 v77, v135
	v_mov_b32_e32 v76, v135
	v_mov_b32_e32 v71, v135
	v_mov_b32_e32 v70, v135
	v_mov_b32_e32 v69, v135
	v_mov_b32_e32 v68, v135
	v_mov_b32_e32 v63, v135
	v_mov_b32_e32 v62, v135
	v_mov_b32_e32 v61, v135
	v_mov_b32_e32 v60, v135
	v_mov_b32_e32 v59, v135
	v_mov_b32_e32 v58, v135
	v_mov_b32_e32 v57, v135
	v_mov_b32_e32 v56, v135
	v_mov_b32_e32 v47, v135
	v_mov_b32_e32 v46, v135
	v_mov_b32_e32 v45, v135
	v_mov_b32_e32 v44, v135
	v_mov_b32_e32 v43, v135
	v_mov_b32_e32 v42, v135
	v_mov_b32_e32 v41, v135
	v_mov_b32_e32 v40, v135
	v_mov_b32_e32 v31, v135
	v_mov_b32_e32 v30, v135
	v_mov_b32_e32 v29, v135
	v_mov_b32_e32 v28, v135
	v_mov_b32_e32 v27, v135
	v_mov_b32_e32 v26, v135
	v_mov_b32_e32 v25, v135
	v_mov_b32_e32 v24, v135
	v_mov_b32_e32 v15, v135
	v_mov_b32_e32 v14, v135
	v_mov_b32_e32 v13, v135
	v_mov_b32_e32 v12, v135
	v_mov_b32_e32 v11, v135
	v_mov_b32_e32 v10, v135
	v_mov_b32_e32 v9, v135
	v_mov_b32_e32 v8, v135
	v_mov_b32_e32 v55, v135
	v_mov_b32_e32 v54, v135
	v_mov_b32_e32 v53, v135
	v_mov_b32_e32 v52, v135
	v_mov_b32_e32 v51, v135
	v_mov_b32_e32 v50, v135
	v_mov_b32_e32 v49, v135
	v_mov_b32_e32 v48, v135
	v_mov_b32_e32 v39, v135
	v_mov_b32_e32 v38, v135
	v_mov_b32_e32 v37, v135
	v_mov_b32_e32 v36, v135
	v_mov_b32_e32 v35, v135
	v_mov_b32_e32 v34, v135
	v_mov_b32_e32 v33, v135
	v_mov_b32_e32 v32, v135
	v_mov_b32_e32 v23, v135
	v_mov_b32_e32 v22, v135
	v_mov_b32_e32 v21, v135
	v_mov_b32_e32 v20, v135
	v_mov_b32_e32 v19, v135
	v_mov_b32_e32 v18, v135
	v_mov_b32_e32 v17, v135
	v_mov_b32_e32 v16, v135
	v_mov_b32_e32 v7, v135
	v_mov_b32_e32 v6, v135
	v_mov_b32_e32 v5, v135
	v_mov_b32_e32 v4, v135
	v_mov_b32_e32 v3, v135
	v_mov_b32_e32 v2, v135
	v_mov_b32_e32 v1, v135
	v_mov_b32_e32 v0, v135
	s_cbranch_scc1 .LBB0_906
	s_lshl_b32 s38, s31, 2
	s_add_i32 s39, s38, 4
	s_add_u32 s42, s14, 0x100
	s_addc_u32 s43, s15, 0
	s_mov_b32 s53, -4
	s_add_u32 s14, s10, 0x100
	s_addc_u32 s15, s11, 0
	s_add_i32 s54, 0, 0x10000
	s_cmp_eq_u32 s38, s53
	s_cselect_b32 s19, s1, s15
	s_cselect_b32 s18, s0, s14
	s_cselect_b32 s17, s9, s43
	s_cselect_b32 s16, s8, s42
	s_add_i32 s55, 0, 0x14000
	v_add_u32_e32 v140, s54, v198
	v_add_u32_e32 v156, s55, v198
	ds_read_b128 v[64:67], v140
	ds_read_b128 v[72:75], v140 offset:1024
	ds_read_b128 v[136:139], v140 offset:2048
	ds_read_b128 v[140:143], v140 offset:3072
	ds_read_b128 v[144:147], v156
	ds_read_b128 v[148:151], v156 offset:1024
	ds_read_b128 v[152:155], v156 offset:2048
	ds_read_b128 v[156:159], v156 offset:3072
	v_lshl_add_u64 v[196:197], s[10:11], 0, v[184:185]
	s_add_i32 m0, s21, 0xc000
	ds_read_b128 v[160:163], v199
	ds_read_b128 v[188:191], v199 offset:1024
	ds_read_b128 v[192:195], v199 offset:2048
	ds_read_b128 v[210:213], v199 offset:3072
	ds_read_b128 v[214:217], v199 offset:4096
	ds_read_b128 v[218:221], v199 offset:5120
	ds_read_b128 v[222:225], v199 offset:6144
	ds_read_b128 v[226:229], v199 offset:7168
	global_load_lds_dwordx4 v[196:197], off
	v_lshl_add_u64 v[196:197], s[10:11], 0, v[182:183]
	s_add_i32 m0, s21, 0xe000
	s_nop 0
	global_load_lds_dwordx4 v[196:197], off
	s_waitcnt vmcnt(8)
	s_waitcnt lgkmcnt(0)
	s_barrier
	s_setprio 1
	s_waitcnt lgkmcnt(0)
	v_mfma_f32_16x16x32_f16 v[132:135], v[64:67], v[160:163], 0
	v_mfma_f32_16x16x32_f16 v[128:131], v[136:139], v[160:163], 0
	v_mfma_f32_16x16x32_f16 v[116:119], v[64:67], v[192:195], 0
	v_mfma_f32_16x16x32_f16 v[112:115], v[136:139], v[192:195], 0
	v_mfma_f32_16x16x32_f16 v[100:103], v[64:67], v[214:217], 0
	v_mfma_f32_16x16x32_f16 v[96:99], v[136:139], v[214:217], 0
	v_mfma_f32_16x16x32_f16 v[84:87], v[64:67], v[222:225], 0
	v_mfma_f32_16x16x32_f16 v[80:83], v[136:139], v[222:225], 0
	v_mfma_f32_16x16x32_f16 v[132:135], v[72:75], v[188:191], v[132:135]
	v_mfma_f32_16x16x32_f16 v[128:131], v[140:143], v[188:191], v[128:131]
	v_mfma_f32_16x16x32_f16 v[116:119], v[72:75], v[210:213], v[116:119]
	v_mfma_f32_16x16x32_f16 v[112:115], v[140:143], v[210:213], v[112:115]
	v_mfma_f32_16x16x32_f16 v[100:103], v[72:75], v[218:221], v[100:103]
	v_mfma_f32_16x16x32_f16 v[96:99], v[140:143], v[218:221], v[96:99]
	v_mfma_f32_16x16x32_f16 v[84:87], v[72:75], v[226:229], v[84:87]
	v_mfma_f32_16x16x32_f16 v[80:83], v[140:143], v[226:229], v[80:83]
	s_setprio 0
	s_setprio 1
	v_mfma_f32_16x16x32_f16 v[124:127], v[144:147], v[160:163], 0
	v_mfma_f32_16x16x32_f16 v[120:123], v[152:155], v[160:163], 0
	v_mfma_f32_16x16x32_f16 v[108:111], v[144:147], v[192:195], 0
	v_mfma_f32_16x16x32_f16 v[104:107], v[152:155], v[192:195], 0
	v_mfma_f32_16x16x32_f16 v[92:95], v[144:147], v[214:217], 0
	v_mfma_f32_16x16x32_f16 v[88:91], v[152:155], v[214:217], 0
	v_mfma_f32_16x16x32_f16 v[76:79], v[144:147], v[222:225], 0
	v_mfma_f32_16x16x32_f16 v[68:71], v[152:155], v[222:225], 0
	v_mfma_f32_16x16x32_f16 v[124:127], v[148:151], v[188:191], v[124:127]
	v_mfma_f32_16x16x32_f16 v[120:123], v[156:159], v[188:191], v[120:123]
	v_mfma_f32_16x16x32_f16 v[108:111], v[148:151], v[210:213], v[108:111]
	v_mfma_f32_16x16x32_f16 v[104:107], v[156:159], v[210:213], v[104:107]
	v_mfma_f32_16x16x32_f16 v[92:95], v[148:151], v[218:221], v[92:95]
	v_mfma_f32_16x16x32_f16 v[88:91], v[156:159], v[218:221], v[88:91]
	v_mfma_f32_16x16x32_f16 v[76:79], v[148:151], v[226:229], v[76:79]
	v_mfma_f32_16x16x32_f16 v[68:71], v[156:159], v[226:229], v[68:71]
	s_setprio 0
	s_barrier
	s_add_i32 s10, s54, s20
	v_lshl_add_u64 v[196:197], s[16:17], 0, v[168:169]
	s_mov_b32 m0, s10
	ds_read_b128 v[160:163], v199 offset:16384
	ds_read_b128 v[188:191], v199 offset:17408
	ds_read_b128 v[192:195], v199 offset:18432
	ds_read_b128 v[210:213], v199 offset:19456
	ds_read_b128 v[214:217], v199 offset:20480
	ds_read_b128 v[218:221], v199 offset:21504
	ds_read_b128 v[222:225], v199 offset:22528
	ds_read_b128 v[226:229], v199 offset:23552
	global_load_lds_dwordx4 v[196:197], off
	s_add_i32 m0, s10, 0x2000
	s_add_u32 s10, s16, 0x48000
	v_lshl_add_u64 v[230:231], s[16:17], 0, v[164:165]
	s_addc_u32 s11, s17, 0
	s_add_i32 s54, s55, s20
	global_load_lds_dwordx4 v[230:231], off
	v_lshl_add_u64 v[232:233], s[10:11], 0, v[168:169]
	s_mov_b32 m0, s54
	v_lshl_add_u64 v[234:235], s[18:19], 0, v[166:167]
	global_load_lds_dwordx4 v[232:233], off
	v_lshl_add_u64 v[232:233], s[10:11], 0, v[164:165]
	s_add_i32 m0, s54, 0x2000
	s_nop 0
	global_load_lds_dwordx4 v[232:233], off
	v_lshl_add_u64 v[232:233], s[18:19], 0, v[170:171]
	s_mov_b32 m0, s21
	s_nop 0
	global_load_lds_dwordx4 v[232:233], off
	s_mov_b32 m0, s22
	s_nop 0
	global_load_lds_dwordx4 v[234:235], off
	s_waitcnt vmcnt(8)
	s_waitcnt lgkmcnt(0)
	s_barrier
	s_setprio 1
	s_waitcnt lgkmcnt(0)
	v_mfma_f32_16x16x32_f16 v[60:63], v[64:67], v[160:163], 0
	v_mfma_f32_16x16x32_f16 v[56:59], v[136:139], v[160:163], 0
	v_mfma_f32_16x16x32_f16 v[44:47], v[64:67], v[192:195], 0
	v_mfma_f32_16x16x32_f16 v[40:43], v[136:139], v[192:195], 0
	v_mfma_f32_16x16x32_f16 v[28:31], v[64:67], v[214:217], 0
	v_mfma_f32_16x16x32_f16 v[24:27], v[136:139], v[214:217], 0
	v_mfma_f32_16x16x32_f16 v[12:15], v[64:67], v[222:225], 0
	v_mfma_f32_16x16x32_f16 v[8:11], v[136:139], v[222:225], 0
	v_mfma_f32_16x16x32_f16 v[60:63], v[72:75], v[188:191], v[60:63]
	v_mfma_f32_16x16x32_f16 v[56:59], v[140:143], v[188:191], v[56:59]
	v_mfma_f32_16x16x32_f16 v[44:47], v[72:75], v[210:213], v[44:47]
	v_mfma_f32_16x16x32_f16 v[40:43], v[140:143], v[210:213], v[40:43]
	v_mfma_f32_16x16x32_f16 v[28:31], v[72:75], v[218:221], v[28:31]
	v_mfma_f32_16x16x32_f16 v[24:27], v[140:143], v[218:221], v[24:27]
	v_mfma_f32_16x16x32_f16 v[12:15], v[72:75], v[226:229], v[12:15]
	v_mfma_f32_16x16x32_f16 v[8:11], v[140:143], v[226:229], v[8:11]
	s_setprio 0
	s_setprio 1
	v_mfma_f32_16x16x32_f16 v[52:55], v[144:147], v[160:163], 0
	v_mfma_f32_16x16x32_f16 v[48:51], v[152:155], v[160:163], 0
	v_mfma_f32_16x16x32_f16 v[36:39], v[144:147], v[192:195], 0
	v_mfma_f32_16x16x32_f16 v[32:35], v[152:155], v[192:195], 0
	v_mfma_f32_16x16x32_f16 v[20:23], v[144:147], v[214:217], 0
	v_mfma_f32_16x16x32_f16 v[16:19], v[152:155], v[214:217], 0
	v_mfma_f32_16x16x32_f16 v[4:7], v[144:147], v[222:225], 0
	v_mfma_f32_16x16x32_f16 v[0:3], v[152:155], v[222:225], 0
	v_mfma_f32_16x16x32_f16 v[52:55], v[148:151], v[188:191], v[52:55]
	v_mfma_f32_16x16x32_f16 v[48:51], v[156:159], v[188:191], v[48:51]
	v_mfma_f32_16x16x32_f16 v[36:39], v[148:151], v[210:213], v[36:39]
	v_mfma_f32_16x16x32_f16 v[32:35], v[156:159], v[210:213], v[32:35]
	v_mfma_f32_16x16x32_f16 v[20:23], v[148:151], v[218:221], v[20:23]
	v_mfma_f32_16x16x32_f16 v[16:19], v[156:159], v[218:221], v[16:19]
	v_mfma_f32_16x16x32_f16 v[4:7], v[148:151], v[226:229], v[4:7]
	v_mfma_f32_16x16x32_f16 v[0:3], v[156:159], v[226:229], v[0:3]
	s_setprio 0
	s_barrier
	s_add_i32 s54, 0, 0x18000
	s_add_i32 s55, 0, 0x1c000
	v_add_u32_e32 v140, s54, v198
	v_add_u32_e32 v156, s55, v198
	ds_read_b128 v[64:67], v140
	ds_read_b128 v[72:75], v140 offset:1024
	ds_read_b128 v[136:139], v140 offset:2048
	ds_read_b128 v[140:143], v140 offset:3072
	ds_read_b128 v[144:147], v156
	ds_read_b128 v[148:151], v156 offset:1024
	ds_read_b128 v[152:155], v156 offset:2048
	ds_read_b128 v[156:159], v156 offset:3072
	s_add_u32 s10, s18, 0x48000
	s_addc_u32 s11, s19, 0
	s_mov_b32 m0, s23
	v_lshl_add_u64 v[236:237], s[10:11], 0, v[170:171]
	ds_read_b128 v[160:163], v199 offset:32768
	ds_read_b128 v[188:191], v199 offset:33792
	ds_read_b128 v[192:195], v199 offset:34816
	ds_read_b128 v[210:213], v199 offset:35840
	ds_read_b128 v[214:217], v199 offset:36864
	ds_read_b128 v[218:221], v199 offset:37888
	ds_read_b128 v[222:225], v199 offset:38912
	ds_read_b128 v[226:229], v199 offset:39936
	global_load_lds_dwordx4 v[236:237], off
	v_lshl_add_u64 v[236:237], s[10:11], 0, v[166:167]
	s_mov_b32 m0, s24
	s_nop 0
	global_load_lds_dwordx4 v[236:237], off
	s_waitcnt vmcnt(8)
	s_waitcnt lgkmcnt(0)
	s_barrier
	s_setprio 1
	s_waitcnt lgkmcnt(0)
	v_mfma_f32_16x16x32_f16 v[132:135], v[64:67], v[160:163], v[132:135]
	v_mfma_f32_16x16x32_f16 v[128:131], v[136:139], v[160:163], v[128:131]
	v_mfma_f32_16x16x32_f16 v[116:119], v[64:67], v[192:195], v[116:119]
	v_mfma_f32_16x16x32_f16 v[112:115], v[136:139], v[192:195], v[112:115]
	v_mfma_f32_16x16x32_f16 v[100:103], v[64:67], v[214:217], v[100:103]
	v_mfma_f32_16x16x32_f16 v[96:99], v[136:139], v[214:217], v[96:99]
	v_mfma_f32_16x16x32_f16 v[84:87], v[64:67], v[222:225], v[84:87]
	v_mfma_f32_16x16x32_f16 v[80:83], v[136:139], v[222:225], v[80:83]
	v_mfma_f32_16x16x32_f16 v[132:135], v[72:75], v[188:191], v[132:135]
	v_mfma_f32_16x16x32_f16 v[128:131], v[140:143], v[188:191], v[128:131]
	v_mfma_f32_16x16x32_f16 v[116:119], v[72:75], v[210:213], v[116:119]
	v_mfma_f32_16x16x32_f16 v[112:115], v[140:143], v[210:213], v[112:115]
	v_mfma_f32_16x16x32_f16 v[100:103], v[72:75], v[218:221], v[100:103]
	v_mfma_f32_16x16x32_f16 v[96:99], v[140:143], v[218:221], v[96:99]
	v_mfma_f32_16x16x32_f16 v[84:87], v[72:75], v[226:229], v[84:87]
	v_mfma_f32_16x16x32_f16 v[80:83], v[140:143], v[226:229], v[80:83]
	s_setprio 0
	s_setprio 1
	v_mfma_f32_16x16x32_f16 v[124:127], v[144:147], v[160:163], v[124:127]
	v_mfma_f32_16x16x32_f16 v[120:123], v[152:155], v[160:163], v[120:123]
	v_mfma_f32_16x16x32_f16 v[108:111], v[144:147], v[192:195], v[108:111]
	v_mfma_f32_16x16x32_f16 v[104:107], v[152:155], v[192:195], v[104:107]
	v_mfma_f32_16x16x32_f16 v[92:95], v[144:147], v[214:217], v[92:95]
	v_mfma_f32_16x16x32_f16 v[88:91], v[152:155], v[214:217], v[88:91]
	v_mfma_f32_16x16x32_f16 v[76:79], v[144:147], v[222:225], v[76:79]
	v_mfma_f32_16x16x32_f16 v[68:71], v[152:155], v[222:225], v[68:71]
	v_mfma_f32_16x16x32_f16 v[124:127], v[148:151], v[188:191], v[124:127]
	v_mfma_f32_16x16x32_f16 v[120:123], v[156:159], v[188:191], v[120:123]
	v_mfma_f32_16x16x32_f16 v[108:111], v[148:151], v[210:213], v[108:111]
	v_mfma_f32_16x16x32_f16 v[104:107], v[156:159], v[210:213], v[104:107]
	v_mfma_f32_16x16x32_f16 v[92:95], v[148:151], v[218:221], v[92:95]
	v_mfma_f32_16x16x32_f16 v[88:91], v[156:159], v[218:221], v[88:91]
	v_mfma_f32_16x16x32_f16 v[76:79], v[148:151], v[226:229], v[76:79]
	v_mfma_f32_16x16x32_f16 v[68:71], v[156:159], v[226:229], v[68:71]
	s_setprio 0
	s_barrier
	s_add_i32 s10, s54, s20
	v_lshl_add_u64 v[196:197], v[196:197], 0, s[72:73]
	s_mov_b32 m0, s10
	ds_read_b128 v[160:163], v199 offset:49152
	ds_read_b128 v[188:191], v199 offset:50176
	ds_read_b128 v[192:195], v199 offset:51200
	ds_read_b128 v[210:213], v199 offset:52224
	ds_read_b128 v[214:217], v199 offset:53248
	ds_read_b128 v[218:221], v199 offset:54272
	ds_read_b128 v[222:225], v199 offset:55296
	ds_read_b128 v[226:229], v199 offset:56320
	global_load_lds_dwordx4 v[196:197], off
	s_add_i32 m0, s10, 0x2000
	s_add_u32 s10, s16, 0x48080
	v_lshl_add_u64 v[196:197], v[230:231], 0, s[72:73]
	s_addc_u32 s11, s17, 0
	s_add_i32 s16, s55, s20
	global_load_lds_dwordx4 v[196:197], off
	v_lshl_add_u64 v[196:197], s[10:11], 0, v[168:169]
	s_mov_b32 m0, s16
	s_nop 0
	global_load_lds_dwordx4 v[196:197], off
	v_lshl_add_u64 v[196:197], s[10:11], 0, v[164:165]
	s_add_i32 m0, s16, 0x2000
	s_nop 0
	global_load_lds_dwordx4 v[196:197], off
	v_lshl_add_u64 v[196:197], v[232:233], 0, s[72:73]
	s_mov_b32 m0, s25
	s_nop 0
	global_load_lds_dwordx4 v[196:197], off
	v_lshl_add_u64 v[196:197], v[234:235], 0, s[72:73]
	s_mov_b32 m0, s26
	s_nop 0
	global_load_lds_dwordx4 v[196:197], off
	s_waitcnt vmcnt(8)
	s_waitcnt lgkmcnt(0)
	s_barrier
	s_setprio 1
	s_waitcnt lgkmcnt(0)
	v_mfma_f32_16x16x32_f16 v[60:63], v[64:67], v[160:163], v[60:63]
	v_mfma_f32_16x16x32_f16 v[56:59], v[136:139], v[160:163], v[56:59]
	v_mfma_f32_16x16x32_f16 v[44:47], v[64:67], v[192:195], v[44:47]
	v_mfma_f32_16x16x32_f16 v[40:43], v[136:139], v[192:195], v[40:43]
	v_mfma_f32_16x16x32_f16 v[28:31], v[64:67], v[214:217], v[28:31]
	v_mfma_f32_16x16x32_f16 v[24:27], v[136:139], v[214:217], v[24:27]
	v_mfma_f32_16x16x32_f16 v[12:15], v[64:67], v[222:225], v[12:15]
	v_mfma_f32_16x16x32_f16 v[8:11], v[136:139], v[222:225], v[8:11]
	v_mfma_f32_16x16x32_f16 v[60:63], v[72:75], v[188:191], v[60:63]
	v_mfma_f32_16x16x32_f16 v[56:59], v[140:143], v[188:191], v[56:59]
	v_mfma_f32_16x16x32_f16 v[44:47], v[72:75], v[210:213], v[44:47]
	v_mfma_f32_16x16x32_f16 v[40:43], v[140:143], v[210:213], v[40:43]
	v_mfma_f32_16x16x32_f16 v[28:31], v[72:75], v[218:221], v[28:31]
	v_mfma_f32_16x16x32_f16 v[24:27], v[140:143], v[218:221], v[24:27]
	v_mfma_f32_16x16x32_f16 v[12:15], v[72:75], v[226:229], v[12:15]
	v_mfma_f32_16x16x32_f16 v[8:11], v[140:143], v[226:229], v[8:11]
	s_setprio 0
	s_setprio 1
	v_mfma_f32_16x16x32_f16 v[52:55], v[144:147], v[160:163], v[52:55]
	v_mfma_f32_16x16x32_f16 v[48:51], v[152:155], v[160:163], v[48:51]
	v_mfma_f32_16x16x32_f16 v[36:39], v[144:147], v[192:195], v[36:39]
	v_mfma_f32_16x16x32_f16 v[32:35], v[152:155], v[192:195], v[32:35]
	v_mfma_f32_16x16x32_f16 v[20:23], v[144:147], v[214:217], v[20:23]
	v_mfma_f32_16x16x32_f16 v[16:19], v[152:155], v[214:217], v[16:19]
	v_mfma_f32_16x16x32_f16 v[4:7], v[144:147], v[222:225], v[4:7]
	v_mfma_f32_16x16x32_f16 v[0:3], v[152:155], v[222:225], v[0:3]
	v_mfma_f32_16x16x32_f16 v[52:55], v[148:151], v[188:191], v[52:55]
	v_mfma_f32_16x16x32_f16 v[48:51], v[156:159], v[188:191], v[48:51]
	v_mfma_f32_16x16x32_f16 v[36:39], v[148:151], v[210:213], v[36:39]
	v_mfma_f32_16x16x32_f16 v[32:35], v[156:159], v[210:213], v[32:35]
	v_mfma_f32_16x16x32_f16 v[20:23], v[148:151], v[218:221], v[20:23]
	v_mfma_f32_16x16x32_f16 v[16:19], v[156:159], v[218:221], v[16:19]
	v_mfma_f32_16x16x32_f16 v[4:7], v[148:151], v[226:229], v[4:7]
	v_mfma_f32_16x16x32_f16 v[0:3], v[156:159], v[226:229], v[0:3]
	s_setprio 0
	s_barrier
	s_add_i32 s16, s53, 2
	s_add_i32 s10, s53, 4
	s_add_u32 s42, s42, 0x100
	s_addc_u32 s43, s43, 0
	s_cmp_ge_i32 s10, s39
	s_mov_b64 s[10:11], s[14:15]
	s_mov_b32 s53, s16

.LBB0_925:
	s_lshl_b64 s[16:17], s[10:11], 18
	s_add_u32 s16, s28, s16
	s_addc_u32 s17, s29, s17
	s_and_b64 s[0:1], s[0:1], exec
	s_cselect_b32 s11, s17, s23
	s_cselect_b32 s68, s16, s22
	s_add_u32 s69, s22, 0x100
	s_addc_u32 s70, s23, 0
	s_mov_b32 s71, -2
	s_add_u32 s0, s20, 0x100
	s_addc_u32 s1, s21, 0
	s_add_i32 s76, 0, 0x10000
	v_add_u32_e32 v79, s76, v77
	ds_read_b128 v[80:83], v79
	ds_read_b128 v[84:87], v79 offset:1024
	ds_read_b128 v[88:91], v79 offset:2048
	ds_read_b128 v[92:95], v79 offset:3072
	s_cmp_eq_u32 s71, 12
	s_cselect_b32 s25, s15, s1
	s_cselect_b32 s24, s14, s0
	s_cselect_b32 s23, s11, s70
	s_cselect_b32 s22, s68, s69
	v_lshl_add_u64 v[128:129], s[20:21], 0, v[74:75]
	s_add_i32 m0, s31, 0xc000
	ds_read_b128 v[96:99], v78
	ds_read_b128 v[100:103], v78 offset:1024
	ds_read_b128 v[104:107], v78 offset:2048
	ds_read_b128 v[108:111], v78 offset:3072
	ds_read_b128 v[112:115], v78 offset:4096
	ds_read_b128 v[116:119], v78 offset:5120
	ds_read_b128 v[120:123], v78 offset:6144
	ds_read_b128 v[124:127], v78 offset:7168
	global_load_lds_dwordx4 v[128:129], off
	v_lshl_add_u64 v[128:129], s[20:21], 0, v[72:73]
	s_add_i32 m0, s31, 0xe000
	s_nop 0
	global_load_lds_dwordx4 v[128:129], off
	s_waitcnt vmcnt(8)
	s_waitcnt lgkmcnt(0)
	s_barrier
	s_setprio 1
	s_waitcnt lgkmcnt(0)
	v_mfma_f32_16x16x32_f16 v[60:63], v[80:83], v[96:99], 0
	v_mfma_f32_16x16x32_f16 v[56:59], v[88:91], v[96:99], 0
	v_mfma_f32_16x16x32_f16 v[52:55], v[80:83], v[104:107], 0
	v_mfma_f32_16x16x32_f16 v[48:51], v[88:91], v[104:107], 0
	v_mfma_f32_16x16x32_f16 v[44:47], v[80:83], v[112:115], 0
	v_mfma_f32_16x16x32_f16 v[40:43], v[88:91], v[112:115], 0
	v_mfma_f32_16x16x32_f16 v[36:39], v[80:83], v[120:123], 0
	v_mfma_f32_16x16x32_f16 v[32:35], v[88:91], v[120:123], 0
	v_mfma_f32_16x16x32_f16 v[60:63], v[84:87], v[100:103], v[60:63]
	v_mfma_f32_16x16x32_f16 v[56:59], v[92:95], v[100:103], v[56:59]
	v_mfma_f32_16x16x32_f16 v[52:55], v[84:87], v[108:111], v[52:55]
	v_mfma_f32_16x16x32_f16 v[48:51], v[92:95], v[108:111], v[48:51]
	v_mfma_f32_16x16x32_f16 v[44:47], v[84:87], v[116:119], v[44:47]
	v_mfma_f32_16x16x32_f16 v[40:43], v[92:95], v[116:119], v[40:43]
	v_mfma_f32_16x16x32_f16 v[36:39], v[84:87], v[124:127], v[36:39]
	v_mfma_f32_16x16x32_f16 v[32:35], v[92:95], v[124:127], v[32:35]
	s_setprio 0
	s_setprio 1
	s_setprio 0
	s_barrier
	s_add_i32 s20, s76, s30
	v_lshl_add_u64 v[128:129], s[22:23], 0, v[68:69]
	s_mov_b32 m0, s20
	ds_read_b128 v[96:99], v78 offset:16384
	ds_read_b128 v[100:103], v78 offset:17408
	ds_read_b128 v[104:107], v78 offset:18432
	ds_read_b128 v[108:111], v78 offset:19456
	ds_read_b128 v[112:115], v78 offset:20480
	ds_read_b128 v[116:119], v78 offset:21504
	ds_read_b128 v[120:123], v78 offset:22528
	ds_read_b128 v[124:127], v78 offset:23552
	global_load_lds_dwordx4 v[128:129], off
	s_add_i32 m0, s20, 0x2000
	s_add_u32 s20, s22, 0x40000
	v_lshl_add_u64 v[130:131], s[22:23], 0, v[64:65]
	s_addc_u32 s21, s23, 0
	global_load_lds_dwordx4 v[130:131], off
	v_lshl_add_u64 v[132:133], s[20:21], 0, v[68:69]
	s_mov_b32 m0, s36
	v_lshl_add_u64 v[134:135], s[24:25], 0, v[66:67]
	global_load_lds_dwordx4 v[132:133], off
	v_lshl_add_u64 v[132:133], s[20:21], 0, v[64:65]
	s_mov_b32 m0, s37
	s_nop 0
	global_load_lds_dwordx4 v[132:133], off
	v_lshl_add_u64 v[132:133], s[24:25], 0, v[70:71]
	s_mov_b32 m0, s31
	s_nop 0
	global_load_lds_dwordx4 v[132:133], off
	s_mov_b32 m0, s38
	s_nop 0
	global_load_lds_dwordx4 v[134:135], off
	s_waitcnt vmcnt(8)
	s_waitcnt lgkmcnt(0)
	s_barrier
	s_setprio 1
	s_waitcnt lgkmcnt(0)
	v_mfma_f32_16x16x32_f16 v[28:31], v[80:83], v[96:99], 0
	v_mfma_f32_16x16x32_f16 v[24:27], v[88:91], v[96:99], 0
	v_mfma_f32_16x16x32_f16 v[20:23], v[80:83], v[104:107], 0
	v_mfma_f32_16x16x32_f16 v[16:19], v[88:91], v[104:107], 0
	v_mfma_f32_16x16x32_f16 v[12:15], v[80:83], v[112:115], 0
	v_mfma_f32_16x16x32_f16 v[8:11], v[88:91], v[112:115], 0
	v_mfma_f32_16x16x32_f16 v[4:7], v[80:83], v[120:123], 0
	v_mfma_f32_16x16x32_f16 v[0:3], v[88:91], v[120:123], 0
	v_mfma_f32_16x16x32_f16 v[28:31], v[84:87], v[100:103], v[28:31]
	v_mfma_f32_16x16x32_f16 v[24:27], v[92:95], v[100:103], v[24:27]
	v_mfma_f32_16x16x32_f16 v[20:23], v[84:87], v[108:111], v[20:23]
	v_mfma_f32_16x16x32_f16 v[16:19], v[92:95], v[108:111], v[16:19]
	v_mfma_f32_16x16x32_f16 v[12:15], v[84:87], v[116:119], v[12:15]
	v_mfma_f32_16x16x32_f16 v[8:11], v[92:95], v[116:119], v[8:11]
	v_mfma_f32_16x16x32_f16 v[4:7], v[84:87], v[124:127], v[4:7]
	v_mfma_f32_16x16x32_f16 v[0:3], v[92:95], v[124:127], v[0:3]
	s_setprio 0
	s_setprio 1
	s_setprio 0
	s_barrier
	s_add_i32 s76, 0, 0x18000
	v_add_u32_e32 v79, s76, v77
	ds_read_b128 v[80:83], v79
	ds_read_b128 v[84:87], v79 offset:1024
	ds_read_b128 v[88:91], v79 offset:2048
	ds_read_b128 v[92:95], v79 offset:3072
	s_add_u32 s20, s24, 0x48000
	s_addc_u32 s21, s25, 0
	s_mov_b32 m0, s39
	v_lshl_add_u64 v[136:137], s[20:21], 0, v[70:71]
	ds_read_b128 v[96:99], v78 offset:32768
	ds_read_b128 v[100:103], v78 offset:33792
	ds_read_b128 v[104:107], v78 offset:34816
	ds_read_b128 v[108:111], v78 offset:35840
	ds_read_b128 v[112:115], v78 offset:36864
	ds_read_b128 v[116:119], v78 offset:37888
	ds_read_b128 v[120:123], v78 offset:38912
	ds_read_b128 v[124:127], v78 offset:39936
	global_load_lds_dwordx4 v[136:137], off
	v_lshl_add_u64 v[136:137], s[20:21], 0, v[66:67]
	s_mov_b32 m0, s42
	s_nop 0
	global_load_lds_dwordx4 v[136:137], off
	s_waitcnt vmcnt(8)
	s_waitcnt lgkmcnt(0)
	s_barrier
	s_setprio 1
	s_waitcnt lgkmcnt(0)
	v_mfma_f32_16x16x32_f16 v[60:63], v[80:83], v[96:99], v[60:63]
	v_mfma_f32_16x16x32_f16 v[56:59], v[88:91], v[96:99], v[56:59]
	v_mfma_f32_16x16x32_f16 v[52:55], v[80:83], v[104:107], v[52:55]
	v_mfma_f32_16x16x32_f16 v[48:51], v[88:91], v[104:107], v[48:51]
	v_mfma_f32_16x16x32_f16 v[44:47], v[80:83], v[112:115], v[44:47]
	v_mfma_f32_16x16x32_f16 v[40:43], v[88:91], v[112:115], v[40:43]
	v_mfma_f32_16x16x32_f16 v[36:39], v[80:83], v[120:123], v[36:39]
	v_mfma_f32_16x16x32_f16 v[32:35], v[88:91], v[120:123], v[32:35]
	v_mfma_f32_16x16x32_f16 v[60:63], v[84:87], v[100:103], v[60:63]
	v_mfma_f32_16x16x32_f16 v[56:59], v[92:95], v[100:103], v[56:59]
	v_mfma_f32_16x16x32_f16 v[52:55], v[84:87], v[108:111], v[52:55]
	v_mfma_f32_16x16x32_f16 v[48:51], v[92:95], v[108:111], v[48:51]
	v_mfma_f32_16x16x32_f16 v[44:47], v[84:87], v[116:119], v[44:47]
	v_mfma_f32_16x16x32_f16 v[40:43], v[92:95], v[116:119], v[40:43]
	v_mfma_f32_16x16x32_f16 v[36:39], v[84:87], v[124:127], v[36:39]
	v_mfma_f32_16x16x32_f16 v[32:35], v[92:95], v[124:127], v[32:35]
	s_setprio 0
	s_setprio 1
	s_setprio 0
	s_barrier
	s_add_i32 s20, s76, s30
	v_lshl_add_u64 v[128:129], v[128:129], 0, s[72:73]
	s_mov_b32 m0, s20
	ds_read_b128 v[96:99], v78 offset:49152
	ds_read_b128 v[100:103], v78 offset:50176
	ds_read_b128 v[104:107], v78 offset:51200
	ds_read_b128 v[108:111], v78 offset:52224
	ds_read_b128 v[112:115], v78 offset:53248
	ds_read_b128 v[116:119], v78 offset:54272
	ds_read_b128 v[120:123], v78 offset:55296
	ds_read_b128 v[124:127], v78 offset:56320
	global_load_lds_dwordx4 v[128:129], off
	s_add_i32 m0, s20, 0x2000
	s_add_u32 s20, s22, 0x40080
	v_lshl_add_u64 v[128:129], v[130:131], 0, s[72:73]
	s_addc_u32 s21, s23, 0
	global_load_lds_dwordx4 v[128:129], off
	v_lshl_add_u64 v[128:129], s[20:21], 0, v[68:69]
	s_mov_b32 m0, s54
	s_nop 0
	global_load_lds_dwordx4 v[128:129], off
	v_lshl_add_u64 v[128:129], s[20:21], 0, v[64:65]
	s_mov_b32 m0, s55
	s_nop 0
	global_load_lds_dwordx4 v[128:129], off
	v_lshl_add_u64 v[128:129], v[132:133], 0, s[72:73]
	s_mov_b32 m0, s49
	s_nop 0
	global_load_lds_dwordx4 v[128:129], off
	v_lshl_add_u64 v[128:129], v[134:135], 0, s[72:73]
	s_mov_b32 m0, s53
	s_nop 0
	global_load_lds_dwordx4 v[128:129], off
	s_waitcnt vmcnt(8)
	s_waitcnt lgkmcnt(0)
	s_barrier
	s_setprio 1
	s_waitcnt lgkmcnt(0)
	v_mfma_f32_16x16x32_f16 v[28:31], v[80:83], v[96:99], v[28:31]
	v_mfma_f32_16x16x32_f16 v[24:27], v[88:91], v[96:99], v[24:27]
	v_mfma_f32_16x16x32_f16 v[20:23], v[80:83], v[104:107], v[20:23]
	v_mfma_f32_16x16x32_f16 v[16:19], v[88:91], v[104:107], v[16:19]
	v_mfma_f32_16x16x32_f16 v[12:15], v[80:83], v[112:115], v[12:15]
	v_mfma_f32_16x16x32_f16 v[8:11], v[88:91], v[112:115], v[8:11]
	v_mfma_f32_16x16x32_f16 v[4:7], v[80:83], v[120:123], v[4:7]
	v_mfma_f32_16x16x32_f16 v[0:3], v[88:91], v[120:123], v[0:3]
	v_mfma_f32_16x16x32_f16 v[28:31], v[84:87], v[100:103], v[28:31]
	v_mfma_f32_16x16x32_f16 v[24:27], v[92:95], v[100:103], v[24:27]
	v_mfma_f32_16x16x32_f16 v[20:23], v[84:87], v[108:111], v[20:23]
	v_mfma_f32_16x16x32_f16 v[16:19], v[92:95], v[108:111], v[16:19]
	v_mfma_f32_16x16x32_f16 v[12:15], v[84:87], v[116:119], v[12:15]
	v_mfma_f32_16x16x32_f16 v[8:11], v[92:95], v[116:119], v[8:11]
	v_mfma_f32_16x16x32_f16 v[4:7], v[84:87], v[124:127], v[4:7]
	v_mfma_f32_16x16x32_f16 v[0:3], v[92:95], v[124:127], v[0:3]
	s_setprio 0
	s_setprio 1
	s_setprio 0
	s_barrier
	s_add_i32 s71, s71, 2
	s_add_u32 s69, s69, 0x100
	s_addc_u32 s70, s70, 0
	s_cmp_gt_u32 s71, 13
	s_mov_b64 s[20:21], s[0:1]

.LBB0_953:
	s_ashr_i32 s11, s10, 31
	s_lshl_b64 s[14:15], s[10:11], 19
	s_add_u32 s14, s44, s14
	s_addc_u32 s15, s45, s15
	s_and_b64 s[16:17], s[4:5], exec
	s_cselect_b32 s11, s15, s21
	s_cselect_b32 s42, s14, s20
	s_ashr_i32 s9, s8, 31
	s_lshl_b64 s[16:17], s[8:9], 19
	s_add_u32 s16, s34, s16
	s_addc_u32 s17, s35, s17
	s_and_b64 s[22:23], s[4:5], exec
	s_cselect_b32 s9, s17, s19
	s_cselect_b32 s43, s16, s18
	s_add_u32 s48, s18, 0x100
	s_addc_u32 s49, s19, 0
	s_add_u32 s18, s20, 0x40080
	s_addc_u32 s19, s21, 0
	s_mov_b32 s54, -2
	s_add_u32 s20, s18, 0xfffc0080
	s_addc_u32 s21, s19, -1
	s_add_i32 s53, 0, 0x10000
	s_cmp_eq_u32 s54, 12
	s_cselect_b32 s23, s11, s21
	s_cselect_b32 s22, s42, s20
	v_add_u32_e32 v148, s53, v137
	s_cselect_b32 s21, s9, s49
	s_cselect_b32 s20, s43, s48
	s_add_i32 s55, 0, 0x14000
	ds_read_b128 v[156:159], v148
	ds_read_b128 v[160:163], v148 offset:1024
	ds_read_b128 v[164:167], v148 offset:2048
	ds_read_b128 v[168:171], v148 offset:3072
	v_add_u32_e32 v148, s55, v137
	ds_read_b128 v[172:175], v148
	ds_read_b128 v[182:185], v148 offset:1024
	ds_read_b128 v[186:189], v148 offset:2048
	ds_read_b128 v[190:193], v148 offset:3072
	v_lshl_add_u64 v[148:149], s[18:19], 0, v[146:147]
	s_add_i32 m0, s25, 0xc000
	ds_read_b128 v[194:197], v154
	ds_read_b128 v[210:213], v154 offset:1024
	ds_read_b128 v[214:217], v154 offset:2048
	ds_read_b128 v[218:221], v154 offset:3072
	ds_read_b128 v[222:225], v154 offset:4096
	ds_read_b128 v[226:229], v154 offset:5120
	ds_read_b128 v[230:233], v154 offset:6144
	ds_read_b128 v[234:237], v154 offset:7168
	global_load_lds_dwordx4 v[148:149], off
	v_lshl_add_u64 v[148:149], s[18:19], 0, v[144:145]
	s_add_i32 m0, s25, 0xe000
	s_nop 0
	global_load_lds_dwordx4 v[148:149], off
	s_waitcnt vmcnt(8)
	s_waitcnt lgkmcnt(0)
	s_barrier
	s_setprio 1
	s_waitcnt lgkmcnt(0)
	v_mfma_f32_16x16x32_f16 v[124:127], v[156:159], v[194:197], 0
	v_mfma_f32_16x16x32_f16 v[120:123], v[164:167], v[194:197], 0
	v_mfma_f32_16x16x32_f16 v[116:119], v[156:159], v[214:217], 0
	v_mfma_f32_16x16x32_f16 v[108:111], v[164:167], v[214:217], 0
	v_mfma_f32_16x16x32_f16 v[100:103], v[156:159], v[222:225], 0
	v_mfma_f32_16x16x32_f16 v[92:95], v[164:167], v[222:225], 0
	v_mfma_f32_16x16x32_f16 v[84:87], v[156:159], v[230:233], 0
	v_mfma_f32_16x16x32_f16 v[76:79], v[164:167], v[230:233], 0
	v_mfma_f32_16x16x32_f16 v[124:127], v[160:163], v[210:213], v[124:127]
	v_mfma_f32_16x16x32_f16 v[120:123], v[168:171], v[210:213], v[120:123]
	v_mfma_f32_16x16x32_f16 v[116:119], v[160:163], v[218:221], v[116:119]
	v_mfma_f32_16x16x32_f16 v[108:111], v[168:171], v[218:221], v[108:111]
	v_mfma_f32_16x16x32_f16 v[100:103], v[160:163], v[226:229], v[100:103]
	v_mfma_f32_16x16x32_f16 v[92:95], v[168:171], v[226:229], v[92:95]
	v_mfma_f32_16x16x32_f16 v[84:87], v[160:163], v[234:237], v[84:87]
	v_mfma_f32_16x16x32_f16 v[76:79], v[168:171], v[234:237], v[76:79]
	s_setprio 0
	s_setprio 1
	v_mfma_f32_16x16x32_f16 v[112:115], v[172:175], v[194:197], 0
	v_mfma_f32_16x16x32_f16 v[104:107], v[186:189], v[194:197], 0
	v_mfma_f32_16x16x32_f16 v[96:99], v[172:175], v[214:217], 0
	v_mfma_f32_16x16x32_f16 v[88:91], v[186:189], v[214:217], 0
	v_mfma_f32_16x16x32_f16 v[80:83], v[172:175], v[222:225], 0
	v_mfma_f32_16x16x32_f16 v[72:75], v[186:189], v[222:225], 0
	v_mfma_f32_16x16x32_f16 v[68:71], v[172:175], v[230:233], 0
	v_mfma_f32_16x16x32_f16 v[64:67], v[186:189], v[230:233], 0
	v_mfma_f32_16x16x32_f16 v[112:115], v[182:185], v[210:213], v[112:115]
	v_mfma_f32_16x16x32_f16 v[104:107], v[190:193], v[210:213], v[104:107]
	v_mfma_f32_16x16x32_f16 v[96:99], v[182:185], v[218:221], v[96:99]
	v_mfma_f32_16x16x32_f16 v[88:91], v[190:193], v[218:221], v[88:91]
	v_mfma_f32_16x16x32_f16 v[80:83], v[182:185], v[226:229], v[80:83]
	v_mfma_f32_16x16x32_f16 v[72:75], v[190:193], v[226:229], v[72:75]
	v_mfma_f32_16x16x32_f16 v[68:71], v[182:185], v[234:237], v[68:71]
	v_mfma_f32_16x16x32_f16 v[64:67], v[190:193], v[234:237], v[64:67]
	s_setprio 0
	s_barrier
	s_add_i32 s53, s53, s24
	v_lshl_add_u64 v[148:149], s[20:21], 0, v[176:177]
	s_mov_b32 m0, s53
	ds_read_b128 v[194:197], v154 offset:16384
	ds_read_b128 v[210:213], v154 offset:17408
	ds_read_b128 v[214:217], v154 offset:18432
	ds_read_b128 v[218:221], v154 offset:19456
	ds_read_b128 v[222:225], v154 offset:20480
	ds_read_b128 v[226:229], v154 offset:21504
	ds_read_b128 v[230:233], v154 offset:22528
	ds_read_b128 v[234:237], v154 offset:23552
	global_load_lds_dwordx4 v[148:149], off
	s_add_i32 m0, s53, 0x2000
	s_add_u32 s56, s20, 0x40000
	v_lshl_add_u64 v[198:199], s[20:21], 0, v[128:129]
	s_addc_u32 s57, s21, 0
	s_add_i32 s53, s55, s24
	global_load_lds_dwordx4 v[198:199], off
	v_lshl_add_u64 v[238:239], s[56:57], 0, v[176:177]
	s_mov_b32 m0, s53
	v_lshl_add_u64 v[240:241], s[22:23], 0, v[130:131]
	global_load_lds_dwordx4 v[238:239], off
	v_lshl_add_u64 v[238:239], s[56:57], 0, v[128:129]
	s_add_i32 m0, s53, 0x2000
	s_nop 0
	global_load_lds_dwordx4 v[238:239], off
	v_lshl_add_u64 v[238:239], s[22:23], 0, v[132:133]
	s_mov_b32 m0, s25
	s_nop 0
	global_load_lds_dwordx4 v[238:239], off
	s_mov_b32 m0, s26
	s_nop 0
	global_load_lds_dwordx4 v[240:241], off
	s_waitcnt vmcnt(8)
	s_waitcnt lgkmcnt(0)
	s_barrier
	s_setprio 1
	s_waitcnt lgkmcnt(0)
	v_mfma_f32_16x16x32_f16 v[60:63], v[156:159], v[194:197], 0
	v_mfma_f32_16x16x32_f16 v[56:59], v[164:167], v[194:197], 0
	v_mfma_f32_16x16x32_f16 v[52:55], v[156:159], v[214:217], 0
	v_mfma_f32_16x16x32_f16 v[44:47], v[164:167], v[214:217], 0
	v_mfma_f32_16x16x32_f16 v[36:39], v[156:159], v[222:225], 0
	v_mfma_f32_16x16x32_f16 v[28:31], v[164:167], v[222:225], 0
	v_mfma_f32_16x16x32_f16 v[20:23], v[156:159], v[230:233], 0
	v_mfma_f32_16x16x32_f16 v[12:15], v[164:167], v[230:233], 0
	v_mfma_f32_16x16x32_f16 v[60:63], v[160:163], v[210:213], v[60:63]
	v_mfma_f32_16x16x32_f16 v[56:59], v[168:171], v[210:213], v[56:59]
	v_mfma_f32_16x16x32_f16 v[52:55], v[160:163], v[218:221], v[52:55]
	v_mfma_f32_16x16x32_f16 v[44:47], v[168:171], v[218:221], v[44:47]
	v_mfma_f32_16x16x32_f16 v[36:39], v[160:163], v[226:229], v[36:39]
	v_mfma_f32_16x16x32_f16 v[28:31], v[168:171], v[226:229], v[28:31]
	v_mfma_f32_16x16x32_f16 v[20:23], v[160:163], v[234:237], v[20:23]
	v_mfma_f32_16x16x32_f16 v[12:15], v[168:171], v[234:237], v[12:15]
	s_setprio 0
	s_setprio 1
	v_mfma_f32_16x16x32_f16 v[48:51], v[172:175], v[194:197], 0
	v_mfma_f32_16x16x32_f16 v[40:43], v[186:189], v[194:197], 0
	v_mfma_f32_16x16x32_f16 v[32:35], v[172:175], v[214:217], 0
	v_mfma_f32_16x16x32_f16 v[24:27], v[186:189], v[214:217], 0
	v_mfma_f32_16x16x32_f16 v[16:19], v[172:175], v[222:225], 0
	v_mfma_f32_16x16x32_f16 v[8:11], v[186:189], v[222:225], 0
	v_mfma_f32_16x16x32_f16 v[4:7], v[172:175], v[230:233], 0
	v_mfma_f32_16x16x32_f16 v[0:3], v[186:189], v[230:233], 0
	v_mfma_f32_16x16x32_f16 v[48:51], v[182:185], v[210:213], v[48:51]
	v_mfma_f32_16x16x32_f16 v[40:43], v[190:193], v[210:213], v[40:43]
	v_mfma_f32_16x16x32_f16 v[32:35], v[182:185], v[218:221], v[32:35]
	v_mfma_f32_16x16x32_f16 v[24:27], v[190:193], v[218:221], v[24:27]
	v_mfma_f32_16x16x32_f16 v[16:19], v[182:185], v[226:229], v[16:19]
	v_mfma_f32_16x16x32_f16 v[8:11], v[190:193], v[226:229], v[8:11]
	v_mfma_f32_16x16x32_f16 v[4:7], v[182:185], v[234:237], v[4:7]
	v_mfma_f32_16x16x32_f16 v[0:3], v[190:193], v[234:237], v[0:3]
	s_setprio 0
	s_barrier
	s_add_i32 s53, 0, 0x18000
	v_add_u32_e32 v155, s53, v137
	s_add_i32 s55, 0, 0x1c000
	ds_read_b128 v[156:159], v155
	ds_read_b128 v[160:163], v155 offset:1024
	ds_read_b128 v[164:167], v155 offset:2048
	ds_read_b128 v[168:171], v155 offset:3072
	v_add_u32_e32 v155, s55, v137
	ds_read_b128 v[172:175], v155
	ds_read_b128 v[182:185], v155 offset:1024
	ds_read_b128 v[186:189], v155 offset:2048
	ds_read_b128 v[190:193], v155 offset:3072
	s_add_u32 s22, s22, 0x40000
	s_addc_u32 s23, s23, 0
	s_mov_b32 m0, s27
	v_lshl_add_u64 v[242:243], s[22:23], 0, v[132:133]
	ds_read_b128 v[194:197], v154 offset:32768
	ds_read_b128 v[210:213], v154 offset:33792
	ds_read_b128 v[214:217], v154 offset:34816
	ds_read_b128 v[218:221], v154 offset:35840
	ds_read_b128 v[222:225], v154 offset:36864
	ds_read_b128 v[226:229], v154 offset:37888
	ds_read_b128 v[230:233], v154 offset:38912
	ds_read_b128 v[234:237], v154 offset:39936
	global_load_lds_dwordx4 v[242:243], off
	v_lshl_add_u64 v[242:243], s[22:23], 0, v[130:131]
	s_mov_b32 m0, s28
	s_nop 0
	global_load_lds_dwordx4 v[242:243], off
	s_waitcnt vmcnt(8)
	s_waitcnt lgkmcnt(0)
	s_barrier
	s_setprio 1
	s_waitcnt lgkmcnt(0)
	v_mfma_f32_16x16x32_f16 v[124:127], v[156:159], v[194:197], v[124:127]
	v_mfma_f32_16x16x32_f16 v[120:123], v[164:167], v[194:197], v[120:123]
	v_mfma_f32_16x16x32_f16 v[116:119], v[156:159], v[214:217], v[116:119]
	v_mfma_f32_16x16x32_f16 v[108:111], v[164:167], v[214:217], v[108:111]
	v_mfma_f32_16x16x32_f16 v[100:103], v[156:159], v[222:225], v[100:103]
	v_mfma_f32_16x16x32_f16 v[92:95], v[164:167], v[222:225], v[92:95]
	v_mfma_f32_16x16x32_f16 v[84:87], v[156:159], v[230:233], v[84:87]
	v_mfma_f32_16x16x32_f16 v[76:79], v[164:167], v[230:233], v[76:79]
	v_mfma_f32_16x16x32_f16 v[124:127], v[160:163], v[210:213], v[124:127]
	v_mfma_f32_16x16x32_f16 v[120:123], v[168:171], v[210:213], v[120:123]
	v_mfma_f32_16x16x32_f16 v[116:119], v[160:163], v[218:221], v[116:119]
	v_mfma_f32_16x16x32_f16 v[108:111], v[168:171], v[218:221], v[108:111]
	v_mfma_f32_16x16x32_f16 v[100:103], v[160:163], v[226:229], v[100:103]
	v_mfma_f32_16x16x32_f16 v[92:95], v[168:171], v[226:229], v[92:95]
	v_mfma_f32_16x16x32_f16 v[84:87], v[160:163], v[234:237], v[84:87]
	v_mfma_f32_16x16x32_f16 v[76:79], v[168:171], v[234:237], v[76:79]
	s_setprio 0
	s_setprio 1
	v_mfma_f32_16x16x32_f16 v[112:115], v[172:175], v[194:197], v[112:115]
	v_mfma_f32_16x16x32_f16 v[104:107], v[186:189], v[194:197], v[104:107]
	v_mfma_f32_16x16x32_f16 v[96:99], v[172:175], v[214:217], v[96:99]
	v_mfma_f32_16x16x32_f16 v[88:91], v[186:189], v[214:217], v[88:91]
	v_mfma_f32_16x16x32_f16 v[80:83], v[172:175], v[222:225], v[80:83]
	v_mfma_f32_16x16x32_f16 v[72:75], v[186:189], v[222:225], v[72:75]
	v_mfma_f32_16x16x32_f16 v[68:71], v[172:175], v[230:233], v[68:71]
	v_mfma_f32_16x16x32_f16 v[64:67], v[186:189], v[230:233], v[64:67]
	v_mfma_f32_16x16x32_f16 v[112:115], v[182:185], v[210:213], v[112:115]
	v_mfma_f32_16x16x32_f16 v[104:107], v[190:193], v[210:213], v[104:107]
	v_mfma_f32_16x16x32_f16 v[96:99], v[182:185], v[218:221], v[96:99]
	v_mfma_f32_16x16x32_f16 v[88:91], v[190:193], v[218:221], v[88:91]
	v_mfma_f32_16x16x32_f16 v[80:83], v[182:185], v[226:229], v[80:83]
	v_mfma_f32_16x16x32_f16 v[72:75], v[190:193], v[226:229], v[72:75]
	v_mfma_f32_16x16x32_f16 v[68:71], v[182:185], v[234:237], v[68:71]
	v_mfma_f32_16x16x32_f16 v[64:67], v[190:193], v[234:237], v[64:67]
	s_setprio 0
	s_barrier
	s_add_i32 s22, s53, s24
	v_lshl_add_u64 v[148:149], v[148:149], 0, s[72:73]
	s_mov_b32 m0, s22
	ds_read_b128 v[194:197], v154 offset:49152
	ds_read_b128 v[210:213], v154 offset:50176
	ds_read_b128 v[214:217], v154 offset:51200
	ds_read_b128 v[218:221], v154 offset:52224
	ds_read_b128 v[222:225], v154 offset:53248
	ds_read_b128 v[226:229], v154 offset:54272
	ds_read_b128 v[230:233], v154 offset:55296
	ds_read_b128 v[234:237], v154 offset:56320
	global_load_lds_dwordx4 v[148:149], off
	s_add_i32 m0, s22, 0x2000
	s_add_u32 s20, s20, 0x40080
	v_lshl_add_u64 v[148:149], v[198:199], 0, s[72:73]
	s_addc_u32 s21, s21, 0
	s_add_i32 s22, s55, s24
	global_load_lds_dwordx4 v[148:149], off
	v_lshl_add_u64 v[148:149], s[20:21], 0, v[176:177]
	s_mov_b32 m0, s22
	s_nop 0
	global_load_lds_dwordx4 v[148:149], off
	v_lshl_add_u64 v[148:149], s[20:21], 0, v[128:129]
	s_add_i32 m0, s22, 0x2000
	s_nop 0
	global_load_lds_dwordx4 v[148:149], off
	v_lshl_add_u64 v[148:149], v[238:239], 0, s[72:73]
	s_mov_b32 m0, s30
	s_nop 0
	global_load_lds_dwordx4 v[148:149], off
	v_lshl_add_u64 v[148:149], v[240:241], 0, s[72:73]
	s_mov_b32 m0, s31
	s_nop 0
	global_load_lds_dwordx4 v[148:149], off
	s_waitcnt vmcnt(8)
	s_waitcnt lgkmcnt(0)
	s_barrier
	s_setprio 1
	s_waitcnt lgkmcnt(0)
	v_mfma_f32_16x16x32_f16 v[60:63], v[156:159], v[194:197], v[60:63]
	v_mfma_f32_16x16x32_f16 v[56:59], v[164:167], v[194:197], v[56:59]
	v_mfma_f32_16x16x32_f16 v[52:55], v[156:159], v[214:217], v[52:55]
	v_mfma_f32_16x16x32_f16 v[44:47], v[164:167], v[214:217], v[44:47]
	v_mfma_f32_16x16x32_f16 v[36:39], v[156:159], v[222:225], v[36:39]
	v_mfma_f32_16x16x32_f16 v[28:31], v[164:167], v[222:225], v[28:31]
	v_mfma_f32_16x16x32_f16 v[20:23], v[156:159], v[230:233], v[20:23]
	v_mfma_f32_16x16x32_f16 v[12:15], v[164:167], v[230:233], v[12:15]
	v_mfma_f32_16x16x32_f16 v[60:63], v[160:163], v[210:213], v[60:63]
	v_mfma_f32_16x16x32_f16 v[56:59], v[168:171], v[210:213], v[56:59]
	v_mfma_f32_16x16x32_f16 v[52:55], v[160:163], v[218:221], v[52:55]
	v_mfma_f32_16x16x32_f16 v[44:47], v[168:171], v[218:221], v[44:47]
	v_mfma_f32_16x16x32_f16 v[36:39], v[160:163], v[226:229], v[36:39]
	v_mfma_f32_16x16x32_f16 v[28:31], v[168:171], v[226:229], v[28:31]
	v_mfma_f32_16x16x32_f16 v[20:23], v[160:163], v[234:237], v[20:23]
	v_mfma_f32_16x16x32_f16 v[12:15], v[168:171], v[234:237], v[12:15]
	s_setprio 0
	s_setprio 1
	v_mfma_f32_16x16x32_f16 v[48:51], v[172:175], v[194:197], v[48:51]
	v_mfma_f32_16x16x32_f16 v[40:43], v[186:189], v[194:197], v[40:43]
	v_mfma_f32_16x16x32_f16 v[32:35], v[172:175], v[214:217], v[32:35]
	v_mfma_f32_16x16x32_f16 v[24:27], v[186:189], v[214:217], v[24:27]
	v_mfma_f32_16x16x32_f16 v[16:19], v[172:175], v[222:225], v[16:19]
	v_mfma_f32_16x16x32_f16 v[8:11], v[186:189], v[222:225], v[8:11]
	v_mfma_f32_16x16x32_f16 v[4:7], v[172:175], v[230:233], v[4:7]
	v_mfma_f32_16x16x32_f16 v[0:3], v[186:189], v[230:233], v[0:3]
	v_mfma_f32_16x16x32_f16 v[48:51], v[182:185], v[210:213], v[48:51]
	v_mfma_f32_16x16x32_f16 v[40:43], v[190:193], v[210:213], v[40:43]
	v_mfma_f32_16x16x32_f16 v[32:35], v[182:185], v[218:221], v[32:35]
	v_mfma_f32_16x16x32_f16 v[24:27], v[190:193], v[218:221], v[24:27]
	v_mfma_f32_16x16x32_f16 v[16:19], v[182:185], v[226:229], v[16:19]
	v_mfma_f32_16x16x32_f16 v[8:11], v[190:193], v[226:229], v[8:11]
	v_mfma_f32_16x16x32_f16 v[4:7], v[182:185], v[234:237], v[4:7]
	v_mfma_f32_16x16x32_f16 v[0:3], v[190:193], v[234:237], v[0:3]
	s_setprio 0
	s_barrier
	s_add_i32 s54, s54, 2
	s_add_u32 s48, s48, 0x100
	s_addc_u32 s49, s49, 0
	s_add_u32 s18, s18, 0x100
	s_addc_u32 s19, s19, 0
	s_cmp_gt_u32 s54, 13
